# v36 + nt on the prologue's read-once f32 weight loads (weight transposes and adaLN GEMV)
# speedup vs baseline: 1.0037x; 1.0037x over previous
; __device__ __forceinline__ void p0_prologue(Frame& F) {
;     ...
;         for (int it = gw; it < 96 * ADA_KCH; it += NGW) {
;             const int cc = it % 96, kc = it / 96, col = 256 * cc + 4 * lane;
;             f32x4 a0 = {0.f, 0.f, 0.f, 0.f}, a1 = a0, a2 = a0, a3 = a0;
;             for (int k8 = 0; k8 < 4; ++k8) {
;                 const int kbase = 256 * kc + 64 * k8;
;                 float s0, s1, s2, s3;
;                 { const float x0 = F.c[0 * D + kbase + lane], x1 = F.c[1 * D + kbase + lane], x2 = F.c[2 * D + kbase + lane], x3 = F.c[3 * D + kbase + lane];
;                   s0 = x0 / (1.f + expf(-x0)); s1 = x1 / (1.f + expf(-x1)); s2 = x2 / (1.f + expf(-x2)); s3 = x3 / (1.f + expf(-x3)); }
;                 const float* wp = F.w_ada + (size_t)kbase * NADA + col;
; #pragma unroll 16
;                 for (int kk = 0; kk < 64; ++kk) { const f32x4 w = *(const f32x4*)(wp + (size_t)kk * NADA);
.LBB0_16:
	s_mul_hi_i32 s0, s79, 0x2aaaaaab
	s_lshr_b32 s1, s0, 31
	s_ashr_i32 s80, s0, 4
	s_add_i32 s80, s80, s1
	s_lshl_b32 s62, s80, 8
	v_or_b32_e32 v2, s62, v186
	v_readlane_b32 s0, v245, 29
	v_add_u32_e32 v4, s62, v58
	v_ashrrev_i32_e32 v3, 31, v2
	v_readlane_b32 s2, v245, 31
	v_readlane_b32 s3, v245, 32
	v_ashrrev_i32_e32 v5, 31, v4
	v_add_u32_e32 v6, s62, v59
	v_add_u32_e32 v8, s62, v60
	v_lshl_add_u64 v[2:3], v[2:3], 2, s[2:3]
	v_lshl_add_u64 v[4:5], v[4:5], 2, s[2:3]
	v_ashrrev_i32_e32 v7, 31, v6
	v_ashrrev_i32_e32 v9, 31, v8
	v_lshl_add_u64 v[6:7], v[6:7], 2, s[2:3]
	v_lshl_add_u64 v[8:9], v[8:9], 2, s[2:3]
	global_load_dword v2, v[2:3], off nt
	s_nop 0
	global_load_dword v3, v[4:5], off nt
	s_nop 0
	global_load_dword v4, v[6:7], off nt
	global_load_dword v5, v[8:9], off nt
	v_readlane_b32 s1, v245, 30
	s_ashr_i32 s63, s62, 31
	s_mov_b32 s29, 0
	v_readlane_b32 s4, v245, 33
	v_readlane_b32 s5, v245, 34
	v_readlane_b32 s6, v245, 35
	v_readlane_b32 s7, v245, 36
	v_readlane_b32 s8, v245, 37
	v_readlane_b32 s9, v245, 38
	v_readlane_b32 s10, v245, 39
	v_readlane_b32 s11, v245, 40
	v_readlane_b32 s12, v245, 41
	v_readlane_b32 s13, v245, 42
	v_readlane_b32 s14, v245, 43
	v_readlane_b32 s15, v245, 44
	s_waitcnt vmcnt(3)
	v_mul_f32_e32 v6, 0xbfb8aa3b, v2
	s_waitcnt vmcnt(2)
	v_mul_f32_e32 v7, 0xbfb8aa3b, v3
	v_fma_f32 v10, v2, s41, -v6
	v_rndne_f32_e32 v11, v6
	s_waitcnt vmcnt(1)
	v_mul_f32_e32 v8, 0xbfb8aa3b, v4
	v_fma_f32 v12, v3, s41, -v7
	v_rndne_f32_e32 v13, v7
	v_fmac_f32_e32 v10, 0xb2a5705f, v2
	v_sub_f32_e32 v6, v6, v11
	s_waitcnt vmcnt(0)
	v_mul_f32_e32 v9, 0xbfb8aa3b, v5
	v_fma_f32 v14, v4, s41, -v8
	v_rndne_f32_e32 v15, v8
	v_fmac_f32_e32 v12, 0xb2a5705f, v3
	v_sub_f32_e32 v7, v7, v13
	v_add_f32_e32 v6, v6, v10
	v_fma_f32 v16, v5, s41, -v9
	v_rndne_f32_e32 v17, v9
	v_cvt_i32_f32_e32 v11, v11
	v_fmac_f32_e32 v14, 0xb2a5705f, v4
	v_sub_f32_e32 v8, v8, v15
	v_add_f32_e32 v7, v7, v12
	v_exp_f32_e32 v6, v6
	v_cvt_i32_f32_e32 v13, v13
	v_fmac_f32_e32 v16, 0xb2a5705f, v5
	v_sub_f32_e32 v9, v9, v17
	v_add_f32_e32 v8, v8, v14
	v_exp_f32_e32 v7, v7
	v_cvt_i32_f32_e32 v15, v15
	v_add_f32_e32 v9, v9, v16
	v_exp_f32_e32 v8, v8
	v_cvt_i32_f32_e32 v17, v17
	v_exp_f32_e32 v9, v9
	v_ldexp_f32 v6, v6, v11
	v_cmp_nlt_f32_e32 vcc, s43, v2
	v_ldexp_f32 v7, v7, v13
	v_ldexp_f32 v8, v8, v15
	v_cndmask_b32_e32 v6, 0, v6, vcc
	v_cmp_nlt_f32_e32 vcc, s43, v3
	v_ldexp_f32 v9, v9, v17
	s_nop 0
	v_cndmask_b32_e32 v7, 0, v7, vcc
	v_cmp_nlt_f32_e32 vcc, s43, v4
	s_nop 1
	v_cndmask_b32_e32 v8, 0, v8, vcc
	v_cmp_nlt_f32_e32 vcc, s43, v5
	s_nop 1
	v_cndmask_b32_e32 v9, 0, v9, vcc
	v_cmp_ngt_f32_e32 vcc, s45, v2
	s_nop 1
	v_cndmask_b32_e32 v6, v61, v6, vcc
	v_cmp_ngt_f32_e32 vcc, s45, v3
	v_add_f32_e32 v6, 1.0, v6
	v_div_scale_f32 v10, s[0:1], v6, v6, v2
	v_cndmask_b32_e32 v7, v61, v7, vcc
	v_add_f32_e32 v7, 1.0, v7
	v_div_scale_f32 v12, s[0:1], v7, v7, v3
	v_rcp_f32_e32 v15, v10
	v_rcp_f32_e32 v16, v12
	v_cmp_ngt_f32_e32 vcc, s45, v4
	v_div_scale_f32 v13, s[0:1], v3, v7, v3
	v_fma_f32 v19, -v10, v15, 1.0
	v_cndmask_b32_e32 v8, v61, v8, vcc
	v_div_scale_f32 v11, vcc, v2, v6, v2
	v_fma_f32 v20, -v12, v16, 1.0
	v_fmac_f32_e32 v15, v19, v15
	v_add_f32_e32 v8, 1.0, v8
	v_fmac_f32_e32 v16, v20, v16
	v_mul_f32_e32 v19, v11, v15
	v_div_scale_f32 v14, s[2:3], v8, v8, v4
	v_mul_f32_e32 v20, v13, v16
	v_fma_f32 v22, -v10, v19, v11
	v_rcp_f32_e32 v17, v14
	v_fma_f32 v23, -v12, v20, v13
	v_fmac_f32_e32 v19, v22, v15
	v_fmac_f32_e32 v20, v23, v16
	v_fma_f32 v10, -v10, v19, v11
	v_fma_f32 v11, -v12, v20, v13
	v_div_fmas_f32 v10, v10, v15, v19
	s_mov_b64 vcc, s[0:1]
	v_div_fixup_f32 v56, v10, v6, v2
	v_div_fmas_f32 v2, v11, v16, v20
	v_cmp_ngt_f32_e32 vcc, s45, v5
	v_fma_f32 v21, -v14, v17, 1.0
	v_div_fixup_f32 v57, v2, v7, v3
	v_cndmask_b32_e32 v2, v61, v9, vcc
	v_div_scale_f32 v18, s[2:3], v4, v8, v4
	v_fmac_f32_e32 v17, v21, v17
	v_add_f32_e32 v2, 1.0, v2
	v_mul_f32_e32 v21, v18, v17
	v_div_scale_f32 v3, s[0:1], v2, v2, v5
	v_fma_f32 v24, -v14, v21, v18
	v_rcp_f32_e32 v6, v3
	v_fmac_f32_e32 v21, v24, v17
	v_fma_f32 v12, -v14, v21, v18
	s_mov_b64 vcc, s[2:3]
	v_div_fmas_f32 v7, v12, v17, v21
	v_div_fixup_f32 v63, v7, v8, v4
	v_fma_f32 v4, -v3, v6, 1.0
	v_fmac_f32_e32 v6, v4, v6
	v_div_scale_f32 v4, vcc, v5, v2, v5
	v_mul_f32_e32 v7, v4, v6
	v_fma_f32 v8, -v3, v7, v4
	v_fmac_f32_e32 v7, v8, v6
	v_fma_f32 v3, -v3, v7, v4
	v_div_fmas_f32 v3, v3, v6, v7
	v_div_fixup_f32 v64, v3, v2, v5
	v_lshl_or_b32 v2, s79, 8, v1
	s_mul_i32 s0, s80, 0x6000
	v_subrev_u32_e32 v2, s0, v2
	v_ashrrev_i32_e32 v3, 31, v2
	v_lshlrev_b64 v[2:3], 2, v[2:3]
	v_mad_i64_i32 v[22:23], s[0:1], s62, v62, v[2:3]
	v_readlane_b32 s0, v245, 61
	v_readlane_b32 s1, v245, 62
	v_mov_b32_e32 v14, 0
	v_mov_b32_e32 v15, v187
	v_lshl_add_u64 v[24:25], s[0:1], 0, v[22:23]
	v_mov_b32_e32 v16, 0
	v_mov_b32_e32 v17, v187
	v_mov_b32_e32 v10, 0
	v_mov_b32_e32 v11, v187
	v_mov_b32_e32 v12, 0
	v_mov_b32_e32 v13, v187
	v_mov_b32_e32 v6, 0
	v_mov_b32_e32 v7, v187
	v_mov_b32_e32 v8, 0
	v_mov_b32_e32 v9, v187
	v_mov_b32_e32 v2, 0
	v_mov_b32_e32 v3, v187
	v_mov_b32_e32 v4, 0
	v_mov_b32_e32 v5, v187
; __device__ __forceinline__ float rdlane(float v, int l) { return __int_as_float(__builtin_amdgcn_readlane(__float_as_int(v), l)); }
; __device__ __forceinline__ void p0_prologue(Frame& F) {
;     ...
;                 const float* wp = F.w_ada + (size_t)kbase * NADA + col;
; #pragma unroll 16
;                 for (int kk = 0; kk < 64; ++kk) { const f32x4 w = *(const f32x4*)(wp + (size_t)kk * NADA);
;                     a0 += w * rdlane(s0, kk); a1 += w * rdlane(s1, kk); a2 += w * rdlane(s2, kk); a3 += w * rdlane(s3, kk); }
.LBB0_17:
	v_add_co_u32_e32 v52, vcc, s47, v24
	v_add_co_u32_e64 v54, s[2:3], s49, v24
	s_nop 0
	v_addc_co_u32_e32 v53, vcc, -1, v25, vcc
	global_load_dwordx4 v[66:69], v[52:53], off nt
	v_readlane_b32 s28, v56, s29
	v_readlane_b32 s34, v57, s29
	v_readlane_b32 s64, v63, s29
	v_readlane_b32 s66, v64, s29
	s_add_i32 s36, s29, 1
	s_add_i32 s38, s29, 2
	s_add_i32 s40, s29, 3
	s_add_i32 s52, s29, 4
	s_add_i32 s68, s29, 5
	s_add_i32 s89, s29, 6
	s_add_i32 s88, s29, 7
	s_add_i32 s86, s29, 8
	s_add_i32 s87, s29, 9
	s_add_i32 s78, s29, 10
	s_add_i32 s85, s29, 11
	s_add_i32 s84, s29, 12
	s_add_i32 s83, s29, 13
	s_add_i32 s82, s29, 14
	s_add_i32 s81, s29, 15
	s_add_i32 s29, s29, 16
	v_addc_co_u32_e64 v55, vcc, -1, v25, s[2:3]
	s_mov_b32 s0, 0x18000
	v_add_co_u32_e64 v30, s[16:17], s0, v24
	s_mov_b32 s0, 0x30000
	v_add_co_u32_e64 v32, s[18:19], s0, v24
	s_mov_b32 s0, 0x48000
	v_add_co_u32_e64 v34, s[20:21], s0, v24
	s_mov_b32 s0, 0x60000
	v_add_co_u32_e64 v50, s[4:5], s51, v24
	v_add_co_u32_e64 v38, s[22:23], s0, v24
	s_nop 0
	v_addc_co_u32_e64 v51, vcc, -1, v25, s[4:5]
	v_addc_co_u32_e64 v31, vcc, 0, v25, s[16:17]
	v_addc_co_u32_e64 v33, vcc, 0, v25, s[18:19]
	v_addc_co_u32_e64 v35, vcc, 0, v25, s[20:21]
	v_addc_co_u32_e64 v39, vcc, 0, v25, s[22:23]
	v_readlane_b32 s16, v56, s36
	v_readlane_b32 s18, v57, s36
	v_readlane_b32 s20, v63, s36
	v_readlane_b32 s22, v64, s36
	v_add_co_u32_e64 v46, s[6:7], s53, v24
	v_readlane_b32 s76, v56, s38
	s_nop 0
	v_addc_co_u32_e64 v47, vcc, -1, v25, s[6:7]
	v_readlane_b32 s74, v57, s38
	v_readlane_b32 s72, v63, s38
	v_readlane_b32 s58, v64, s38
	v_add_co_u32_e64 v40, s[8:9], s55, v24
	v_readlane_b32 s56, v56, s40
	s_nop 0
	v_addc_co_u32_e64 v41, vcc, -1, v25, s[8:9]
	v_readlane_b32 s50, v57, s40
	v_readlane_b32 s48, v63, s40
	v_readlane_b32 s46, v64, s40
	v_add_co_u32_e64 v36, s[10:11], s57, v24
	v_readlane_b32 s44, v56, s52
	s_nop 0
	v_addc_co_u32_e64 v37, vcc, -1, v25, s[10:11]
	v_readlane_b32 s42, v57, s52
	v_readlane_b32 s36, v63, s52
	v_readlane_b32 s38, v64, s52
	v_add_co_u32_e64 v28, s[12:13], s59, v24
	v_readlane_b32 s40, v56, s68
	s_nop 0
	v_addc_co_u32_e64 v29, vcc, -1, v25, s[12:13]
	s_waitcnt vmcnt(0)
	v_pk_fma_f32 v[14:15], v[66:67], s[28:29], v[14:15] op_sel_hi:[1,0,1]
	v_pk_fma_f32 v[10:11], v[66:67], s[34:35], v[10:11] op_sel_hi:[1,0,1]
	v_pk_fma_f32 v[6:7], v[66:67], s[64:65], v[6:7] op_sel_hi:[1,0,1]
	v_pk_fma_f32 v[52:53], v[68:69], s[66:67], v[4:5] op_sel_hi:[1,0,1]
	v_pk_fma_f32 v[66:67], v[66:67], s[66:67], v[2:3] op_sel_hi:[1,0,1]
	global_load_dwordx4 v[2:5], v[54:55], off nt
	v_pk_fma_f32 v[16:17], v[68:69], s[28:29], v[16:17] op_sel_hi:[1,0,1]
	v_pk_fma_f32 v[12:13], v[68:69], s[34:35], v[12:13] op_sel_hi:[1,0,1]
	v_pk_fma_f32 v[8:9], v[68:69], s[64:65], v[8:9] op_sel_hi:[1,0,1]
	v_readlane_b32 s54, v57, s68
	v_readlane_b32 s52, v63, s68
	v_readlane_b32 s96, v64, s68
	global_load_dwordx4 v[18:21], v[24:25], off nt
	s_mov_b32 s0, 0x78000
	v_add_co_u32_e64 v42, s[24:25], s0, v24
	s_mov_b32 s0, 0x90000
	v_add_co_u32_e64 v26, s[14:15], s65, v24
	v_add_co_u32_e64 v44, s[0:1], s0, v24
	s_mov_b32 s26, 0xa8000
	v_add_co_u32_e64 v48, s[26:27], s26, v24
	v_addc_co_u32_e64 v27, vcc, -1, v25, s[14:15]
	v_addc_co_u32_e64 v43, vcc, 0, v25, s[24:25]
	v_addc_co_u32_e64 v45, vcc, 0, v25, s[0:1]
	v_readlane_b32 s70, v56, s89
	v_readlane_b32 s68, v57, s89
	v_addc_co_u32_e64 v49, vcc, 0, v25, s[26:27]
	v_readlane_b32 s26, v63, s89
	v_readlane_b32 s4, v64, s89
	v_readlane_b32 s2, v56, s88
	v_readlane_b32 s0, v57, s88
	v_readlane_b32 s8, v63, s88
	v_readlane_b32 s6, v64, s88
	v_readlane_b32 s10, v56, s86
	v_readlane_b32 s12, v57, s86
	v_readlane_b32 s14, v63, s86
	v_readlane_b32 s24, v63, s87
	v_readlane_b32 s28, v56, s78
	v_readlane_b32 s34, v57, s78
	v_readlane_b32 s64, v63, s78
	v_readlane_b32 s66, v64, s78
	v_readlane_b32 s78, v63, s85
	s_cmp_eq_u32 s29, 64
	s_waitcnt vmcnt(1)
	v_pk_fma_f32 v[16:17], v[4:5], s[16:17], v[16:17] op_sel_hi:[1,0,1]
	v_pk_fma_f32 v[14:15], v[2:3], s[16:17], v[14:15] op_sel_hi:[1,0,1]
	v_pk_fma_f32 v[12:13], v[4:5], s[18:19], v[12:13] op_sel_hi:[1,0,1]
	v_pk_fma_f32 v[10:11], v[2:3], s[18:19], v[10:11] op_sel_hi:[1,0,1]
	v_pk_fma_f32 v[8:9], v[4:5], s[20:21], v[8:9] op_sel_hi:[1,0,1]
	v_pk_fma_f32 v[6:7], v[2:3], s[20:21], v[6:7] op_sel_hi:[1,0,1]
	v_pk_fma_f32 v[52:53], v[4:5], s[22:23], v[52:53] op_sel_hi:[1,0,1]
	v_pk_fma_f32 v[54:55], v[2:3], s[22:23], v[66:67] op_sel_hi:[1,0,1]
	global_load_dwordx4 v[2:5], v[50:51], off nt
	v_readlane_b32 s16, v64, s86
	v_readlane_b32 s18, v56, s87
	v_readlane_b32 s20, v57, s87
	v_readlane_b32 s22, v64, s87
	v_readlane_b32 s86, v56, s84
	s_waitcnt vmcnt(0)
	v_pk_fma_f32 v[16:17], v[4:5], s[76:77], v[16:17] op_sel_hi:[1,0,1]
	v_pk_fma_f32 v[14:15], v[2:3], s[76:77], v[14:15] op_sel_hi:[1,0,1]
	v_pk_fma_f32 v[12:13], v[4:5], s[74:75], v[12:13] op_sel_hi:[1,0,1]
	v_pk_fma_f32 v[10:11], v[2:3], s[74:75], v[10:11] op_sel_hi:[1,0,1]
	v_pk_fma_f32 v[8:9], v[4:5], s[72:73], v[8:9] op_sel_hi:[1,0,1]
	v_pk_fma_f32 v[6:7], v[2:3], s[72:73], v[6:7] op_sel_hi:[1,0,1]
	v_pk_fma_f32 v[50:51], v[4:5], s[58:59], v[52:53] op_sel_hi:[1,0,1]
	v_pk_fma_f32 v[52:53], v[2:3], s[58:59], v[54:55] op_sel_hi:[1,0,1]
	global_load_dwordx4 v[2:5], v[46:47], off nt
	v_readlane_b32 s72, v56, s85
	v_readlane_b32 s74, v57, s85
	v_readlane_b32 s76, v64, s85
	v_readlane_b32 s58, v63, s84
	s_waitcnt vmcnt(0)
; __device__ __forceinline__ float rdlane(float v, int l) { return __int_as_float(__builtin_amdgcn_readlane(__float_as_int(v), l)); }
; __device__ __forceinline__ void p0_prologue(Frame& F) {
;     ...
;                 for (int kk = 0; kk < 64; ++kk) { const f32x4 w = *(const f32x4*)(wp + (size_t)kk * NADA);
;                     a0 += w * rdlane(s0, kk); a1 += w * rdlane(s1, kk); a2 += w * rdlane(s2, kk); a3 += w * rdlane(s3, kk); }
	v_pk_fma_f32 v[16:17], v[4:5], s[56:57], v[16:17] op_sel_hi:[1,0,1]
	v_pk_fma_f32 v[14:15], v[2:3], s[56:57], v[14:15] op_sel_hi:[1,0,1]
	v_pk_fma_f32 v[12:13], v[4:5], s[50:51], v[12:13] op_sel_hi:[1,0,1]
	v_pk_fma_f32 v[10:11], v[2:3], s[50:51], v[10:11] op_sel_hi:[1,0,1]
	v_pk_fma_f32 v[8:9], v[4:5], s[48:49], v[8:9] op_sel_hi:[1,0,1]
	v_pk_fma_f32 v[6:7], v[2:3], s[48:49], v[6:7] op_sel_hi:[1,0,1]
	v_pk_fma_f32 v[46:47], v[4:5], s[46:47], v[50:51] op_sel_hi:[1,0,1]
	v_pk_fma_f32 v[50:51], v[2:3], s[46:47], v[52:53] op_sel_hi:[1,0,1]
	global_load_dwordx4 v[2:5], v[40:41], off nt
	v_readlane_b32 s56, v57, s84
	v_readlane_b32 s46, v56, s82
	v_readlane_b32 s48, v57, s82
	v_readlane_b32 s50, v63, s82
	s_waitcnt vmcnt(0)
	v_pk_fma_f32 v[16:17], v[4:5], s[44:45], v[16:17] op_sel_hi:[1,0,1]
	v_pk_fma_f32 v[14:15], v[2:3], s[44:45], v[14:15] op_sel_hi:[1,0,1]
	v_pk_fma_f32 v[12:13], v[4:5], s[42:43], v[12:13] op_sel_hi:[1,0,1]
	v_pk_fma_f32 v[10:11], v[2:3], s[42:43], v[10:11] op_sel_hi:[1,0,1]
	v_pk_fma_f32 v[8:9], v[4:5], s[36:37], v[8:9] op_sel_hi:[1,0,1]
	v_pk_fma_f32 v[6:7], v[2:3], s[36:37], v[6:7] op_sel_hi:[1,0,1]
	v_pk_fma_f32 v[40:41], v[4:5], s[38:39], v[46:47] op_sel_hi:[1,0,1]
	v_pk_fma_f32 v[46:47], v[2:3], s[38:39], v[50:51] op_sel_hi:[1,0,1]
	global_load_dwordx4 v[2:5], v[36:37], off nt
	v_readlane_b32 s36, v64, s84
	v_readlane_b32 s38, v56, s83
	v_readlane_b32 s44, v63, s83
	v_readlane_b32 s42, v64, s83
	s_waitcnt vmcnt(0)
	v_pk_fma_f32 v[16:17], v[4:5], s[40:41], v[16:17] op_sel_hi:[1,0,1]
	v_pk_fma_f32 v[14:15], v[2:3], s[40:41], v[14:15] op_sel_hi:[1,0,1]
	v_pk_fma_f32 v[12:13], v[4:5], s[54:55], v[12:13] op_sel_hi:[1,0,1]
	v_pk_fma_f32 v[10:11], v[2:3], s[54:55], v[10:11] op_sel_hi:[1,0,1]
	v_pk_fma_f32 v[50:51], v[4:5], s[52:53], v[8:9] op_sel_hi:[1,0,1]
	v_pk_fma_f32 v[52:53], v[2:3], s[52:53], v[6:7] op_sel_hi:[1,0,1]
	v_pk_fma_f32 v[54:55], v[4:5], s[96:97], v[40:41] op_sel_hi:[1,0,1]
	v_pk_fma_f32 v[46:47], v[2:3], s[96:97], v[46:47] op_sel_hi:[1,0,1]
	global_load_dwordx4 v[2:5], v[28:29], off nt
	v_readlane_b32 s40, v57, s83
	v_readlane_b32 s52, v64, s82
	v_readlane_b32 s54, v64, s81
	v_lshl_add_u64 v[24:25], v[24:25], 0, s[60:61]
	s_waitcnt vmcnt(0)
	v_pk_fma_f32 v[66:67], v[4:5], s[70:71], v[16:17] op_sel_hi:[1,0,1]
	v_pk_fma_f32 v[68:69], v[2:3], s[70:71], v[14:15] op_sel_hi:[1,0,1]
	v_pk_fma_f32 v[70:71], v[4:5], s[68:69], v[12:13] op_sel_hi:[1,0,1]
	v_pk_fma_f32 v[72:73], v[2:3], s[68:69], v[10:11] op_sel_hi:[1,0,1]
	global_load_dwordx4 v[6:9], v[26:27], off nt
	global_load_dwordx4 v[10:13], v[30:31], off nt
	global_load_dwordx4 v[14:17], v[32:33], off nt
	s_nop 0
	global_load_dwordx4 v[26:29], v[34:35], off nt
	global_load_dwordx4 v[30:33], v[38:39], off nt
	s_nop 0
	global_load_dwordx4 v[34:37], v[42:43], off nt
	global_load_dwordx4 v[38:41], v[44:45], off nt
	s_nop 0
	global_load_dwordx4 v[42:45], v[48:49], off nt
	v_pk_fma_f32 v[48:49], v[4:5], s[26:27], v[50:51] op_sel_hi:[1,0,1]
	v_pk_fma_f32 v[50:51], v[2:3], s[26:27], v[52:53] op_sel_hi:[1,0,1]
	v_pk_fma_f32 v[4:5], v[4:5], s[4:5], v[54:55] op_sel_hi:[1,0,1]
	v_pk_fma_f32 v[2:3], v[2:3], s[4:5], v[46:47] op_sel_hi:[1,0,1]
	v_readlane_b32 s26, v56, s81
	v_readlane_b32 s4, v57, s81
	s_waitcnt vmcnt(7)
	v_pk_fma_f32 v[46:47], v[8:9], s[2:3], v[66:67] op_sel_hi:[1,0,1]
	v_pk_fma_f32 v[52:53], v[6:7], s[2:3], v[68:69] op_sel_hi:[1,0,1]
	v_pk_fma_f32 v[54:55], v[8:9], s[0:1], v[70:71] op_sel_hi:[1,0,1]
	v_pk_fma_f32 v[66:67], v[6:7], s[0:1], v[72:73] op_sel_hi:[1,0,1]
	v_pk_fma_f32 v[48:49], v[8:9], s[8:9], v[48:49] op_sel_hi:[1,0,1]
	v_pk_fma_f32 v[50:51], v[6:7], s[8:9], v[50:51] op_sel_hi:[1,0,1]
	v_pk_fma_f32 v[4:5], v[8:9], s[6:7], v[4:5] op_sel_hi:[1,0,1]
	v_pk_fma_f32 v[2:3], v[6:7], s[6:7], v[2:3] op_sel_hi:[1,0,1]
	v_pk_fma_f32 v[6:7], v[20:21], s[10:11], v[46:47] op_sel_hi:[1,0,1]
	v_pk_fma_f32 v[8:9], v[18:19], s[10:11], v[52:53] op_sel_hi:[1,0,1]
	v_pk_fma_f32 v[46:47], v[20:21], s[12:13], v[54:55] op_sel_hi:[1,0,1]
	v_pk_fma_f32 v[52:53], v[18:19], s[12:13], v[66:67] op_sel_hi:[1,0,1]
	v_pk_fma_f32 v[48:49], v[20:21], s[14:15], v[48:49] op_sel_hi:[1,0,1]
	v_pk_fma_f32 v[50:51], v[18:19], s[14:15], v[50:51] op_sel_hi:[1,0,1]
	v_pk_fma_f32 v[4:5], v[20:21], s[16:17], v[4:5] op_sel_hi:[1,0,1]
	v_pk_fma_f32 v[2:3], v[18:19], s[16:17], v[2:3] op_sel_hi:[1,0,1]
	s_waitcnt vmcnt(6)
	v_pk_fma_f32 v[6:7], v[12:13], s[18:19], v[6:7] op_sel_hi:[1,0,1]
	v_pk_fma_f32 v[8:9], v[10:11], s[18:19], v[8:9] op_sel_hi:[1,0,1]
	v_pk_fma_f32 v[18:19], v[12:13], s[20:21], v[46:47] op_sel_hi:[1,0,1]
	v_pk_fma_f32 v[20:21], v[10:11], s[20:21], v[52:53] op_sel_hi:[1,0,1]
	v_pk_fma_f32 v[46:47], v[12:13], s[24:25], v[48:49] op_sel_hi:[1,0,1]
	v_pk_fma_f32 v[48:49], v[10:11], s[24:25], v[50:51] op_sel_hi:[1,0,1]
	v_pk_fma_f32 v[4:5], v[12:13], s[22:23], v[4:5] op_sel_hi:[1,0,1]
	v_pk_fma_f32 v[2:3], v[10:11], s[22:23], v[2:3] op_sel_hi:[1,0,1]
	s_waitcnt vmcnt(5)
	v_pk_fma_f32 v[6:7], v[16:17], s[28:29], v[6:7] op_sel_hi:[1,0,1]
	v_pk_fma_f32 v[8:9], v[14:15], s[28:29], v[8:9] op_sel_hi:[1,0,1]
	v_pk_fma_f32 v[10:11], v[16:17], s[34:35], v[18:19] op_sel_hi:[1,0,1]
	v_pk_fma_f32 v[12:13], v[14:15], s[34:35], v[20:21] op_sel_hi:[1,0,1]
	v_pk_fma_f32 v[18:19], v[16:17], s[64:65], v[46:47] op_sel_hi:[1,0,1]
	v_pk_fma_f32 v[20:21], v[14:15], s[64:65], v[48:49] op_sel_hi:[1,0,1]
	v_pk_fma_f32 v[4:5], v[16:17], s[66:67], v[4:5] op_sel_hi:[1,0,1]
	v_pk_fma_f32 v[2:3], v[14:15], s[66:67], v[2:3] op_sel_hi:[1,0,1]
	s_waitcnt vmcnt(4)
; __device__ __forceinline__ float rdlane(float v, int l) { return __int_as_float(__builtin_amdgcn_readlane(__float_as_int(v), l)); }
; __device__ __forceinline__ void p0_prologue(Frame& F) {
;     ...
;             for (int k8 = 0; k8 < 4; ++k8) {
;                 const int kbase = 256 * kc + 64 * k8;
;                 float s0, s1, s2, s3;
;                 { const float x0 = F.c[0 * D + kbase + lane], x1 = F.c[1 * D + kbase + lane], x2 = F.c[2 * D + kbase + lane], x3 = F.c[3 * D + kbase + lane];
;                   s0 = x0 / (1.f + expf(-x0)); s1 = x1 / (1.f + expf(-x1)); s2 = x2 / (1.f + expf(-x2)); s3 = x3 / (1.f + expf(-x3)); }
;     ...
;                 for (int kk = 0; kk < 64; ++kk) { const f32x4 w = *(const f32x4*)(wp + (size_t)kk * NADA);
;                     a0 += w * rdlane(s0, kk); a1 += w * rdlane(s1, kk); a2 += w * rdlane(s2, kk); a3 += w * rdlane(s3, kk); }
	v_pk_fma_f32 v[6:7], v[28:29], s[72:73], v[6:7] op_sel_hi:[1,0,1]
	v_pk_fma_f32 v[8:9], v[26:27], s[72:73], v[8:9] op_sel_hi:[1,0,1]
	v_pk_fma_f32 v[10:11], v[28:29], s[74:75], v[10:11] op_sel_hi:[1,0,1]
	v_pk_fma_f32 v[12:13], v[26:27], s[74:75], v[12:13] op_sel_hi:[1,0,1]
	v_pk_fma_f32 v[14:15], v[28:29], s[78:79], v[18:19] op_sel_hi:[1,0,1]
	v_pk_fma_f32 v[16:17], v[26:27], s[78:79], v[20:21] op_sel_hi:[1,0,1]
	v_pk_fma_f32 v[4:5], v[28:29], s[76:77], v[4:5] op_sel_hi:[1,0,1]
	v_pk_fma_f32 v[2:3], v[26:27], s[76:77], v[2:3] op_sel_hi:[1,0,1]
	s_waitcnt vmcnt(3)
	v_pk_fma_f32 v[6:7], v[32:33], s[86:87], v[6:7] op_sel_hi:[1,0,1]
	v_pk_fma_f32 v[8:9], v[30:31], s[86:87], v[8:9] op_sel_hi:[1,0,1]
	v_pk_fma_f32 v[10:11], v[32:33], s[56:57], v[10:11] op_sel_hi:[1,0,1]
	v_pk_fma_f32 v[12:13], v[30:31], s[56:57], v[12:13] op_sel_hi:[1,0,1]
	v_pk_fma_f32 v[14:15], v[32:33], s[58:59], v[14:15] op_sel_hi:[1,0,1]
	v_pk_fma_f32 v[16:17], v[30:31], s[58:59], v[16:17] op_sel_hi:[1,0,1]
	v_pk_fma_f32 v[4:5], v[32:33], s[36:37], v[4:5] op_sel_hi:[1,0,1]
	v_pk_fma_f32 v[2:3], v[30:31], s[36:37], v[2:3] op_sel_hi:[1,0,1]
	s_waitcnt vmcnt(2)
	v_pk_fma_f32 v[6:7], v[36:37], s[38:39], v[6:7] op_sel_hi:[1,0,1]
	v_pk_fma_f32 v[8:9], v[34:35], s[38:39], v[8:9] op_sel_hi:[1,0,1]
	v_pk_fma_f32 v[10:11], v[36:37], s[40:41], v[10:11] op_sel_hi:[1,0,1]
	v_pk_fma_f32 v[12:13], v[34:35], s[40:41], v[12:13] op_sel_hi:[1,0,1]
	v_pk_fma_f32 v[14:15], v[36:37], s[44:45], v[14:15] op_sel_hi:[1,0,1]
	v_pk_fma_f32 v[16:17], v[34:35], s[44:45], v[16:17] op_sel_hi:[1,0,1]
	v_pk_fma_f32 v[4:5], v[36:37], s[42:43], v[4:5] op_sel_hi:[1,0,1]
	v_pk_fma_f32 v[2:3], v[34:35], s[42:43], v[2:3] op_sel_hi:[1,0,1]
	v_readlane_b32 s2, v63, s81
	s_waitcnt vmcnt(1)
	v_pk_fma_f32 v[6:7], v[40:41], s[46:47], v[6:7] op_sel_hi:[1,0,1]
	v_pk_fma_f32 v[8:9], v[38:39], s[46:47], v[8:9] op_sel_hi:[1,0,1]
	v_pk_fma_f32 v[10:11], v[40:41], s[48:49], v[10:11] op_sel_hi:[1,0,1]
	v_pk_fma_f32 v[18:19], v[38:39], s[48:49], v[12:13] op_sel_hi:[1,0,1]
	v_pk_fma_f32 v[20:21], v[40:41], s[50:51], v[14:15] op_sel_hi:[1,0,1]
	v_pk_fma_f32 v[26:27], v[38:39], s[50:51], v[16:17] op_sel_hi:[1,0,1]
	v_pk_fma_f32 v[4:5], v[40:41], s[52:53], v[4:5] op_sel_hi:[1,0,1]
	v_pk_fma_f32 v[2:3], v[38:39], s[52:53], v[2:3] op_sel_hi:[1,0,1]
	s_waitcnt vmcnt(0)
	v_pk_fma_f32 v[16:17], v[44:45], s[26:27], v[6:7] op_sel_hi:[1,0,1]
	v_pk_fma_f32 v[14:15], v[42:43], s[26:27], v[8:9] op_sel_hi:[1,0,1]
	v_pk_fma_f32 v[12:13], v[44:45], s[4:5], v[10:11] op_sel_hi:[1,0,1]
	v_pk_fma_f32 v[10:11], v[42:43], s[4:5], v[18:19] op_sel_hi:[1,0,1]
	v_pk_fma_f32 v[8:9], v[44:45], s[2:3], v[20:21] op_sel_hi:[1,0,1]
	v_pk_fma_f32 v[6:7], v[42:43], s[2:3], v[26:27] op_sel_hi:[1,0,1]
	v_pk_fma_f32 v[4:5], v[44:45], s[54:55], v[4:5] op_sel_hi:[1,0,1]
	v_pk_fma_f32 v[2:3], v[42:43], s[54:55], v[2:3] op_sel_hi:[1,0,1]
	s_cbranch_scc0 .LBB0_17
	v_readlane_b32 s4, v245, 29
	v_lshl_add_u64 v[18:19], s[62:63], 0, v[186:187]
	v_readlane_b32 s6, v245, 31
	v_readlane_b32 s7, v245, 32
	s_or_b32 s0, s62, 64
	v_add_u32_e32 v20, s0, v59
	v_lshl_add_u64 v[24:25], v[18:19], 2, s[6:7]
	global_load_dword v28, v[24:25], off offset:256 nt
	v_add_u32_e32 v18, s0, v58
	v_ashrrev_i32_e32 v19, 31, v18
	v_ashrrev_i32_e32 v21, 31, v20
	v_add_u32_e32 v26, s0, v60
	v_lshl_add_u64 v[18:19], v[18:19], 2, s[6:7]
	v_lshl_add_u64 v[20:21], v[20:21], 2, s[6:7]
	v_ashrrev_i32_e32 v27, 31, v26
	v_lshl_add_u64 v[26:27], v[26:27], 2, s[6:7]
	global_load_dword v18, v[18:19], off nt
	s_nop 0
	global_load_dword v19, v[20:21], off nt
	s_nop 0
	global_load_dword v20, v[26:27], off nt
	s_mov_b32 s63, 0
	v_readlane_b32 s5, v245, 30
	v_readlane_b32 s8, v245, 33
	v_readlane_b32 s9, v245, 34
	v_readlane_b32 s10, v245, 35
	v_readlane_b32 s11, v245, 36
	v_readlane_b32 s12, v245, 37
	v_readlane_b32 s13, v245, 38
	v_readlane_b32 s14, v245, 39
	v_readlane_b32 s15, v245, 40
	v_readlane_b32 s16, v245, 41
	v_readlane_b32 s17, v245, 42
	v_readlane_b32 s18, v245, 43
	v_readlane_b32 s19, v245, 44
	s_waitcnt vmcnt(3)
	v_mul_f32_e32 v21, 0xbfb8aa3b, v28
	v_fma_f32 v26, v28, s41, -v21
	v_rndne_f32_e32 v27, v21
	v_fmac_f32_e32 v26, 0xb2a5705f, v28
	v_sub_f32_e32 v21, v21, v27
	v_add_f32_e32 v21, v21, v26
	v_cvt_i32_f32_e32 v27, v27
	s_waitcnt vmcnt(2)
	v_mul_f32_e32 v29, 0xbfb8aa3b, v18
	s_waitcnt vmcnt(1)
	v_mul_f32_e32 v30, 0xbfb8aa3b, v19
	s_waitcnt vmcnt(0)
; __device__ __forceinline__ float rdlane(float v, int l) { return __int_as_float(__builtin_amdgcn_readlane(__float_as_int(v), l)); }
; __device__ __forceinline__ void p0_prologue(Frame& F) {
;     ...
;                 { const float x0 = F.c[0 * D + kbase + lane], x1 = F.c[1 * D + kbase + lane], x2 = F.c[2 * D + kbase + lane], x3 = F.c[3 * D + kbase + lane];
;                   s0 = x0 / (1.f + expf(-x0)); s1 = x1 / (1.f + expf(-x1)); s2 = x2 / (1.f + expf(-x2)); s3 = x3 / (1.f + expf(-x3)); }
;                 const float* wp = F.w_ada + (size_t)kbase * NADA + col;
; #pragma unroll 16
;                 for (int kk = 0; kk < 64; ++kk) { const f32x4 w = *(const f32x4*)(wp + (size_t)kk * NADA);
;                     a0 += w * rdlane(s0, kk); a1 += w * rdlane(s1, kk); a2 += w * rdlane(s2, kk); a3 += w * rdlane(s3, kk); }
	v_mul_f32_e32 v31, 0xbfb8aa3b, v20
	v_exp_f32_e32 v21, v21
	v_fma_f32 v26, v18, s41, -v29
	v_rndne_f32_e32 v32, v29
	v_fma_f32 v33, v19, s41, -v30
	v_rndne_f32_e32 v34, v30
	v_fma_f32 v35, v20, s41, -v31
	v_rndne_f32_e32 v36, v31
	v_fmac_f32_e32 v26, 0xb2a5705f, v18
	v_sub_f32_e32 v29, v29, v32
	v_fmac_f32_e32 v33, 0xb2a5705f, v19
	v_sub_f32_e32 v30, v30, v34
	v_fmac_f32_e32 v35, 0xb2a5705f, v20
	v_sub_f32_e32 v31, v31, v36
	v_add_f32_e32 v26, v29, v26
	v_add_f32_e32 v29, v30, v33
	v_add_f32_e32 v30, v31, v35
	v_cvt_i32_f32_e32 v32, v32
	v_cvt_i32_f32_e32 v34, v34
	v_cvt_i32_f32_e32 v36, v36
	v_exp_f32_e32 v26, v26
	v_exp_f32_e32 v29, v29
	v_exp_f32_e32 v30, v30
	v_ldexp_f32 v21, v21, v27
	v_cmp_nlt_f32_e32 vcc, s43, v28
	v_ldexp_f32 v26, v26, v32
	v_ldexp_f32 v27, v29, v34
	v_cndmask_b32_e32 v21, 0, v21, vcc
	v_cmp_ngt_f32_e32 vcc, s45, v28
	v_ldexp_f32 v29, v30, v36
	s_nop 0
	v_cndmask_b32_e32 v21, v61, v21, vcc
	v_add_f32_e32 v21, 1.0, v21
	v_cmp_nlt_f32_e32 vcc, s43, v18
	v_div_scale_f32 v30, s[0:1], v21, v21, v28
	s_nop 0
	v_cndmask_b32_e32 v26, 0, v26, vcc
	v_cmp_ngt_f32_e64 s[0:1], s45, v18
	v_cmp_nlt_f32_e32 vcc, s43, v19
	v_rcp_f32_e32 v32, v30
	v_cndmask_b32_e64 v26, v61, v26, s[0:1]
	v_cndmask_b32_e32 v27, 0, v27, vcc
	v_cmp_ngt_f32_e64 s[0:1], s45, v19
	v_add_f32_e32 v26, 1.0, v26
	v_cmp_nlt_f32_e32 vcc, s43, v20
	v_cndmask_b32_e64 v27, v61, v27, s[0:1]
	v_div_scale_f32 v33, s[0:1], v26, v26, v18
	v_rcp_f32_e32 v37, v33
	v_fma_f32 v39, -v30, v32, 1.0
	v_cndmask_b32_e32 v29, 0, v29, vcc
	v_div_scale_f32 v31, vcc, v28, v21, v28
	v_fmac_f32_e32 v32, v39, v32
	v_mul_f32_e32 v39, v31, v32
	v_fma_f32 v40, -v33, v37, 1.0
	v_add_f32_e32 v27, 1.0, v27
	v_div_scale_f32 v34, s[0:1], v18, v26, v18
	v_fma_f32 v42, -v30, v39, v31
	v_fmac_f32_e32 v37, v40, v37
	v_div_scale_f32 v35, s[2:3], v27, v27, v19
	v_fmac_f32_e32 v39, v42, v32
	v_mul_f32_e32 v40, v34, v37
	v_rcp_f32_e32 v38, v35
	v_fma_f32 v30, -v30, v39, v31
	v_fma_f32 v31, -v33, v40, v34
	v_div_fmas_f32 v30, v30, v32, v39
	v_fmac_f32_e32 v40, v31, v37
	v_div_fixup_f32 v63, v30, v21, v28
	v_fma_f32 v21, -v33, v40, v34
	s_mov_b64 vcc, s[0:1]
	v_div_fmas_f32 v21, v21, v37, v40
	v_cmp_ngt_f32_e32 vcc, s45, v20
	v_fma_f32 v41, -v35, v38, 1.0
	v_div_fixup_f32 v64, v21, v26, v18
	v_cndmask_b32_e32 v18, v61, v29, vcc
	v_div_scale_f32 v36, s[2:3], v19, v27, v19
	v_fmac_f32_e32 v38, v41, v38
	v_add_f32_e32 v18, 1.0, v18
	v_mul_f32_e32 v41, v36, v38
	v_div_scale_f32 v21, s[0:1], v18, v18, v20
	v_fma_f32 v42, -v35, v41, v36
	v_rcp_f32_e32 v26, v21
	v_fmac_f32_e32 v41, v42, v38
	v_fma_f32 v28, -v35, v41, v36
	s_mov_b64 vcc, s[2:3]
	v_div_fmas_f32 v28, v28, v38, v41
	v_div_fixup_f32 v65, v28, v27, v19
	v_fma_f32 v19, -v21, v26, 1.0
	v_fmac_f32_e32 v26, v19, v26
	v_div_scale_f32 v19, vcc, v20, v18, v20
	v_mul_f32_e32 v27, v19, v26
	v_fma_f32 v28, -v21, v27, v19
	v_fmac_f32_e32 v27, v28, v26
	v_fma_f32 v19, -v21, v27, v19
	v_readlane_b32 s0, v245, 63
	v_div_fmas_f32 v19, v19, v26, v27
	v_readlane_b32 s1, v244, 0
	v_div_fixup_f32 v66, v19, v18, v20
	s_nop 0
	v_lshl_add_u64 v[26:27], s[0:1], 0, v[22:23]
.LBB0_19:
	v_add_co_u32_e32 v54, vcc, 0xffe98000, v26
	v_add_co_u32_e64 v56, s[2:3], s67, v26
	s_nop 0
	v_addc_co_u32_e32 v55, vcc, -1, v27, vcc
	global_load_dwordx4 v[68:71], v[54:55], off nt
	v_readlane_b32 s64, v63, s63
	v_readlane_b32 s34, v64, s63
	v_readlane_b32 s96, v65, s63
	v_readlane_b32 s86, v66, s63
	s_add_i32 s87, s63, 7
	v_addc_co_u32_e64 v57, s[0:1], -1, v27, s[2:3]
	s_add_i32 s36, s63, 1
	v_add_co_u32_e64 v52, s[4:5], s69, v26
	v_add_co_u32_e64 v30, s[16:17], s49, v26
	v_add_co_u32_e64 v34, s[18:19], s51, v26
	v_add_co_u32_e64 v36, s[20:21], s53, v26
	v_add_co_u32_e64 v40, s[22:23], s55, v26
	v_addc_co_u32_e64 v53, s[0:1], -1, v27, s[4:5]
	v_addc_co_u32_e64 v31, s[0:1], -1, v27, s[16:17]
	v_addc_co_u32_e64 v35, s[0:1], -1, v27, s[18:19]
	v_addc_co_u32_e64 v37, s[0:1], -1, v27, s[20:21]
	v_addc_co_u32_e64 v41, s[0:1], -1, v27, s[22:23]
	v_readlane_b32 s16, v63, s36
	v_readlane_b32 s18, v64, s36
	v_readlane_b32 s20, v65, s36
	v_readlane_b32 s22, v66, s36
	s_add_i32 s38, s63, 2
	v_add_co_u32_e64 v48, s[6:7], s71, v26
	v_add_co_u32_e64 v46, s[26:27], s59, v26
	v_add_co_u32_e64 v50, s[28:29], s65, v26
	v_addc_co_u32_e64 v49, s[0:1], -1, v27, s[6:7]
	v_addc_co_u32_e64 v47, s[0:1], -1, v27, s[26:27]
	v_addc_co_u32_e64 v51, s[0:1], -1, v27, s[28:29]
	v_readlane_b32 s26, v63, s38
	v_readlane_b32 s28, v64, s38
	v_readlane_b32 s52, v65, s38
	v_readlane_b32 s50, v66, s38
	s_add_i32 s44, s63, 3
	v_add_co_u32_e64 v44, s[8:9], s73, v26
	v_readlane_b32 s38, v63, s44
	s_nop 0
	v_addc_co_u32_e64 v45, s[0:1], -1, v27, s[8:9]
	v_readlane_b32 s40, v64, s44
	v_readlane_b32 s42, v65, s44
	v_readlane_b32 s44, v66, s44
	s_add_i32 s54, s63, 4
	v_add_co_u32_e64 v38, s[10:11], s75, v26
	v_readlane_b32 s46, v63, s54
	s_nop 0
	v_addc_co_u32_e64 v39, s[0:1], -1, v27, s[10:11]
	v_readlane_b32 s48, v64, s54
	v_readlane_b32 s56, v65, s54
	v_readlane_b32 s58, v66, s54
	s_add_i32 s70, s63, 5
	v_add_co_u32_e64 v32, s[12:13], s77, v26
	v_readlane_b32 s74, v63, s70
	s_nop 0
	v_addc_co_u32_e64 v33, s[0:1], -1, v27, s[12:13]
	v_readlane_b32 s66, v64, s70
	v_readlane_b32 s68, v65, s70
	v_readlane_b32 s70, v66, s70
	global_load_dwordx4 v[18:21], v[26:27], off nt
	s_add_i32 s84, s63, 6
	v_add_co_u32_e64 v28, s[14:15], s47, v26
	s_waitcnt vmcnt(1)
; __device__ __forceinline__ float rdlane(float v, int l) { return __int_as_float(__builtin_amdgcn_readlane(__float_as_int(v), l)); }
; __device__ __forceinline__ void p0_prologue(Frame& F) {
;     ...
;                 for (int kk = 0; kk < 64; ++kk) { const f32x4 w = *(const f32x4*)(wp + (size_t)kk * NADA);
;                     a0 += w * rdlane(s0, kk); a1 += w * rdlane(s1, kk); a2 += w * rdlane(s2, kk); a3 += w * rdlane(s3, kk); }
	v_pk_fma_f32 v[14:15], v[68:69], s[64:65], v[14:15] op_sel_hi:[1,0,1]
	v_pk_fma_f32 v[10:11], v[68:69], s[34:35], v[10:11] op_sel_hi:[1,0,1]
	v_pk_fma_f32 v[6:7], v[68:69], s[96:97], v[6:7] op_sel_hi:[1,0,1]
	v_pk_fma_f32 v[54:55], v[70:71], s[86:87], v[4:5] op_sel_hi:[1,0,1]
	v_pk_fma_f32 v[68:69], v[68:69], s[86:87], v[2:3] op_sel_hi:[1,0,1]
	global_load_dwordx4 v[2:5], v[56:57], off nt
	v_pk_fma_f32 v[16:17], v[70:71], s[64:65], v[16:17] op_sel_hi:[1,0,1]
	v_pk_fma_f32 v[12:13], v[70:71], s[34:35], v[12:13] op_sel_hi:[1,0,1]
	v_pk_fma_f32 v[8:9], v[70:71], s[96:97], v[8:9] op_sel_hi:[1,0,1]
	v_add_co_u32_e64 v42, s[24:25], s57, v26
	v_addc_co_u32_e64 v29, s[0:1], -1, v27, s[14:15]
	s_nop 0
	v_addc_co_u32_e64 v43, s[0:1], -1, v27, s[24:25]
	v_readlane_b32 s72, v63, s84
	v_readlane_b32 s76, v64, s84
	v_readlane_b32 s36, v65, s84
	v_readlane_b32 s24, v66, s84
	s_add_i32 s88, s63, 8
	v_readlane_b32 s10, v63, s87
	v_readlane_b32 s0, v64, s87
	v_readlane_b32 s2, v65, s87
	v_readlane_b32 s4, v66, s87
	s_add_i32 s90, s63, 9
	v_readlane_b32 s6, v63, s88
	v_readlane_b32 s8, v64, s88
	v_readlane_b32 s14, v65, s88
	v_readlane_b32 s12, v66, s88
	s_add_i32 s89, s63, 10
	s_add_i32 s85, s63, 11
	v_readlane_b32 s34, v66, s89
	s_add_i32 s83, s63, 12
	v_readlane_b32 s54, v63, s85
	s_add_i32 s82, s63, 13
	s_add_i32 s81, s63, 14
	v_readlane_b32 s64, v65, s82
	s_add_i32 s78, s63, 15
	s_add_i32 s63, s63, 16
	s_cmp_lg_u32 s63, 64
	s_waitcnt vmcnt(0)
	v_pk_fma_f32 v[16:17], v[4:5], s[16:17], v[16:17] op_sel_hi:[1,0,1]
	v_pk_fma_f32 v[14:15], v[2:3], s[16:17], v[14:15] op_sel_hi:[1,0,1]
	v_pk_fma_f32 v[12:13], v[4:5], s[18:19], v[12:13] op_sel_hi:[1,0,1]
	v_pk_fma_f32 v[10:11], v[2:3], s[18:19], v[10:11] op_sel_hi:[1,0,1]
	v_pk_fma_f32 v[8:9], v[4:5], s[20:21], v[8:9] op_sel_hi:[1,0,1]
	v_pk_fma_f32 v[6:7], v[2:3], s[20:21], v[6:7] op_sel_hi:[1,0,1]
	v_pk_fma_f32 v[54:55], v[4:5], s[22:23], v[54:55] op_sel_hi:[1,0,1]
	v_pk_fma_f32 v[56:57], v[2:3], s[22:23], v[68:69] op_sel_hi:[1,0,1]
	global_load_dwordx4 v[2:5], v[52:53], off nt
	v_readlane_b32 s16, v63, s90
	v_readlane_b32 s18, v64, s90
	v_readlane_b32 s20, v65, s90
	v_readlane_b32 s22, v66, s90
	s_waitcnt vmcnt(0)
	v_pk_fma_f32 v[16:17], v[4:5], s[26:27], v[16:17] op_sel_hi:[1,0,1]
	v_pk_fma_f32 v[14:15], v[2:3], s[26:27], v[14:15] op_sel_hi:[1,0,1]
	v_pk_fma_f32 v[12:13], v[4:5], s[28:29], v[12:13] op_sel_hi:[1,0,1]
	v_pk_fma_f32 v[10:11], v[2:3], s[28:29], v[10:11] op_sel_hi:[1,0,1]
	v_pk_fma_f32 v[8:9], v[4:5], s[52:53], v[8:9] op_sel_hi:[1,0,1]
	v_pk_fma_f32 v[6:7], v[2:3], s[52:53], v[6:7] op_sel_hi:[1,0,1]
	v_pk_fma_f32 v[52:53], v[4:5], s[50:51], v[54:55] op_sel_hi:[1,0,1]
	v_pk_fma_f32 v[54:55], v[2:3], s[50:51], v[56:57] op_sel_hi:[1,0,1]
	global_load_dwordx4 v[2:5], v[48:49], off nt
	v_readlane_b32 s26, v63, s89
	v_readlane_b32 s28, v64, s89
	v_readlane_b32 s52, v65, s89
	v_readlane_b32 s50, v65, s83
	s_waitcnt vmcnt(0)
	v_pk_fma_f32 v[16:17], v[4:5], s[38:39], v[16:17] op_sel_hi:[1,0,1]
	v_pk_fma_f32 v[14:15], v[2:3], s[38:39], v[14:15] op_sel_hi:[1,0,1]
	v_pk_fma_f32 v[12:13], v[4:5], s[40:41], v[12:13] op_sel_hi:[1,0,1]
	v_pk_fma_f32 v[10:11], v[2:3], s[40:41], v[10:11] op_sel_hi:[1,0,1]
	v_pk_fma_f32 v[8:9], v[4:5], s[42:43], v[8:9] op_sel_hi:[1,0,1]
	v_pk_fma_f32 v[6:7], v[2:3], s[42:43], v[6:7] op_sel_hi:[1,0,1]
	v_pk_fma_f32 v[48:49], v[4:5], s[44:45], v[52:53] op_sel_hi:[1,0,1]
	v_pk_fma_f32 v[52:53], v[2:3], s[44:45], v[54:55] op_sel_hi:[1,0,1]
	global_load_dwordx4 v[2:5], v[44:45], off nt
	v_readlane_b32 s38, v64, s85
	v_readlane_b32 s40, v65, s85
	v_readlane_b32 s42, v66, s85
	v_readlane_b32 s44, v63, s83
	s_waitcnt vmcnt(0)
	v_pk_fma_f32 v[16:17], v[4:5], s[46:47], v[16:17] op_sel_hi:[1,0,1]
	v_pk_fma_f32 v[14:15], v[2:3], s[46:47], v[14:15] op_sel_hi:[1,0,1]
	v_pk_fma_f32 v[12:13], v[4:5], s[48:49], v[12:13] op_sel_hi:[1,0,1]
	v_pk_fma_f32 v[10:11], v[2:3], s[48:49], v[10:11] op_sel_hi:[1,0,1]
	v_pk_fma_f32 v[8:9], v[4:5], s[56:57], v[8:9] op_sel_hi:[1,0,1]
	v_pk_fma_f32 v[6:7], v[2:3], s[56:57], v[6:7] op_sel_hi:[1,0,1]
	v_pk_fma_f32 v[44:45], v[4:5], s[58:59], v[48:49] op_sel_hi:[1,0,1]
	v_pk_fma_f32 v[48:49], v[2:3], s[58:59], v[52:53] op_sel_hi:[1,0,1]
	global_load_dwordx4 v[2:5], v[38:39], off nt
	v_readlane_b32 s46, v64, s83
	v_readlane_b32 s48, v66, s83
	v_readlane_b32 s56, v63, s82
	v_readlane_b32 s58, v64, s82
	s_waitcnt vmcnt(0)
	v_pk_fma_f32 v[16:17], v[4:5], s[74:75], v[16:17] op_sel_hi:[1,0,1]
	v_pk_fma_f32 v[14:15], v[2:3], s[74:75], v[14:15] op_sel_hi:[1,0,1]
	v_pk_fma_f32 v[12:13], v[4:5], s[66:67], v[12:13] op_sel_hi:[1,0,1]
	v_pk_fma_f32 v[10:11], v[2:3], s[66:67], v[10:11] op_sel_hi:[1,0,1]
	v_pk_fma_f32 v[52:53], v[4:5], s[68:69], v[8:9] op_sel_hi:[1,0,1]
	v_pk_fma_f32 v[54:55], v[2:3], s[68:69], v[6:7] op_sel_hi:[1,0,1]
	v_pk_fma_f32 v[56:57], v[4:5], s[70:71], v[44:45] op_sel_hi:[1,0,1]
	v_pk_fma_f32 v[48:49], v[2:3], s[70:71], v[48:49] op_sel_hi:[1,0,1]
	global_load_dwordx4 v[2:5], v[32:33], off nt
	v_readlane_b32 s66, v66, s82
	v_readlane_b32 s68, v63, s81
	v_readlane_b32 s70, v64, s81
	v_readlane_b32 s74, v65, s81
	v_lshl_add_u64 v[26:27], v[26:27], 0, s[60:61]
	s_waitcnt vmcnt(0)
; __device__ __forceinline__ float rdlane(float v, int l) { return __int_as_float(__builtin_amdgcn_readlane(__float_as_int(v), l)); }
; __device__ __forceinline__ void p0_prologue(Frame& F) {
;     ...
;                 for (int kk = 0; kk < 64; ++kk) { const f32x4 w = *(const f32x4*)(wp + (size_t)kk * NADA);
;                     a0 += w * rdlane(s0, kk); a1 += w * rdlane(s1, kk); a2 += w * rdlane(s2, kk); a3 += w * rdlane(s3, kk); }
	v_pk_fma_f32 v[68:69], v[4:5], s[72:73], v[16:17] op_sel_hi:[1,0,1]
	v_pk_fma_f32 v[70:71], v[2:3], s[72:73], v[14:15] op_sel_hi:[1,0,1]
	v_pk_fma_f32 v[72:73], v[4:5], s[76:77], v[12:13] op_sel_hi:[1,0,1]
	v_pk_fma_f32 v[74:75], v[2:3], s[76:77], v[10:11] op_sel_hi:[1,0,1]
	global_load_dwordx4 v[6:9], v[28:29], off nt
	global_load_dwordx4 v[10:13], v[30:31], off nt
	global_load_dwordx4 v[14:17], v[34:35], off nt
	s_nop 0
	global_load_dwordx4 v[28:31], v[36:37], off nt
	global_load_dwordx4 v[32:35], v[40:41], off nt
	s_nop 0
	global_load_dwordx4 v[36:39], v[42:43], off nt
	s_nop 0
	global_load_dwordx4 v[40:43], v[46:47], off nt
	s_nop 0
	global_load_dwordx4 v[44:47], v[50:51], off nt
	v_pk_fma_f32 v[50:51], v[4:5], s[36:37], v[52:53] op_sel_hi:[1,0,1]
	v_pk_fma_f32 v[52:53], v[2:3], s[36:37], v[54:55] op_sel_hi:[1,0,1]
	v_pk_fma_f32 v[4:5], v[4:5], s[24:25], v[56:57] op_sel_hi:[1,0,1]
	v_pk_fma_f32 v[2:3], v[2:3], s[24:25], v[48:49] op_sel_hi:[1,0,1]
	v_readlane_b32 s72, v66, s81
	v_readlane_b32 s76, v63, s78
	v_readlane_b32 s36, v64, s78
	v_readlane_b32 s24, v65, s78
	s_waitcnt vmcnt(7)
	v_pk_fma_f32 v[48:49], v[8:9], s[10:11], v[68:69] op_sel_hi:[1,0,1]
	v_pk_fma_f32 v[54:55], v[6:7], s[10:11], v[70:71] op_sel_hi:[1,0,1]
	v_pk_fma_f32 v[56:57], v[8:9], s[0:1], v[72:73] op_sel_hi:[1,0,1]
	v_pk_fma_f32 v[68:69], v[6:7], s[0:1], v[74:75] op_sel_hi:[1,0,1]
	v_pk_fma_f32 v[50:51], v[8:9], s[2:3], v[50:51] op_sel_hi:[1,0,1]
	v_pk_fma_f32 v[52:53], v[6:7], s[2:3], v[52:53] op_sel_hi:[1,0,1]
	v_pk_fma_f32 v[4:5], v[8:9], s[4:5], v[4:5] op_sel_hi:[1,0,1]
	v_pk_fma_f32 v[2:3], v[6:7], s[4:5], v[2:3] op_sel_hi:[1,0,1]
	s_waitcnt vmcnt(6)
	v_pk_fma_f32 v[6:7], v[12:13], s[6:7], v[48:49] op_sel_hi:[1,0,1]
	v_pk_fma_f32 v[8:9], v[10:11], s[6:7], v[54:55] op_sel_hi:[1,0,1]
	v_pk_fma_f32 v[48:49], v[12:13], s[8:9], v[56:57] op_sel_hi:[1,0,1]
	v_pk_fma_f32 v[54:55], v[10:11], s[8:9], v[68:69] op_sel_hi:[1,0,1]
	v_pk_fma_f32 v[50:51], v[12:13], s[14:15], v[50:51] op_sel_hi:[1,0,1]
	v_pk_fma_f32 v[52:53], v[10:11], s[14:15], v[52:53] op_sel_hi:[1,0,1]
	v_pk_fma_f32 v[4:5], v[12:13], s[12:13], v[4:5] op_sel_hi:[1,0,1]
	v_pk_fma_f32 v[2:3], v[10:11], s[12:13], v[2:3] op_sel_hi:[1,0,1]
	s_waitcnt vmcnt(5)
	v_pk_fma_f32 v[6:7], v[16:17], s[16:17], v[6:7] op_sel_hi:[1,0,1]
	v_pk_fma_f32 v[8:9], v[14:15], s[16:17], v[8:9] op_sel_hi:[1,0,1]
	v_pk_fma_f32 v[10:11], v[16:17], s[18:19], v[48:49] op_sel_hi:[1,0,1]
	v_pk_fma_f32 v[12:13], v[14:15], s[18:19], v[54:55] op_sel_hi:[1,0,1]
	v_pk_fma_f32 v[48:49], v[16:17], s[20:21], v[50:51] op_sel_hi:[1,0,1]
	v_pk_fma_f32 v[50:51], v[14:15], s[20:21], v[52:53] op_sel_hi:[1,0,1]
	v_pk_fma_f32 v[4:5], v[16:17], s[22:23], v[4:5] op_sel_hi:[1,0,1]
	v_pk_fma_f32 v[2:3], v[14:15], s[22:23], v[2:3] op_sel_hi:[1,0,1]
	s_waitcnt vmcnt(4)
	v_pk_fma_f32 v[6:7], v[30:31], s[26:27], v[6:7] op_sel_hi:[1,0,1]
	v_pk_fma_f32 v[8:9], v[28:29], s[26:27], v[8:9] op_sel_hi:[1,0,1]
	v_pk_fma_f32 v[10:11], v[30:31], s[28:29], v[10:11] op_sel_hi:[1,0,1]
	v_pk_fma_f32 v[12:13], v[28:29], s[28:29], v[12:13] op_sel_hi:[1,0,1]
	v_pk_fma_f32 v[14:15], v[30:31], s[52:53], v[48:49] op_sel_hi:[1,0,1]
	v_pk_fma_f32 v[16:17], v[28:29], s[52:53], v[50:51] op_sel_hi:[1,0,1]
	v_pk_fma_f32 v[4:5], v[30:31], s[34:35], v[4:5] op_sel_hi:[1,0,1]
	v_pk_fma_f32 v[2:3], v[28:29], s[34:35], v[2:3] op_sel_hi:[1,0,1]
	s_waitcnt vmcnt(3)
	v_pk_fma_f32 v[6:7], v[34:35], s[54:55], v[6:7] op_sel_hi:[1,0,1]
	v_pk_fma_f32 v[8:9], v[32:33], s[54:55], v[8:9] op_sel_hi:[1,0,1]
	v_pk_fma_f32 v[10:11], v[34:35], s[38:39], v[10:11] op_sel_hi:[1,0,1]
	v_pk_fma_f32 v[12:13], v[32:33], s[38:39], v[12:13] op_sel_hi:[1,0,1]
	v_pk_fma_f32 v[14:15], v[34:35], s[40:41], v[14:15] op_sel_hi:[1,0,1]
	v_pk_fma_f32 v[16:17], v[32:33], s[40:41], v[16:17] op_sel_hi:[1,0,1]
	v_pk_fma_f32 v[4:5], v[34:35], s[42:43], v[4:5] op_sel_hi:[1,0,1]
	v_pk_fma_f32 v[2:3], v[32:33], s[42:43], v[2:3] op_sel_hi:[1,0,1]
	s_waitcnt vmcnt(2)
	v_pk_fma_f32 v[6:7], v[38:39], s[44:45], v[6:7] op_sel_hi:[1,0,1]
	v_pk_fma_f32 v[8:9], v[36:37], s[44:45], v[8:9] op_sel_hi:[1,0,1]
	v_pk_fma_f32 v[10:11], v[38:39], s[46:47], v[10:11] op_sel_hi:[1,0,1]
	v_pk_fma_f32 v[12:13], v[36:37], s[46:47], v[12:13] op_sel_hi:[1,0,1]
	v_pk_fma_f32 v[14:15], v[38:39], s[50:51], v[14:15] op_sel_hi:[1,0,1]
	v_pk_fma_f32 v[16:17], v[36:37], s[50:51], v[16:17] op_sel_hi:[1,0,1]
	v_pk_fma_f32 v[4:5], v[38:39], s[48:49], v[4:5] op_sel_hi:[1,0,1]
	v_pk_fma_f32 v[2:3], v[36:37], s[48:49], v[2:3] op_sel_hi:[1,0,1]
	s_waitcnt vmcnt(1)
	v_pk_fma_f32 v[6:7], v[42:43], s[56:57], v[6:7] op_sel_hi:[1,0,1]
	v_pk_fma_f32 v[8:9], v[40:41], s[56:57], v[8:9] op_sel_hi:[1,0,1]
	v_pk_fma_f32 v[10:11], v[42:43], s[58:59], v[10:11] op_sel_hi:[1,0,1]
	v_pk_fma_f32 v[12:13], v[40:41], s[58:59], v[12:13] op_sel_hi:[1,0,1]
	v_pk_fma_f32 v[14:15], v[42:43], s[64:65], v[14:15] op_sel_hi:[1,0,1]
	v_pk_fma_f32 v[16:17], v[40:41], s[64:65], v[16:17] op_sel_hi:[1,0,1]
	v_pk_fma_f32 v[4:5], v[42:43], s[66:67], v[4:5] op_sel_hi:[1,0,1]
	v_pk_fma_f32 v[2:3], v[40:41], s[66:67], v[2:3] op_sel_hi:[1,0,1]
	v_readlane_b32 s10, v66, s78
	s_waitcnt vmcnt(0)
	v_pk_fma_f32 v[6:7], v[46:47], s[68:69], v[6:7] op_sel_hi:[1,0,1]
	v_pk_fma_f32 v[8:9], v[44:45], s[68:69], v[8:9] op_sel_hi:[1,0,1]
	v_pk_fma_f32 v[10:11], v[46:47], s[70:71], v[10:11] op_sel_hi:[1,0,1]
	v_pk_fma_f32 v[28:29], v[44:45], s[70:71], v[12:13] op_sel_hi:[1,0,1]
	v_pk_fma_f32 v[30:31], v[46:47], s[74:75], v[14:15] op_sel_hi:[1,0,1]
	v_pk_fma_f32 v[32:33], v[44:45], s[74:75], v[16:17] op_sel_hi:[1,0,1]
	v_pk_fma_f32 v[4:5], v[46:47], s[72:73], v[4:5] op_sel_hi:[1,0,1]
	v_pk_fma_f32 v[2:3], v[44:45], s[72:73], v[2:3] op_sel_hi:[1,0,1]
	v_pk_fma_f32 v[16:17], v[20:21], s[76:77], v[6:7] op_sel_hi:[1,0,1]
	v_pk_fma_f32 v[14:15], v[18:19], s[76:77], v[8:9] op_sel_hi:[1,0,1]
	v_pk_fma_f32 v[12:13], v[20:21], s[36:37], v[10:11] op_sel_hi:[1,0,1]
	v_pk_fma_f32 v[10:11], v[18:19], s[36:37], v[28:29] op_sel_hi:[1,0,1]
	v_pk_fma_f32 v[8:9], v[20:21], s[24:25], v[30:31] op_sel_hi:[1,0,1]
	v_pk_fma_f32 v[6:7], v[18:19], s[24:25], v[32:33] op_sel_hi:[1,0,1]
	v_pk_fma_f32 v[4:5], v[20:21], s[10:11], v[4:5] op_sel_hi:[1,0,1]
	v_pk_fma_f32 v[2:3], v[18:19], s[10:11], v[2:3] op_sel_hi:[1,0,1]
	s_cbranch_scc1 .LBB0_19
; __device__ __forceinline__ void p0_prologue(Frame& F) {
;     ...
;             for (int k8 = 0; k8 < 4; ++k8) {
;                 const int kbase = 256 * kc + 64 * k8;
;                 float s0, s1, s2, s3;
;                 { const float x0 = F.c[0 * D + kbase + lane], x1 = F.c[1 * D + kbase + lane], x2 = F.c[2 * D + kbase + lane], x3 = F.c[3 * D + kbase + lane];
;                   s0 = x0 / (1.f + expf(-x0)); s1 = x1 / (1.f + expf(-x1)); s2 = x2 / (1.f + expf(-x2)); s3 = x3 / (1.f + expf(-x3)); }
;                 const float* wp = F.w_ada + (size_t)kbase * NADA + col;
	global_load_dword v28, v[24:25], off offset:512 nt
	s_or_b32 s0, s62, 0x80
	v_add_u32_e32 v18, s0, v58
	v_readlane_b32 s4, v245, 29
	v_add_u32_e32 v20, s0, v59
	v_ashrrev_i32_e32 v19, 31, v18
	v_readlane_b32 s6, v245, 31
	v_readlane_b32 s7, v245, 32
	v_ashrrev_i32_e32 v21, 31, v20
	v_add_u32_e32 v26, s0, v60
	v_lshl_add_u64 v[18:19], v[18:19], 2, s[6:7]
	v_lshl_add_u64 v[20:21], v[20:21], 2, s[6:7]
	v_ashrrev_i32_e32 v27, 31, v26
	v_lshl_add_u64 v[26:27], v[26:27], 2, s[6:7]
	global_load_dword v18, v[18:19], off nt
	s_nop 0
	global_load_dword v19, v[20:21], off nt
	s_nop 0
	global_load_dword v20, v[26:27], off nt
	s_mov_b32 s63, 0
	v_readlane_b32 s5, v245, 30
	v_readlane_b32 s8, v245, 33
	v_readlane_b32 s9, v245, 34
	v_readlane_b32 s10, v245, 35
	v_readlane_b32 s11, v245, 36
	v_readlane_b32 s12, v245, 37
	v_readlane_b32 s13, v245, 38
	v_readlane_b32 s14, v245, 39
	v_readlane_b32 s15, v245, 40
	v_readlane_b32 s16, v245, 41
	v_readlane_b32 s17, v245, 42
	v_readlane_b32 s18, v245, 43
	v_readlane_b32 s19, v245, 44
	s_waitcnt vmcnt(3)
	v_mul_f32_e32 v21, 0xbfb8aa3b, v28
	v_rndne_f32_e32 v26, v21
	v_fma_f32 v27, v28, s41, -v21
	v_sub_f32_e32 v21, v21, v26
	v_fmac_f32_e32 v27, 0xb2a5705f, v28
	v_add_f32_e32 v21, v21, v27
	v_cvt_i32_f32_e32 v26, v26
	v_exp_f32_e32 v21, v21
	v_cmp_nlt_f32_e32 vcc, s43, v28
	v_ldexp_f32 v21, v21, v26
	s_waitcnt vmcnt(2)
	v_mul_f32_e32 v27, 0xbfb8aa3b, v18
	s_waitcnt vmcnt(1)
	v_mul_f32_e32 v29, 0xbfb8aa3b, v19
	v_fma_f32 v31, v18, s41, -v27
	v_rndne_f32_e32 v32, v27
	s_waitcnt vmcnt(0)
	v_mul_f32_e32 v30, 0xbfb8aa3b, v20
	v_fma_f32 v33, v19, s41, -v29
	v_rndne_f32_e32 v34, v29
	v_fmac_f32_e32 v31, 0xb2a5705f, v18
	v_sub_f32_e32 v27, v27, v32
	v_fma_f32 v35, v20, s41, -v30
	v_rndne_f32_e32 v36, v30
	v_fmac_f32_e32 v33, 0xb2a5705f, v19
	v_sub_f32_e32 v29, v29, v34
	v_add_f32_e32 v27, v27, v31
	v_cvt_i32_f32_e32 v32, v32
	v_fmac_f32_e32 v35, 0xb2a5705f, v20
	v_sub_f32_e32 v30, v30, v36
	v_add_f32_e32 v29, v29, v33
	v_exp_f32_e32 v26, v27
	v_cndmask_b32_e32 v21, 0, v21, vcc
	v_cmp_ngt_f32_e32 vcc, s45, v28
	v_cvt_i32_f32_e32 v34, v34
	v_add_f32_e32 v30, v30, v35
	v_exp_f32_e32 v27, v29
	v_cndmask_b32_e32 v21, v61, v21, vcc
	v_cvt_i32_f32_e32 v36, v36
	v_exp_f32_e32 v29, v30
	v_add_f32_e32 v21, 1.0, v21
	v_div_scale_f32 v30, s[0:1], v21, v21, v28
	v_ldexp_f32 v26, v26, v32
	v_cmp_nlt_f32_e64 s[0:1], s43, v18
	v_ldexp_f32 v27, v27, v34
	v_ldexp_f32 v29, v29, v36
	v_cndmask_b32_e64 v26, 0, v26, s[0:1]
	v_cmp_nlt_f32_e64 s[0:1], s43, v19
	v_rcp_f32_e32 v32, v30
	v_div_scale_f32 v31, vcc, v28, v21, v28
	v_cndmask_b32_e64 v27, 0, v27, s[0:1]
	v_cmp_nlt_f32_e64 s[0:1], s43, v20
	v_fma_f32 v37, -v30, v32, 1.0
	v_fmac_f32_e32 v32, v37, v32
	v_cndmask_b32_e64 v29, 0, v29, s[0:1]
	v_cmp_ngt_f32_e64 s[0:1], s45, v18
	v_mul_f32_e32 v37, v31, v32
	v_fma_f32 v40, -v30, v37, v31
	v_cndmask_b32_e64 v26, v61, v26, s[0:1]
	v_cmp_ngt_f32_e64 s[0:1], s45, v19
	v_add_f32_e32 v26, 1.0, v26
	v_fmac_f32_e32 v37, v40, v32
	v_cndmask_b32_e64 v27, v61, v27, s[0:1]
	v_cmp_ngt_f32_e64 s[0:1], s45, v20
	v_add_f32_e32 v27, 1.0, v27
	v_div_scale_f32 v35, s[2:3], v27, v27, v19
	v_cndmask_b32_e64 v29, v61, v29, s[0:1]
	v_div_scale_f32 v33, s[0:1], v26, v26, v18
	v_rcp_f32_e32 v38, v33
	v_div_scale_f32 v34, s[0:1], v18, v26, v18
	v_rcp_f32_e32 v39, v35
	v_fma_f32 v40, -v33, v38, 1.0
	v_fma_f32 v30, -v30, v37, v31
	v_fmac_f32_e32 v38, v40, v38
	v_div_fmas_f32 v30, v30, v32, v37
	v_mul_f32_e32 v31, v34, v38
	v_div_fixup_f32 v63, v30, v21, v28
	v_fma_f32 v21, -v33, v31, v34
	v_fmac_f32_e32 v31, v21, v38
	v_fma_f32 v41, -v35, v39, 1.0
	v_fma_f32 v21, -v33, v31, v34
	s_mov_b64 vcc, s[0:1]
	v_add_f32_e32 v29, 1.0, v29
	v_div_scale_f32 v36, s[2:3], v19, v27, v19
	v_fmac_f32_e32 v39, v41, v39
	v_div_fmas_f32 v21, v21, v38, v31
	v_mul_f32_e32 v32, v36, v39
	v_div_fixup_f32 v64, v21, v26, v18
	v_div_scale_f32 v18, s[0:1], v29, v29, v20
	v_fma_f32 v28, -v35, v32, v36
	v_rcp_f32_e32 v21, v18
	v_fmac_f32_e32 v32, v28, v39
	v_fma_f32 v28, -v35, v32, v36
	s_mov_b64 vcc, s[2:3]
	v_div_fmas_f32 v26, v28, v39, v32
	v_div_fixup_f32 v65, v26, v27, v19
	v_fma_f32 v19, -v18, v21, 1.0
	v_fmac_f32_e32 v21, v19, v21
	v_div_scale_f32 v19, vcc, v20, v29, v20
	v_mul_f32_e32 v26, v19, v21
	v_fma_f32 v27, -v18, v26, v19
	v_fmac_f32_e32 v26, v27, v21
	v_fma_f32 v18, -v18, v26, v19
	v_readlane_b32 s0, v244, 1
	v_div_fmas_f32 v18, v18, v21, v26
	v_readlane_b32 s1, v244, 2
	v_div_fixup_f32 v66, v18, v29, v20
	s_nop 0
	v_lshl_add_u64 v[26:27], s[0:1], 0, v[22:23]
; __device__ __forceinline__ float rdlane(float v, int l) { return __int_as_float(__builtin_amdgcn_readlane(__float_as_int(v), l)); }
; __device__ __forceinline__ void p0_prologue(Frame& F) {
;     ...
;                 const float* wp = F.w_ada + (size_t)kbase * NADA + col;
; #pragma unroll 16
;                 for (int kk = 0; kk < 64; ++kk) { const f32x4 w = *(const f32x4*)(wp + (size_t)kk * NADA);
;                     a0 += w * rdlane(s0, kk); a1 += w * rdlane(s1, kk); a2 += w * rdlane(s2, kk); a3 += w * rdlane(s3, kk); }
.LBB0_21:
	v_add_co_u32_e32 v54, vcc, 0xffe98000, v26
	v_add_co_u32_e64 v56, s[2:3], s67, v26
	s_nop 0
	v_addc_co_u32_e32 v55, vcc, -1, v27, vcc
	global_load_dwordx4 v[68:71], v[54:55], off nt
	v_readlane_b32 s68, v63, s63
	v_readlane_b32 s66, v64, s63
	v_readlane_b32 s64, v65, s63
	v_readlane_b32 s34, v66, s63
	v_addc_co_u32_e64 v57, s[0:1], -1, v27, s[2:3]
	s_add_i32 s36, s63, 1
	v_add_co_u32_e64 v52, s[4:5], s69, v26
	v_add_co_u32_e64 v30, s[16:17], s49, v26
	v_add_co_u32_e64 v32, s[18:19], s51, v26
	v_add_co_u32_e64 v36, s[20:21], s53, v26
	v_add_co_u32_e64 v40, s[22:23], s55, v26
	v_addc_co_u32_e64 v53, s[0:1], -1, v27, s[4:5]
	v_addc_co_u32_e64 v31, s[0:1], -1, v27, s[16:17]
	v_addc_co_u32_e64 v33, s[0:1], -1, v27, s[18:19]
	v_addc_co_u32_e64 v37, s[0:1], -1, v27, s[20:21]
	v_addc_co_u32_e64 v41, s[0:1], -1, v27, s[22:23]
	v_readlane_b32 s16, v63, s36
	v_readlane_b32 s18, v64, s36
	v_readlane_b32 s20, v65, s36
	v_readlane_b32 s22, v66, s36
	s_add_i32 s38, s63, 2
	v_add_co_u32_e64 v48, s[6:7], s71, v26
	v_add_co_u32_e64 v46, s[26:27], s59, v26
	v_add_co_u32_e64 v50, s[28:29], s65, v26
	v_addc_co_u32_e64 v49, s[0:1], -1, v27, s[6:7]
	v_addc_co_u32_e64 v47, s[0:1], -1, v27, s[26:27]
	v_addc_co_u32_e64 v51, s[0:1], -1, v27, s[28:29]
	v_readlane_b32 s26, v63, s38
	v_readlane_b32 s28, v64, s38
	v_readlane_b32 s54, v65, s38
	v_readlane_b32 s48, v66, s38
	s_add_i32 s42, s63, 3
	v_add_co_u32_e64 v44, s[8:9], s73, v26
	v_readlane_b32 s36, v63, s42
	s_nop 0
	v_addc_co_u32_e64 v45, s[0:1], -1, v27, s[8:9]
	v_readlane_b32 s38, v64, s42
	v_readlane_b32 s40, v65, s42
	v_readlane_b32 s42, v66, s42
	s_add_i32 s52, s63, 4
	v_add_co_u32_e64 v38, s[10:11], s75, v26
	v_readlane_b32 s44, v63, s52
	s_nop 0
	v_addc_co_u32_e64 v39, s[0:1], -1, v27, s[10:11]
	v_readlane_b32 s46, v64, s52
	v_readlane_b32 s50, v65, s52
	v_readlane_b32 s58, v66, s52
	s_add_i32 s56, s63, 5
	v_add_co_u32_e64 v34, s[12:13], s77, v26
	s_add_i32 s87, s63, 11
	s_nop 0
	v_addc_co_u32_e64 v35, s[0:1], -1, v27, s[12:13]
	v_readlane_b32 s86, v63, s56
	v_readlane_b32 s78, v64, s56
	v_readlane_b32 s74, v65, s56
	v_readlane_b32 s70, v66, s56
	global_load_dwordx4 v[18:21], v[26:27], off nt
	s_add_i32 s85, s63, 6
	v_add_co_u32_e64 v28, s[14:15], s47, v26
	s_waitcnt vmcnt(1)
	v_pk_fma_f32 v[14:15], v[68:69], s[68:69], v[14:15] op_sel_hi:[1,0,1]
	v_pk_fma_f32 v[10:11], v[68:69], s[66:67], v[10:11] op_sel_hi:[1,0,1]
	v_pk_fma_f32 v[6:7], v[68:69], s[64:65], v[6:7] op_sel_hi:[1,0,1]
	v_pk_fma_f32 v[54:55], v[70:71], s[34:35], v[4:5] op_sel_hi:[1,0,1]
	v_pk_fma_f32 v[68:69], v[68:69], s[34:35], v[2:3] op_sel_hi:[1,0,1]
	global_load_dwordx4 v[2:5], v[56:57], off nt
	v_pk_fma_f32 v[16:17], v[70:71], s[68:69], v[16:17] op_sel_hi:[1,0,1]
	v_pk_fma_f32 v[12:13], v[70:71], s[66:67], v[12:13] op_sel_hi:[1,0,1]
	v_pk_fma_f32 v[8:9], v[70:71], s[64:65], v[8:9] op_sel_hi:[1,0,1]
	v_add_co_u32_e64 v42, s[24:25], s57, v26
	v_addc_co_u32_e64 v29, s[0:1], -1, v27, s[14:15]
	s_nop 0
	v_addc_co_u32_e64 v43, s[0:1], -1, v27, s[24:25]
	v_readlane_b32 s72, v63, s85
	v_readlane_b32 s76, v64, s85
	s_add_i32 s88, s63, 7
	v_readlane_b32 s52, v65, s85
	v_readlane_b32 s24, v66, s85
	s_add_i32 s89, s63, 8
	v_readlane_b32 s10, v63, s88
	v_readlane_b32 s0, v64, s88
	v_readlane_b32 s2, v65, s88
	v_readlane_b32 s4, v66, s88
	s_add_i32 s91, s63, 9
	v_readlane_b32 s6, v63, s89
	v_readlane_b32 s8, v64, s89
	v_readlane_b32 s14, v65, s89
	v_readlane_b32 s12, v66, s89
	s_add_i32 s90, s63, 10
	v_readlane_b32 s34, v66, s90
	s_add_i32 s84, s63, 12
	v_readlane_b32 s56, v63, s87
	s_add_i32 s83, s63, 13
	s_add_i32 s82, s63, 14
	v_readlane_b32 s64, v65, s83
	v_readlane_b32 s66, v66, s83
	s_add_i32 s81, s63, 15
	v_readlane_b32 s68, v63, s82
	s_add_i32 s63, s63, 16
	s_cmp_lg_u32 s63, 64
	s_waitcnt vmcnt(0)
	v_pk_fma_f32 v[16:17], v[4:5], s[16:17], v[16:17] op_sel_hi:[1,0,1]
	v_pk_fma_f32 v[14:15], v[2:3], s[16:17], v[14:15] op_sel_hi:[1,0,1]
	v_pk_fma_f32 v[12:13], v[4:5], s[18:19], v[12:13] op_sel_hi:[1,0,1]
	v_pk_fma_f32 v[10:11], v[2:3], s[18:19], v[10:11] op_sel_hi:[1,0,1]
	v_pk_fma_f32 v[8:9], v[4:5], s[20:21], v[8:9] op_sel_hi:[1,0,1]
	v_pk_fma_f32 v[6:7], v[2:3], s[20:21], v[6:7] op_sel_hi:[1,0,1]
	v_pk_fma_f32 v[54:55], v[4:5], s[22:23], v[54:55] op_sel_hi:[1,0,1]
	v_pk_fma_f32 v[56:57], v[2:3], s[22:23], v[68:69] op_sel_hi:[1,0,1]
	global_load_dwordx4 v[2:5], v[52:53], off nt
	v_readlane_b32 s16, v63, s91
	v_readlane_b32 s18, v64, s91
	v_readlane_b32 s20, v65, s91
	v_readlane_b32 s22, v66, s91
	s_waitcnt vmcnt(0)
	v_pk_fma_f32 v[16:17], v[4:5], s[26:27], v[16:17] op_sel_hi:[1,0,1]
	v_pk_fma_f32 v[14:15], v[2:3], s[26:27], v[14:15] op_sel_hi:[1,0,1]
	v_pk_fma_f32 v[12:13], v[4:5], s[28:29], v[12:13] op_sel_hi:[1,0,1]
	v_pk_fma_f32 v[10:11], v[2:3], s[28:29], v[10:11] op_sel_hi:[1,0,1]
	v_pk_fma_f32 v[8:9], v[4:5], s[54:55], v[8:9] op_sel_hi:[1,0,1]
	v_pk_fma_f32 v[6:7], v[2:3], s[54:55], v[6:7] op_sel_hi:[1,0,1]
	v_pk_fma_f32 v[52:53], v[4:5], s[48:49], v[54:55] op_sel_hi:[1,0,1]
	v_pk_fma_f32 v[54:55], v[2:3], s[48:49], v[56:57] op_sel_hi:[1,0,1]
	global_load_dwordx4 v[2:5], v[48:49], off nt
	v_readlane_b32 s26, v63, s90
	v_readlane_b32 s28, v64, s90
	v_readlane_b32 s54, v65, s90
	v_readlane_b32 s48, v65, s84
	s_waitcnt vmcnt(0)
	v_pk_fma_f32 v[16:17], v[4:5], s[36:37], v[16:17] op_sel_hi:[1,0,1]
	v_pk_fma_f32 v[14:15], v[2:3], s[36:37], v[14:15] op_sel_hi:[1,0,1]
	v_pk_fma_f32 v[12:13], v[4:5], s[38:39], v[12:13] op_sel_hi:[1,0,1]
	v_pk_fma_f32 v[10:11], v[2:3], s[38:39], v[10:11] op_sel_hi:[1,0,1]
	v_pk_fma_f32 v[8:9], v[4:5], s[40:41], v[8:9] op_sel_hi:[1,0,1]
	v_pk_fma_f32 v[6:7], v[2:3], s[40:41], v[6:7] op_sel_hi:[1,0,1]
	v_pk_fma_f32 v[48:49], v[4:5], s[42:43], v[52:53] op_sel_hi:[1,0,1]
	v_pk_fma_f32 v[52:53], v[2:3], s[42:43], v[54:55] op_sel_hi:[1,0,1]
	global_load_dwordx4 v[2:5], v[44:45], off nt
	v_readlane_b32 s36, v64, s87
	v_readlane_b32 s38, v65, s87
	v_readlane_b32 s40, v66, s87
	v_readlane_b32 s42, v63, s84
	s_waitcnt vmcnt(0)
; __device__ __forceinline__ float rdlane(float v, int l) { return __int_as_float(__builtin_amdgcn_readlane(__float_as_int(v), l)); }
; __device__ __forceinline__ void p0_prologue(Frame& F) {
;     ...
;                 const float* wp = F.w_ada + (size_t)kbase * NADA + col;
; #pragma unroll 16
;                 for (int kk = 0; kk < 64; ++kk) { const f32x4 w = *(const f32x4*)(wp + (size_t)kk * NADA);
;                     a0 += w * rdlane(s0, kk); a1 += w * rdlane(s1, kk); a2 += w * rdlane(s2, kk); a3 += w * rdlane(s3, kk); }
	v_pk_fma_f32 v[16:17], v[4:5], s[44:45], v[16:17] op_sel_hi:[1,0,1]
	v_pk_fma_f32 v[14:15], v[2:3], s[44:45], v[14:15] op_sel_hi:[1,0,1]
	v_pk_fma_f32 v[12:13], v[4:5], s[46:47], v[12:13] op_sel_hi:[1,0,1]
	v_pk_fma_f32 v[10:11], v[2:3], s[46:47], v[10:11] op_sel_hi:[1,0,1]
	v_pk_fma_f32 v[8:9], v[4:5], s[50:51], v[8:9] op_sel_hi:[1,0,1]
	v_pk_fma_f32 v[6:7], v[2:3], s[50:51], v[6:7] op_sel_hi:[1,0,1]
	v_pk_fma_f32 v[44:45], v[4:5], s[58:59], v[48:49] op_sel_hi:[1,0,1]
	v_pk_fma_f32 v[48:49], v[2:3], s[58:59], v[52:53] op_sel_hi:[1,0,1]
	global_load_dwordx4 v[2:5], v[38:39], off nt
	v_readlane_b32 s44, v64, s84
	v_readlane_b32 s46, v66, s84
	v_readlane_b32 s50, v63, s83
	v_readlane_b32 s58, v64, s83
	s_waitcnt vmcnt(0)
	v_pk_fma_f32 v[16:17], v[4:5], s[86:87], v[16:17] op_sel_hi:[1,0,1]
	v_pk_fma_f32 v[14:15], v[2:3], s[86:87], v[14:15] op_sel_hi:[1,0,1]
	v_pk_fma_f32 v[12:13], v[4:5], s[78:79], v[12:13] op_sel_hi:[1,0,1]
	v_pk_fma_f32 v[10:11], v[2:3], s[78:79], v[10:11] op_sel_hi:[1,0,1]
	v_pk_fma_f32 v[52:53], v[4:5], s[74:75], v[8:9] op_sel_hi:[1,0,1]
	v_pk_fma_f32 v[54:55], v[2:3], s[74:75], v[6:7] op_sel_hi:[1,0,1]
	v_pk_fma_f32 v[56:57], v[4:5], s[70:71], v[44:45] op_sel_hi:[1,0,1]
	v_pk_fma_f32 v[48:49], v[2:3], s[70:71], v[48:49] op_sel_hi:[1,0,1]
	global_load_dwordx4 v[2:5], v[34:35], off nt
	v_readlane_b32 s70, v64, s82
	v_readlane_b32 s74, v65, s82
	v_lshl_add_u64 v[26:27], v[26:27], 0, s[60:61]
	s_waitcnt vmcnt(0)
	v_pk_fma_f32 v[68:69], v[4:5], s[72:73], v[16:17] op_sel_hi:[1,0,1]
	v_pk_fma_f32 v[70:71], v[2:3], s[72:73], v[14:15] op_sel_hi:[1,0,1]
	v_pk_fma_f32 v[72:73], v[4:5], s[76:77], v[12:13] op_sel_hi:[1,0,1]
	v_pk_fma_f32 v[74:75], v[2:3], s[76:77], v[10:11] op_sel_hi:[1,0,1]
	global_load_dwordx4 v[6:9], v[28:29], off nt
	global_load_dwordx4 v[10:13], v[30:31], off nt
	global_load_dwordx4 v[14:17], v[32:33], off nt
	s_nop 0
	global_load_dwordx4 v[28:31], v[36:37], off nt
	global_load_dwordx4 v[32:35], v[40:41], off nt
	s_nop 0
	global_load_dwordx4 v[36:39], v[42:43], off nt
	s_nop 0
	global_load_dwordx4 v[40:43], v[46:47], off nt
	s_nop 0
	global_load_dwordx4 v[44:47], v[50:51], off nt
	v_pk_fma_f32 v[50:51], v[4:5], s[52:53], v[52:53] op_sel_hi:[1,0,1]
	v_pk_fma_f32 v[52:53], v[2:3], s[52:53], v[54:55] op_sel_hi:[1,0,1]
	v_pk_fma_f32 v[4:5], v[4:5], s[24:25], v[56:57] op_sel_hi:[1,0,1]
	v_pk_fma_f32 v[2:3], v[2:3], s[24:25], v[48:49] op_sel_hi:[1,0,1]
	v_readlane_b32 s72, v66, s82
	v_readlane_b32 s76, v63, s81
	v_readlane_b32 s52, v64, s81
	v_readlane_b32 s24, v65, s81
	s_waitcnt vmcnt(7)
	v_pk_fma_f32 v[48:49], v[8:9], s[10:11], v[68:69] op_sel_hi:[1,0,1]
	v_pk_fma_f32 v[54:55], v[6:7], s[10:11], v[70:71] op_sel_hi:[1,0,1]
	v_pk_fma_f32 v[56:57], v[8:9], s[0:1], v[72:73] op_sel_hi:[1,0,1]
	v_pk_fma_f32 v[68:69], v[6:7], s[0:1], v[74:75] op_sel_hi:[1,0,1]
	v_pk_fma_f32 v[50:51], v[8:9], s[2:3], v[50:51] op_sel_hi:[1,0,1]
	v_pk_fma_f32 v[52:53], v[6:7], s[2:3], v[52:53] op_sel_hi:[1,0,1]
	v_pk_fma_f32 v[4:5], v[8:9], s[4:5], v[4:5] op_sel_hi:[1,0,1]
	v_pk_fma_f32 v[2:3], v[6:7], s[4:5], v[2:3] op_sel_hi:[1,0,1]
	s_waitcnt vmcnt(6)
	v_pk_fma_f32 v[6:7], v[12:13], s[6:7], v[48:49] op_sel_hi:[1,0,1]
	v_pk_fma_f32 v[8:9], v[10:11], s[6:7], v[54:55] op_sel_hi:[1,0,1]
	v_pk_fma_f32 v[48:49], v[12:13], s[8:9], v[56:57] op_sel_hi:[1,0,1]
	v_pk_fma_f32 v[54:55], v[10:11], s[8:9], v[68:69] op_sel_hi:[1,0,1]
	v_pk_fma_f32 v[50:51], v[12:13], s[14:15], v[50:51] op_sel_hi:[1,0,1]
	v_pk_fma_f32 v[52:53], v[10:11], s[14:15], v[52:53] op_sel_hi:[1,0,1]
	v_pk_fma_f32 v[4:5], v[12:13], s[12:13], v[4:5] op_sel_hi:[1,0,1]
	v_pk_fma_f32 v[2:3], v[10:11], s[12:13], v[2:3] op_sel_hi:[1,0,1]
	s_waitcnt vmcnt(5)
	v_pk_fma_f32 v[6:7], v[16:17], s[16:17], v[6:7] op_sel_hi:[1,0,1]
	v_pk_fma_f32 v[8:9], v[14:15], s[16:17], v[8:9] op_sel_hi:[1,0,1]
	v_pk_fma_f32 v[10:11], v[16:17], s[18:19], v[48:49] op_sel_hi:[1,0,1]
	v_pk_fma_f32 v[12:13], v[14:15], s[18:19], v[54:55] op_sel_hi:[1,0,1]
	v_pk_fma_f32 v[48:49], v[16:17], s[20:21], v[50:51] op_sel_hi:[1,0,1]
	v_pk_fma_f32 v[50:51], v[14:15], s[20:21], v[52:53] op_sel_hi:[1,0,1]
	v_pk_fma_f32 v[4:5], v[16:17], s[22:23], v[4:5] op_sel_hi:[1,0,1]
	v_pk_fma_f32 v[2:3], v[14:15], s[22:23], v[2:3] op_sel_hi:[1,0,1]
	s_waitcnt vmcnt(4)
	v_pk_fma_f32 v[6:7], v[30:31], s[26:27], v[6:7] op_sel_hi:[1,0,1]
	v_pk_fma_f32 v[8:9], v[28:29], s[26:27], v[8:9] op_sel_hi:[1,0,1]
	v_pk_fma_f32 v[10:11], v[30:31], s[28:29], v[10:11] op_sel_hi:[1,0,1]
	v_pk_fma_f32 v[12:13], v[28:29], s[28:29], v[12:13] op_sel_hi:[1,0,1]
	v_pk_fma_f32 v[14:15], v[30:31], s[54:55], v[48:49] op_sel_hi:[1,0,1]
	v_pk_fma_f32 v[16:17], v[28:29], s[54:55], v[50:51] op_sel_hi:[1,0,1]
	v_pk_fma_f32 v[4:5], v[30:31], s[34:35], v[4:5] op_sel_hi:[1,0,1]
	v_pk_fma_f32 v[2:3], v[28:29], s[34:35], v[2:3] op_sel_hi:[1,0,1]
	s_waitcnt vmcnt(3)
	v_pk_fma_f32 v[6:7], v[34:35], s[56:57], v[6:7] op_sel_hi:[1,0,1]
	v_pk_fma_f32 v[8:9], v[32:33], s[56:57], v[8:9] op_sel_hi:[1,0,1]
	v_pk_fma_f32 v[10:11], v[34:35], s[36:37], v[10:11] op_sel_hi:[1,0,1]
	v_pk_fma_f32 v[12:13], v[32:33], s[36:37], v[12:13] op_sel_hi:[1,0,1]
	v_pk_fma_f32 v[14:15], v[34:35], s[38:39], v[14:15] op_sel_hi:[1,0,1]
	v_pk_fma_f32 v[16:17], v[32:33], s[38:39], v[16:17] op_sel_hi:[1,0,1]
	v_pk_fma_f32 v[4:5], v[34:35], s[40:41], v[4:5] op_sel_hi:[1,0,1]
	v_pk_fma_f32 v[2:3], v[32:33], s[40:41], v[2:3] op_sel_hi:[1,0,1]
	s_waitcnt vmcnt(2)
; __device__ __forceinline__ float rdlane(float v, int l) { return __int_as_float(__builtin_amdgcn_readlane(__float_as_int(v), l)); }
; __device__ __forceinline__ void p0_prologue(Frame& F) {
;     ...
;                 float s0, s1, s2, s3;
;                 { const float x0 = F.c[0 * D + kbase + lane], x1 = F.c[1 * D + kbase + lane], x2 = F.c[2 * D + kbase + lane], x3 = F.c[3 * D + kbase + lane];
;                   s0 = x0 / (1.f + expf(-x0)); s1 = x1 / (1.f + expf(-x1)); s2 = x2 / (1.f + expf(-x2)); s3 = x3 / (1.f + expf(-x3)); }
;                 const float* wp = F.w_ada + (size_t)kbase * NADA + col;
; #pragma unroll 16
;                 for (int kk = 0; kk < 64; ++kk) { const f32x4 w = *(const f32x4*)(wp + (size_t)kk * NADA);
;                     a0 += w * rdlane(s0, kk); a1 += w * rdlane(s1, kk); a2 += w * rdlane(s2, kk); a3 += w * rdlane(s3, kk); }
	v_pk_fma_f32 v[6:7], v[38:39], s[42:43], v[6:7] op_sel_hi:[1,0,1]
	v_pk_fma_f32 v[8:9], v[36:37], s[42:43], v[8:9] op_sel_hi:[1,0,1]
	v_pk_fma_f32 v[10:11], v[38:39], s[44:45], v[10:11] op_sel_hi:[1,0,1]
	v_pk_fma_f32 v[12:13], v[36:37], s[44:45], v[12:13] op_sel_hi:[1,0,1]
	v_pk_fma_f32 v[14:15], v[38:39], s[48:49], v[14:15] op_sel_hi:[1,0,1]
	v_pk_fma_f32 v[16:17], v[36:37], s[48:49], v[16:17] op_sel_hi:[1,0,1]
	v_pk_fma_f32 v[4:5], v[38:39], s[46:47], v[4:5] op_sel_hi:[1,0,1]
	v_pk_fma_f32 v[2:3], v[36:37], s[46:47], v[2:3] op_sel_hi:[1,0,1]
	s_waitcnt vmcnt(1)
	v_pk_fma_f32 v[6:7], v[42:43], s[50:51], v[6:7] op_sel_hi:[1,0,1]
	v_pk_fma_f32 v[8:9], v[40:41], s[50:51], v[8:9] op_sel_hi:[1,0,1]
	v_pk_fma_f32 v[10:11], v[42:43], s[58:59], v[10:11] op_sel_hi:[1,0,1]
	v_pk_fma_f32 v[12:13], v[40:41], s[58:59], v[12:13] op_sel_hi:[1,0,1]
	v_pk_fma_f32 v[14:15], v[42:43], s[64:65], v[14:15] op_sel_hi:[1,0,1]
	v_pk_fma_f32 v[16:17], v[40:41], s[64:65], v[16:17] op_sel_hi:[1,0,1]
	v_pk_fma_f32 v[4:5], v[42:43], s[66:67], v[4:5] op_sel_hi:[1,0,1]
	v_pk_fma_f32 v[2:3], v[40:41], s[66:67], v[2:3] op_sel_hi:[1,0,1]
	v_readlane_b32 s10, v66, s81
	s_waitcnt vmcnt(0)
	v_pk_fma_f32 v[6:7], v[46:47], s[68:69], v[6:7] op_sel_hi:[1,0,1]
	v_pk_fma_f32 v[8:9], v[44:45], s[68:69], v[8:9] op_sel_hi:[1,0,1]
	v_pk_fma_f32 v[10:11], v[46:47], s[70:71], v[10:11] op_sel_hi:[1,0,1]
	v_pk_fma_f32 v[28:29], v[44:45], s[70:71], v[12:13] op_sel_hi:[1,0,1]
	v_pk_fma_f32 v[30:31], v[46:47], s[74:75], v[14:15] op_sel_hi:[1,0,1]
	v_pk_fma_f32 v[32:33], v[44:45], s[74:75], v[16:17] op_sel_hi:[1,0,1]
	v_pk_fma_f32 v[4:5], v[46:47], s[72:73], v[4:5] op_sel_hi:[1,0,1]
	v_pk_fma_f32 v[2:3], v[44:45], s[72:73], v[2:3] op_sel_hi:[1,0,1]
	v_pk_fma_f32 v[16:17], v[20:21], s[76:77], v[6:7] op_sel_hi:[1,0,1]
	v_pk_fma_f32 v[14:15], v[18:19], s[76:77], v[8:9] op_sel_hi:[1,0,1]
	v_pk_fma_f32 v[12:13], v[20:21], s[52:53], v[10:11] op_sel_hi:[1,0,1]
	v_pk_fma_f32 v[10:11], v[18:19], s[52:53], v[28:29] op_sel_hi:[1,0,1]
	v_pk_fma_f32 v[8:9], v[20:21], s[24:25], v[30:31] op_sel_hi:[1,0,1]
	v_pk_fma_f32 v[6:7], v[18:19], s[24:25], v[32:33] op_sel_hi:[1,0,1]
	v_pk_fma_f32 v[4:5], v[20:21], s[10:11], v[4:5] op_sel_hi:[1,0,1]
	v_pk_fma_f32 v[2:3], v[18:19], s[10:11], v[2:3] op_sel_hi:[1,0,1]
	s_cbranch_scc1 .LBB0_21
	global_load_dword v26, v[24:25], off offset:768 nt
	s_or_b32 s0, s62, 0xc0
	v_add_u32_e32 v18, s0, v58
	v_readlane_b32 s4, v245, 29
	v_add_u32_e32 v20, s0, v59
	v_ashrrev_i32_e32 v19, 31, v18
	v_readlane_b32 s6, v245, 31
	v_readlane_b32 s7, v245, 32
	v_ashrrev_i32_e32 v21, 31, v20
	v_add_u32_e32 v24, s0, v60
	v_lshl_add_u64 v[18:19], v[18:19], 2, s[6:7]
	v_lshl_add_u64 v[20:21], v[20:21], 2, s[6:7]
	v_ashrrev_i32_e32 v25, 31, v24
	v_lshl_add_u64 v[24:25], v[24:25], 2, s[6:7]
	global_load_dword v18, v[18:19], off nt
	s_nop 0
	global_load_dword v19, v[20:21], off nt
	s_nop 0
	global_load_dword v20, v[24:25], off nt
	v_lshl_add_u64 v[22:23], s[94:95], 0, v[22:23]
	s_mov_b32 s63, 0
	v_readlane_b32 s96, v245, 26
	v_readlane_b32 s5, v245, 30
	v_readlane_b32 s8, v245, 33
	v_readlane_b32 s9, v245, 34
	v_readlane_b32 s10, v245, 35
	v_readlane_b32 s11, v245, 36
	v_readlane_b32 s12, v245, 37
	v_readlane_b32 s13, v245, 38
	v_readlane_b32 s14, v245, 39
	v_readlane_b32 s15, v245, 40
	v_readlane_b32 s16, v245, 41
	v_readlane_b32 s17, v245, 42
	v_readlane_b32 s18, v245, 43
	v_readlane_b32 s19, v245, 44
	s_waitcnt vmcnt(3)
	v_mul_f32_e32 v21, 0xbfb8aa3b, v26
	v_rndne_f32_e32 v24, v21
	v_fma_f32 v25, v26, s41, -v21
	v_sub_f32_e32 v21, v21, v24
	v_fmac_f32_e32 v25, 0xb2a5705f, v26
	v_add_f32_e32 v21, v21, v25
	v_cvt_i32_f32_e32 v24, v24
	v_exp_f32_e32 v21, v21
	v_cmp_nlt_f32_e32 vcc, s43, v26
	v_ldexp_f32 v21, v21, v24
	s_waitcnt vmcnt(2)
	v_mul_f32_e32 v25, 0xbfb8aa3b, v18
	s_waitcnt vmcnt(1)
	v_mul_f32_e32 v27, 0xbfb8aa3b, v19
	v_fma_f32 v29, v18, s41, -v25
	v_rndne_f32_e32 v30, v25
	s_waitcnt vmcnt(0)
	v_mul_f32_e32 v28, 0xbfb8aa3b, v20
	v_fma_f32 v31, v19, s41, -v27
	v_rndne_f32_e32 v32, v27
	v_fmac_f32_e32 v29, 0xb2a5705f, v18
	v_sub_f32_e32 v25, v25, v30
	v_fma_f32 v33, v20, s41, -v28
	v_rndne_f32_e32 v34, v28
	v_fmac_f32_e32 v31, 0xb2a5705f, v19
	v_sub_f32_e32 v27, v27, v32
	v_add_f32_e32 v25, v25, v29
	v_cvt_i32_f32_e32 v30, v30
	v_fmac_f32_e32 v33, 0xb2a5705f, v20
	v_sub_f32_e32 v28, v28, v34
	v_add_f32_e32 v27, v27, v31
	v_exp_f32_e32 v24, v25
	v_cndmask_b32_e32 v21, 0, v21, vcc
	v_cmp_ngt_f32_e32 vcc, s45, v26
	v_cvt_i32_f32_e32 v32, v32
	v_add_f32_e32 v28, v28, v33
	v_exp_f32_e32 v25, v27
	v_cndmask_b32_e32 v21, v61, v21, vcc
	v_cvt_i32_f32_e32 v34, v34
	v_exp_f32_e32 v27, v28
	v_add_f32_e32 v21, 1.0, v21
	v_div_scale_f32 v28, s[0:1], v21, v21, v26
	v_ldexp_f32 v24, v24, v30
	v_cmp_nlt_f32_e64 s[0:1], s43, v18
	v_ldexp_f32 v25, v25, v32
	v_ldexp_f32 v27, v27, v34
	v_cndmask_b32_e64 v24, 0, v24, s[0:1]
	v_cmp_nlt_f32_e64 s[0:1], s43, v19
	v_rcp_f32_e32 v30, v28
	v_div_scale_f32 v29, vcc, v26, v21, v26
	v_cndmask_b32_e64 v25, 0, v25, s[0:1]
	v_cmp_nlt_f32_e64 s[0:1], s43, v20
	v_fma_f32 v35, -v28, v30, 1.0
	v_fmac_f32_e32 v30, v35, v30
	v_cndmask_b32_e64 v27, 0, v27, s[0:1]
	v_cmp_ngt_f32_e64 s[0:1], s45, v18
	v_mul_f32_e32 v35, v29, v30
	v_fma_f32 v38, -v28, v35, v29
	v_cndmask_b32_e64 v24, v61, v24, s[0:1]
	v_cmp_ngt_f32_e64 s[0:1], s45, v19
	v_add_f32_e32 v24, 1.0, v24
	v_fmac_f32_e32 v35, v38, v30
	v_cndmask_b32_e64 v25, v61, v25, s[0:1]
	v_cmp_ngt_f32_e64 s[0:1], s45, v20
	v_add_f32_e32 v25, 1.0, v25
	v_div_scale_f32 v33, s[2:3], v25, v25, v19
	v_cndmask_b32_e64 v27, v61, v27, s[0:1]
	v_div_scale_f32 v31, s[0:1], v24, v24, v18
	v_rcp_f32_e32 v36, v31
	v_div_scale_f32 v32, s[0:1], v18, v24, v18
	v_rcp_f32_e32 v37, v33
	v_fma_f32 v38, -v31, v36, 1.0
	v_fma_f32 v28, -v28, v35, v29
	v_fmac_f32_e32 v36, v38, v36
	v_div_fmas_f32 v28, v28, v30, v35
	v_mul_f32_e32 v29, v32, v36
	v_div_fixup_f32 v54, v28, v21, v26
	v_fma_f32 v21, -v31, v29, v32
	v_fmac_f32_e32 v29, v21, v36
	v_fma_f32 v39, -v33, v37, 1.0
	v_fma_f32 v21, -v31, v29, v32
	s_mov_b64 vcc, s[0:1]
	v_add_f32_e32 v27, 1.0, v27
	v_div_scale_f32 v34, s[2:3], v19, v25, v19
	v_fmac_f32_e32 v37, v39, v37
	v_div_fmas_f32 v21, v21, v36, v29
	v_mul_f32_e32 v30, v34, v37
	v_div_fixup_f32 v55, v21, v24, v18
	v_div_scale_f32 v18, s[0:1], v27, v27, v20
	v_fma_f32 v26, -v33, v30, v34
	v_rcp_f32_e32 v21, v18
	v_fmac_f32_e32 v30, v26, v37
	v_fma_f32 v26, -v33, v30, v34
	s_mov_b64 vcc, s[2:3]
	v_div_fmas_f32 v24, v26, v37, v30
	v_div_fixup_f32 v56, v24, v25, v19
	v_fma_f32 v19, -v18, v21, 1.0
	v_fmac_f32_e32 v21, v19, v21
	v_div_scale_f32 v19, vcc, v20, v27, v20
	v_mul_f32_e32 v24, v19, v21
	v_fma_f32 v25, -v18, v24, v19
	v_fmac_f32_e32 v24, v25, v21
	v_fma_f32 v18, -v18, v24, v19
	v_div_fmas_f32 v18, v18, v21, v24
	v_div_fixup_f32 v57, v18, v27, v20
; __device__ __forceinline__ float rdlane(float v, int l) { return __int_as_float(__builtin_amdgcn_readlane(__float_as_int(v), l)); }
; __device__ __forceinline__ void p0_prologue(Frame& F) {
;     ...
;                 const float* wp = F.w_ada + (size_t)kbase * NADA + col;
; #pragma unroll 16
;                 for (int kk = 0; kk < 64; ++kk) { const f32x4 w = *(const f32x4*)(wp + (size_t)kk * NADA);
;                     a0 += w * rdlane(s0, kk); a1 += w * rdlane(s1, kk); a2 += w * rdlane(s2, kk); a3 += w * rdlane(s3, kk); }
.LBB0_23:
	v_add_co_u32_e32 v50, vcc, 0xffe98000, v22
	v_add_co_u32_e64 v52, s[2:3], s67, v22
	s_nop 0
	v_addc_co_u32_e32 v51, vcc, -1, v23, vcc
	global_load_dwordx4 v[64:67], v[50:51], off nt
	v_readlane_b32 s66, v54, s63
	v_readlane_b32 s64, v55, s63
	v_readlane_b32 s62, v56, s63
	v_readlane_b32 s34, v57, s63
	s_add_i32 s36, s63, 1
	s_add_i32 s38, s63, 2
	s_add_i32 s42, s63, 3
	s_add_i32 s52, s63, 4
	s_add_i32 s56, s63, 5
	s_add_i32 s85, s63, 6
	s_add_i32 s87, s63, 7
	s_add_i32 s88, s63, 8
	s_add_i32 s90, s63, 9
	s_add_i32 s89, s63, 10
	s_add_i32 s86, s63, 11
	s_add_i32 s84, s63, 12
	s_add_i32 s83, s63, 13
	s_add_i32 s82, s63, 14
	s_add_i32 s81, s63, 15
	s_add_i32 s63, s63, 16
	v_addc_co_u32_e64 v53, s[0:1], -1, v23, s[2:3]
	v_add_co_u32_e64 v48, s[4:5], s69, v22
	v_add_co_u32_e64 v26, s[16:17], s49, v22
	v_add_co_u32_e64 v28, s[18:19], s51, v22
	v_add_co_u32_e64 v32, s[20:21], s53, v22
	v_add_co_u32_e64 v36, s[22:23], s55, v22
	v_addc_co_u32_e64 v49, s[0:1], -1, v23, s[4:5]
	v_addc_co_u32_e64 v27, s[0:1], -1, v23, s[16:17]
	v_addc_co_u32_e64 v29, s[0:1], -1, v23, s[18:19]
	v_addc_co_u32_e64 v33, s[0:1], -1, v23, s[20:21]
	v_addc_co_u32_e64 v37, s[0:1], -1, v23, s[22:23]
	v_readlane_b32 s16, v54, s36
	v_readlane_b32 s18, v55, s36
	v_readlane_b32 s20, v56, s36
	v_readlane_b32 s22, v57, s36
	v_add_co_u32_e64 v44, s[6:7], s71, v22
	v_add_co_u32_e64 v42, s[26:27], s59, v22
	v_add_co_u32_e64 v46, s[28:29], s65, v22
	v_addc_co_u32_e64 v45, s[0:1], -1, v23, s[6:7]
	v_addc_co_u32_e64 v43, s[0:1], -1, v23, s[26:27]
	v_addc_co_u32_e64 v47, s[0:1], -1, v23, s[28:29]
	v_readlane_b32 s26, v54, s38
	v_readlane_b32 s28, v55, s38
	v_readlane_b32 s54, v56, s38
	v_readlane_b32 s48, v57, s38
	v_add_co_u32_e64 v40, s[8:9], s73, v22
	v_readlane_b32 s36, v54, s42
	s_nop 0
	v_addc_co_u32_e64 v41, s[0:1], -1, v23, s[8:9]
	v_readlane_b32 s38, v55, s42
	v_readlane_b32 s40, v56, s42
	v_readlane_b32 s42, v57, s42
	v_add_co_u32_e64 v34, s[10:11], s75, v22
	v_readlane_b32 s44, v54, s52
	s_nop 0
	v_addc_co_u32_e64 v35, s[0:1], -1, v23, s[10:11]
	v_readlane_b32 s46, v55, s52
	v_readlane_b32 s50, v56, s52
	v_readlane_b32 s58, v57, s52
	v_add_co_u32_e64 v30, s[12:13], s77, v22
	s_waitcnt vmcnt(0)
	v_pk_fma_f32 v[14:15], v[64:65], s[66:67], v[14:15] op_sel_hi:[1,0,1]
	v_pk_fma_f32 v[10:11], v[64:65], s[64:65], v[10:11] op_sel_hi:[1,0,1]
	v_pk_fma_f32 v[6:7], v[64:65], s[62:63], v[6:7] op_sel_hi:[1,0,1]
	v_pk_fma_f32 v[50:51], v[66:67], s[34:35], v[4:5] op_sel_hi:[1,0,1]
	v_pk_fma_f32 v[64:65], v[64:65], s[34:35], v[2:3] op_sel_hi:[1,0,1]
	global_load_dwordx4 v[2:5], v[52:53], off nt
	v_pk_fma_f32 v[16:17], v[66:67], s[66:67], v[16:17] op_sel_hi:[1,0,1]
	v_pk_fma_f32 v[12:13], v[66:67], s[64:65], v[12:13] op_sel_hi:[1,0,1]
	v_pk_fma_f32 v[8:9], v[66:67], s[62:63], v[8:9] op_sel_hi:[1,0,1]
	v_addc_co_u32_e64 v31, s[0:1], -1, v23, s[12:13]
	v_readlane_b32 s78, v54, s56
	v_readlane_b32 s76, v55, s56
	v_readlane_b32 s72, v56, s56
	v_readlane_b32 s68, v57, s56
	global_load_dwordx4 v[18:21], v[22:23], off nt
	v_add_co_u32_e64 v24, s[14:15], s47, v22
	v_add_co_u32_e64 v38, s[24:25], s57, v22
	s_nop 0
	v_addc_co_u32_e64 v25, s[0:1], -1, v23, s[14:15]
	v_addc_co_u32_e64 v39, s[0:1], -1, v23, s[24:25]
	v_readlane_b32 s70, v54, s85
	v_readlane_b32 s74, v55, s85
	v_readlane_b32 s52, v56, s85
	v_readlane_b32 s24, v57, s85
	v_readlane_b32 s10, v54, s87
	v_readlane_b32 s0, v55, s87
	v_readlane_b32 s2, v56, s87
	v_readlane_b32 s4, v57, s87
	v_readlane_b32 s6, v54, s88
	v_readlane_b32 s8, v55, s88
	v_readlane_b32 s14, v56, s88
	v_readlane_b32 s12, v57, s88
	v_readlane_b32 s34, v57, s89
	v_readlane_b32 s56, v54, s86
	v_readlane_b32 s62, v56, s83
	v_readlane_b32 s64, v57, s83
	v_readlane_b32 s66, v54, s82
	s_cmp_lg_u32 s63, 64
	s_waitcnt vmcnt(1)
	v_pk_fma_f32 v[16:17], v[4:5], s[16:17], v[16:17] op_sel_hi:[1,0,1]
	v_pk_fma_f32 v[14:15], v[2:3], s[16:17], v[14:15] op_sel_hi:[1,0,1]
	v_pk_fma_f32 v[12:13], v[4:5], s[18:19], v[12:13] op_sel_hi:[1,0,1]
	v_pk_fma_f32 v[10:11], v[2:3], s[18:19], v[10:11] op_sel_hi:[1,0,1]
	v_pk_fma_f32 v[8:9], v[4:5], s[20:21], v[8:9] op_sel_hi:[1,0,1]
	v_pk_fma_f32 v[6:7], v[2:3], s[20:21], v[6:7] op_sel_hi:[1,0,1]
	v_pk_fma_f32 v[50:51], v[4:5], s[22:23], v[50:51] op_sel_hi:[1,0,1]
	v_pk_fma_f32 v[52:53], v[2:3], s[22:23], v[64:65] op_sel_hi:[1,0,1]
	global_load_dwordx4 v[2:5], v[48:49], off nt
	v_readlane_b32 s16, v54, s90
	v_readlane_b32 s18, v55, s90
	v_readlane_b32 s20, v56, s90
	v_readlane_b32 s22, v57, s90
	s_waitcnt vmcnt(0)
	v_pk_fma_f32 v[16:17], v[4:5], s[26:27], v[16:17] op_sel_hi:[1,0,1]
	v_pk_fma_f32 v[14:15], v[2:3], s[26:27], v[14:15] op_sel_hi:[1,0,1]
	v_pk_fma_f32 v[12:13], v[4:5], s[28:29], v[12:13] op_sel_hi:[1,0,1]
	v_pk_fma_f32 v[10:11], v[2:3], s[28:29], v[10:11] op_sel_hi:[1,0,1]
	v_pk_fma_f32 v[8:9], v[4:5], s[54:55], v[8:9] op_sel_hi:[1,0,1]
	v_pk_fma_f32 v[6:7], v[2:3], s[54:55], v[6:7] op_sel_hi:[1,0,1]
	v_pk_fma_f32 v[48:49], v[4:5], s[48:49], v[50:51] op_sel_hi:[1,0,1]
	v_pk_fma_f32 v[50:51], v[2:3], s[48:49], v[52:53] op_sel_hi:[1,0,1]
	global_load_dwordx4 v[2:5], v[44:45], off nt
	v_readlane_b32 s26, v54, s89
	v_readlane_b32 s28, v55, s89
	v_readlane_b32 s54, v56, s89
	v_readlane_b32 s48, v56, s84
	s_waitcnt vmcnt(0)
	v_pk_fma_f32 v[16:17], v[4:5], s[36:37], v[16:17] op_sel_hi:[1,0,1]
	v_pk_fma_f32 v[14:15], v[2:3], s[36:37], v[14:15] op_sel_hi:[1,0,1]
	v_pk_fma_f32 v[12:13], v[4:5], s[38:39], v[12:13] op_sel_hi:[1,0,1]
	v_pk_fma_f32 v[10:11], v[2:3], s[38:39], v[10:11] op_sel_hi:[1,0,1]
	v_pk_fma_f32 v[8:9], v[4:5], s[40:41], v[8:9] op_sel_hi:[1,0,1]
	v_pk_fma_f32 v[6:7], v[2:3], s[40:41], v[6:7] op_sel_hi:[1,0,1]
	v_pk_fma_f32 v[44:45], v[4:5], s[42:43], v[48:49] op_sel_hi:[1,0,1]
	v_pk_fma_f32 v[48:49], v[2:3], s[42:43], v[50:51] op_sel_hi:[1,0,1]
	global_load_dwordx4 v[2:5], v[40:41], off nt
	v_readlane_b32 s36, v55, s86
	v_readlane_b32 s38, v56, s86
	v_readlane_b32 s40, v57, s86
	v_readlane_b32 s42, v54, s84
	s_waitcnt vmcnt(0)
; __device__ __forceinline__ float rdlane(float v, int l) { return __int_as_float(__builtin_amdgcn_readlane(__float_as_int(v), l)); }
; __device__ __forceinline__ void p0_prologue(Frame& F) {
;     ...
;                 const float* wp = F.w_ada + (size_t)kbase * NADA + col;
; #pragma unroll 16
;                 for (int kk = 0; kk < 64; ++kk) { const f32x4 w = *(const f32x4*)(wp + (size_t)kk * NADA);
;                     a0 += w * rdlane(s0, kk); a1 += w * rdlane(s1, kk); a2 += w * rdlane(s2, kk); a3 += w * rdlane(s3, kk); }
	v_pk_fma_f32 v[16:17], v[4:5], s[44:45], v[16:17] op_sel_hi:[1,0,1]
	v_pk_fma_f32 v[14:15], v[2:3], s[44:45], v[14:15] op_sel_hi:[1,0,1]
	v_pk_fma_f32 v[12:13], v[4:5], s[46:47], v[12:13] op_sel_hi:[1,0,1]
	v_pk_fma_f32 v[10:11], v[2:3], s[46:47], v[10:11] op_sel_hi:[1,0,1]
	v_pk_fma_f32 v[8:9], v[4:5], s[50:51], v[8:9] op_sel_hi:[1,0,1]
	v_pk_fma_f32 v[6:7], v[2:3], s[50:51], v[6:7] op_sel_hi:[1,0,1]
	v_pk_fma_f32 v[40:41], v[4:5], s[58:59], v[44:45] op_sel_hi:[1,0,1]
	v_pk_fma_f32 v[44:45], v[2:3], s[58:59], v[48:49] op_sel_hi:[1,0,1]
	global_load_dwordx4 v[2:5], v[34:35], off nt
	v_readlane_b32 s44, v55, s84
	v_readlane_b32 s46, v57, s84
	v_readlane_b32 s50, v54, s83
	v_readlane_b32 s58, v55, s83
	s_waitcnt vmcnt(0)
	v_pk_fma_f32 v[16:17], v[4:5], s[78:79], v[16:17] op_sel_hi:[1,0,1]
	v_pk_fma_f32 v[14:15], v[2:3], s[78:79], v[14:15] op_sel_hi:[1,0,1]
	v_pk_fma_f32 v[12:13], v[4:5], s[76:77], v[12:13] op_sel_hi:[1,0,1]
	v_pk_fma_f32 v[10:11], v[2:3], s[76:77], v[10:11] op_sel_hi:[1,0,1]
	v_pk_fma_f32 v[48:49], v[4:5], s[72:73], v[8:9] op_sel_hi:[1,0,1]
	v_pk_fma_f32 v[50:51], v[2:3], s[72:73], v[6:7] op_sel_hi:[1,0,1]
	v_pk_fma_f32 v[52:53], v[4:5], s[68:69], v[40:41] op_sel_hi:[1,0,1]
	v_pk_fma_f32 v[44:45], v[2:3], s[68:69], v[44:45] op_sel_hi:[1,0,1]
	global_load_dwordx4 v[2:5], v[30:31], off nt
	v_readlane_b32 s68, v55, s82
	v_readlane_b32 s72, v56, s82
	v_lshl_add_u64 v[22:23], v[22:23], 0, s[60:61]
	s_waitcnt vmcnt(0)
	v_pk_fma_f32 v[64:65], v[4:5], s[70:71], v[16:17] op_sel_hi:[1,0,1]
	v_pk_fma_f32 v[66:67], v[2:3], s[70:71], v[14:15] op_sel_hi:[1,0,1]
	v_pk_fma_f32 v[68:69], v[4:5], s[74:75], v[12:13] op_sel_hi:[1,0,1]
	v_pk_fma_f32 v[70:71], v[2:3], s[74:75], v[10:11] op_sel_hi:[1,0,1]
	global_load_dwordx4 v[6:9], v[24:25], off nt
	global_load_dwordx4 v[10:13], v[26:27], off nt
	global_load_dwordx4 v[14:17], v[28:29], off nt
	s_nop 0
	global_load_dwordx4 v[24:27], v[32:33], off nt
	global_load_dwordx4 v[28:31], v[36:37], off nt
	s_nop 0
	global_load_dwordx4 v[32:35], v[38:39], off nt
	s_nop 0
	global_load_dwordx4 v[36:39], v[42:43], off nt
	s_nop 0
	global_load_dwordx4 v[40:43], v[46:47], off nt
	v_pk_fma_f32 v[46:47], v[4:5], s[52:53], v[48:49] op_sel_hi:[1,0,1]
	v_pk_fma_f32 v[48:49], v[2:3], s[52:53], v[50:51] op_sel_hi:[1,0,1]
	v_pk_fma_f32 v[4:5], v[4:5], s[24:25], v[52:53] op_sel_hi:[1,0,1]
	v_pk_fma_f32 v[2:3], v[2:3], s[24:25], v[44:45] op_sel_hi:[1,0,1]
	v_readlane_b32 s70, v57, s82
	v_readlane_b32 s74, v54, s81
	v_readlane_b32 s52, v55, s81
	v_readlane_b32 s24, v56, s81
	s_waitcnt vmcnt(7)
	v_pk_fma_f32 v[44:45], v[8:9], s[10:11], v[64:65] op_sel_hi:[1,0,1]
	v_pk_fma_f32 v[50:51], v[6:7], s[10:11], v[66:67] op_sel_hi:[1,0,1]
	v_pk_fma_f32 v[52:53], v[8:9], s[0:1], v[68:69] op_sel_hi:[1,0,1]
	v_pk_fma_f32 v[64:65], v[6:7], s[0:1], v[70:71] op_sel_hi:[1,0,1]
	v_pk_fma_f32 v[46:47], v[8:9], s[2:3], v[46:47] op_sel_hi:[1,0,1]
	v_pk_fma_f32 v[48:49], v[6:7], s[2:3], v[48:49] op_sel_hi:[1,0,1]
	v_pk_fma_f32 v[4:5], v[8:9], s[4:5], v[4:5] op_sel_hi:[1,0,1]
	v_pk_fma_f32 v[2:3], v[6:7], s[4:5], v[2:3] op_sel_hi:[1,0,1]
	s_waitcnt vmcnt(6)
	v_pk_fma_f32 v[6:7], v[12:13], s[6:7], v[44:45] op_sel_hi:[1,0,1]
	v_pk_fma_f32 v[8:9], v[10:11], s[6:7], v[50:51] op_sel_hi:[1,0,1]
	v_pk_fma_f32 v[44:45], v[12:13], s[8:9], v[52:53] op_sel_hi:[1,0,1]
	v_pk_fma_f32 v[50:51], v[10:11], s[8:9], v[64:65] op_sel_hi:[1,0,1]
	v_pk_fma_f32 v[46:47], v[12:13], s[14:15], v[46:47] op_sel_hi:[1,0,1]
	v_pk_fma_f32 v[48:49], v[10:11], s[14:15], v[48:49] op_sel_hi:[1,0,1]
	v_pk_fma_f32 v[4:5], v[12:13], s[12:13], v[4:5] op_sel_hi:[1,0,1]
	v_pk_fma_f32 v[2:3], v[10:11], s[12:13], v[2:3] op_sel_hi:[1,0,1]
	s_waitcnt vmcnt(5)
	v_pk_fma_f32 v[6:7], v[16:17], s[16:17], v[6:7] op_sel_hi:[1,0,1]
	v_pk_fma_f32 v[8:9], v[14:15], s[16:17], v[8:9] op_sel_hi:[1,0,1]
	v_pk_fma_f32 v[10:11], v[16:17], s[18:19], v[44:45] op_sel_hi:[1,0,1]
	v_pk_fma_f32 v[12:13], v[14:15], s[18:19], v[50:51] op_sel_hi:[1,0,1]
	v_pk_fma_f32 v[44:45], v[16:17], s[20:21], v[46:47] op_sel_hi:[1,0,1]
	v_pk_fma_f32 v[46:47], v[14:15], s[20:21], v[48:49] op_sel_hi:[1,0,1]
	v_pk_fma_f32 v[4:5], v[16:17], s[22:23], v[4:5] op_sel_hi:[1,0,1]
	v_pk_fma_f32 v[2:3], v[14:15], s[22:23], v[2:3] op_sel_hi:[1,0,1]
	s_waitcnt vmcnt(4)
; __device__ __forceinline__ float rdlane(float v, int l) { return __int_as_float(__builtin_amdgcn_readlane(__float_as_int(v), l)); }
; __device__ __forceinline__ void p0_prologue(Frame& F) {
;     ...
;                 const float* wp = F.w_ada + (size_t)kbase * NADA + col;
; #pragma unroll 16
;                 for (int kk = 0; kk < 64; ++kk) { const f32x4 w = *(const f32x4*)(wp + (size_t)kk * NADA);
;                     a0 += w * rdlane(s0, kk); a1 += w * rdlane(s1, kk); a2 += w * rdlane(s2, kk); a3 += w * rdlane(s3, kk); }
;             }
;             *(f32x4*)(modp + ((size_t)(kc * 4 + 0)) * NADA + col) = a0; *(f32x4*)(modp + ((size_t)(kc * 4 + 1)) * NADA + col) = a1;
;             *(f32x4*)(modp + ((size_t)(kc * 4 + 2)) * NADA + col) = a2; *(f32x4*)(modp + ((size_t)(kc * 4 + 3)) * NADA + col) = a3;
;         }
	v_pk_fma_f32 v[6:7], v[26:27], s[26:27], v[6:7] op_sel_hi:[1,0,1]
	v_pk_fma_f32 v[8:9], v[24:25], s[26:27], v[8:9] op_sel_hi:[1,0,1]
	v_pk_fma_f32 v[10:11], v[26:27], s[28:29], v[10:11] op_sel_hi:[1,0,1]
	v_pk_fma_f32 v[12:13], v[24:25], s[28:29], v[12:13] op_sel_hi:[1,0,1]
	v_pk_fma_f32 v[14:15], v[26:27], s[54:55], v[44:45] op_sel_hi:[1,0,1]
	v_pk_fma_f32 v[16:17], v[24:25], s[54:55], v[46:47] op_sel_hi:[1,0,1]
	v_pk_fma_f32 v[4:5], v[26:27], s[34:35], v[4:5] op_sel_hi:[1,0,1]
	v_pk_fma_f32 v[2:3], v[24:25], s[34:35], v[2:3] op_sel_hi:[1,0,1]
	s_waitcnt vmcnt(3)
	v_pk_fma_f32 v[6:7], v[30:31], s[56:57], v[6:7] op_sel_hi:[1,0,1]
	v_pk_fma_f32 v[8:9], v[28:29], s[56:57], v[8:9] op_sel_hi:[1,0,1]
	v_pk_fma_f32 v[10:11], v[30:31], s[36:37], v[10:11] op_sel_hi:[1,0,1]
	v_pk_fma_f32 v[12:13], v[28:29], s[36:37], v[12:13] op_sel_hi:[1,0,1]
	v_pk_fma_f32 v[14:15], v[30:31], s[38:39], v[14:15] op_sel_hi:[1,0,1]
	v_pk_fma_f32 v[16:17], v[28:29], s[38:39], v[16:17] op_sel_hi:[1,0,1]
	v_pk_fma_f32 v[4:5], v[30:31], s[40:41], v[4:5] op_sel_hi:[1,0,1]
	v_pk_fma_f32 v[2:3], v[28:29], s[40:41], v[2:3] op_sel_hi:[1,0,1]
	s_waitcnt vmcnt(2)
	v_pk_fma_f32 v[6:7], v[34:35], s[42:43], v[6:7] op_sel_hi:[1,0,1]
	v_pk_fma_f32 v[8:9], v[32:33], s[42:43], v[8:9] op_sel_hi:[1,0,1]
	v_pk_fma_f32 v[10:11], v[34:35], s[44:45], v[10:11] op_sel_hi:[1,0,1]
	v_pk_fma_f32 v[12:13], v[32:33], s[44:45], v[12:13] op_sel_hi:[1,0,1]
	v_pk_fma_f32 v[14:15], v[34:35], s[48:49], v[14:15] op_sel_hi:[1,0,1]
	v_pk_fma_f32 v[16:17], v[32:33], s[48:49], v[16:17] op_sel_hi:[1,0,1]
	v_pk_fma_f32 v[4:5], v[34:35], s[46:47], v[4:5] op_sel_hi:[1,0,1]
	v_pk_fma_f32 v[2:3], v[32:33], s[46:47], v[2:3] op_sel_hi:[1,0,1]
	s_waitcnt vmcnt(1)
	v_pk_fma_f32 v[6:7], v[38:39], s[50:51], v[6:7] op_sel_hi:[1,0,1]
	v_pk_fma_f32 v[8:9], v[36:37], s[50:51], v[8:9] op_sel_hi:[1,0,1]
	v_pk_fma_f32 v[10:11], v[38:39], s[58:59], v[10:11] op_sel_hi:[1,0,1]
	v_pk_fma_f32 v[12:13], v[36:37], s[58:59], v[12:13] op_sel_hi:[1,0,1]
	v_pk_fma_f32 v[14:15], v[38:39], s[62:63], v[14:15] op_sel_hi:[1,0,1]
	v_pk_fma_f32 v[16:17], v[36:37], s[62:63], v[16:17] op_sel_hi:[1,0,1]
	v_pk_fma_f32 v[4:5], v[38:39], s[64:65], v[4:5] op_sel_hi:[1,0,1]
	v_pk_fma_f32 v[2:3], v[36:37], s[64:65], v[2:3] op_sel_hi:[1,0,1]
	v_readlane_b32 s10, v57, s81
	s_waitcnt vmcnt(0)
	v_pk_fma_f32 v[6:7], v[42:43], s[66:67], v[6:7] op_sel_hi:[1,0,1]
	v_pk_fma_f32 v[8:9], v[40:41], s[66:67], v[8:9] op_sel_hi:[1,0,1]
	v_pk_fma_f32 v[10:11], v[42:43], s[68:69], v[10:11] op_sel_hi:[1,0,1]
	v_pk_fma_f32 v[24:25], v[40:41], s[68:69], v[12:13] op_sel_hi:[1,0,1]
	v_pk_fma_f32 v[26:27], v[42:43], s[72:73], v[14:15] op_sel_hi:[1,0,1]
	v_pk_fma_f32 v[28:29], v[40:41], s[72:73], v[16:17] op_sel_hi:[1,0,1]
	v_pk_fma_f32 v[4:5], v[42:43], s[70:71], v[4:5] op_sel_hi:[1,0,1]
	v_pk_fma_f32 v[2:3], v[40:41], s[70:71], v[2:3] op_sel_hi:[1,0,1]
	v_pk_fma_f32 v[16:17], v[20:21], s[74:75], v[6:7] op_sel_hi:[1,0,1]
	v_pk_fma_f32 v[14:15], v[18:19], s[74:75], v[8:9] op_sel_hi:[1,0,1]
	v_pk_fma_f32 v[12:13], v[20:21], s[52:53], v[10:11] op_sel_hi:[1,0,1]
	v_pk_fma_f32 v[10:11], v[18:19], s[52:53], v[24:25] op_sel_hi:[1,0,1]
	v_pk_fma_f32 v[8:9], v[20:21], s[24:25], v[26:27] op_sel_hi:[1,0,1]
	v_pk_fma_f32 v[6:7], v[18:19], s[24:25], v[28:29] op_sel_hi:[1,0,1]
	v_pk_fma_f32 v[4:5], v[20:21], s[10:11], v[4:5] op_sel_hi:[1,0,1]
	v_pk_fma_f32 v[2:3], v[18:19], s[10:11], v[2:3] op_sel_hi:[1,0,1]
	s_cbranch_scc1 .LBB0_23
	s_mul_i32 s0, s80, 0x60
	s_sub_i32 s0, s79, s0
	v_lshl_or_b32 v18, s0, 8, v1
	s_lshl_b32 s2, s80, 2
	s_mul_i32 s80, s80, 0x60000
	v_ashrrev_i32_e32 v19, 31, v18
	s_mul_hi_i32 s1, s2, 0x18000
	s_add_u32 s0, s33, s80
	s_addc_u32 s1, s39, s1
	v_lshlrev_b64 v[18:19], 2, v[18:19]
	v_lshl_add_u64 v[20:21], s[0:1], 0, v[18:19]
	s_or_b32 s0, s2, 1
	s_mul_hi_i32 s1, s0, 0x18000
	s_mul_i32 s0, s0, 0x18000
	s_add_u32 s0, s33, s0
	s_addc_u32 s1, s39, s1
	global_store_dwordx4 v[20:21], v[14:17], off
	s_nop 1
	v_lshl_add_u64 v[14:15], s[0:1], 0, v[18:19]
	s_or_b32 s0, s2, 2
	s_mul_hi_i32 s1, s0, 0x18000
	s_mul_i32 s0, s0, 0x18000
	s_add_u32 s0, s33, s0
	s_addc_u32 s1, s39, s1
	global_store_dwordx4 v[14:15], v[10:13], off
	s_nop 1
	v_lshl_add_u64 v[10:11], s[0:1], 0, v[18:19]
	s_or_b32 s0, s2, 3
	s_mul_hi_i32 s1, s0, 0x18000
	s_mul_i32 s0, s0, 0x18000
	s_add_u32 s0, s33, s0
	s_addc_u32 s1, s39, s1
	s_add_i32 s79, s79, s37
	global_store_dwordx4 v[10:11], v[6:9], off
	s_cmpk_gt_i32 s79, 0x5ff
	s_nop 0
	v_lshl_add_u64 v[6:7], s[0:1], 0, v[18:19]
	global_store_dwordx4 v[6:7], v[2:5], off
	s_cbranch_scc0 .LBB0_16

; template <bool F8 = false, class Map>
; __device__ __forceinline__ void transpose_item(const float* __restrict__ W, int Nsrc, int K, void* WTv, const float* kscale, float mul, LAS float* scr, int kb, int nb, int lane, const Map map) {
;     const int k0 = 64 * kb, j0 = 32 * nb, sc = map(j0 + (lane & 31)), kh = lane >> 5;
;     float v[32];
; #pragma unroll
;     for (int i = 0; i < 32; ++i) v[i] = sc >= 0 ? W[(size_t)(k0 + 2 * i + kh) * Nsrc + sc] : 0.f;
; __device__ __forceinline__ void p0_prologue(Frame& F) {
;     ...
;         for (int it = gw; it < NITEMS; it += NGW) {
;             int r = it;
;             if (r < I_F1) { int kb, nb; blk16(r, 64, kb, nb); transpose_item(F.w_ff1, DFF, D, (bf16_t*)(ws + WS_WFF1T), nullptr, 1.f, scr, kb, nb, lane, MapId{}); continue; } r -= I_F1;
;             if (r < I_F2) { int kb, nb; blk16(r, 256, kb, nb); transpose_item(F.w_ff2, D, DFF, (bf16_t*)(ws + WS_WFF2T), nullptr, 1.f, scr, kb, nb, lane, MapId{}); continue; } r -= I_F2;
;             if (r < I_IN) { int kb, nb; blk8(r, 64, kb, nb); transpose_item<FP8_IN>(F.w_in, 7280, D, (void*)(ws + WS_WINT), nullptr, FP8_IN ? 64.f : 1.f, scr, kb, nb, lane, MapWin{}); continue; } r -= I_IN;
;             if (r < I_OUT) { int kb, nb; blk16(r, 64, kb, nb); transpose_item<FP8_OUT>(F.w_out, D, D, (void*)(ws + WS_WOUTT), nullptr, FP8_OUT ? 64.f : 1.f, scr, kb, nb, lane, MapId{}); continue; } r -= I_OUT;
;             if (r < I_UQ) { transpose_item<FP8_UP>(F.w_uq, 3072, QR, (void*)(ws + WS_WUQT), F.qn, FP8_UP ? 32.f : 1.f, scr, r / 96, r % 96, lane, MapUq{}); continue; } r -= I_UQ;
;             if (r < I_UKV) { transpose_item<FP8_UP>(F.w_ukv, 4096, KVR, (void*)(ws + WS_WUKVT), F.kvn, FP8_UP ? 16.f : 1.f, scr, r / 128, r % 128, lane, MapUkv{}); continue; } r -= I_UKV;
;             if (r < I_C1) { transpose_item(F.k1, 256, 4096, (bf16_t*)(ws + WS_K1T), nullptr, 1.f, scr, r / 8, r % 8, lane, MapId{}); continue; } r -= I_C1;
;             if (r < I_C1) { transpose_item(F.v1, 256, 4096, (bf16_t*)(ws + WS_V1T), nullptr, 1.f, scr, r / 8, r % 8, lane, MapId{}); continue; } r -= I_C1;
;             if (r < I_C2) { transpose_item(F.k2, 128, 256, (bf16_t*)(ws + WS_SMALL + 65536), nullptr, 1.f, scr, r / 8, r % 8, lane, MapPad{128}); continue; } r -= I_C2;
;             transpose_item(F.v2, 128, 256, (bf16_t*)(ws + WS_SMALL + 196608), nullptr, 1.f, scr, r / 8, r % 8, lane, MapPad{128});
.LBB0_29:
	s_cmpk_gt_i32 s58, 0x7fff
	s_mov_b64 s[4:5], -1
	s_cbranch_scc0 .LBB0_285
	s_cmpk_gt_u32 s58, 0xffff
	s_cbranch_scc0 .LBB0_282
	s_cmp_gt_u32 s58, 0x139ff
	s_cbranch_scc0 .LBB0_199
	s_cmp_gt_u32 s58, 0x159ff
	s_cbranch_scc0 .LBB0_196
	s_cmp_gt_u32 s58, 0x162ff
	s_cbranch_scc0 .LBB0_185
	s_cmp_gt_u32 s58, 0x166ff
	s_cbranch_scc0 .LBB0_176
	s_cmp_gt_u32 s58, 0x168ff
	s_cbranch_scc0 .LBB0_173
	s_cmp_gt_u32 s58, 0x16aff
	s_cbranch_scc0 .LBB0_170
	s_cmp_gt_u32 s58, 0x16b1f
	s_cbranch_scc0 .LBB0_103
	s_and_b32 s0, s17, 0x7fffffc0
	s_add_i32 s0, s0, 0xfff4a700
	v_or_b32_e32 v38, s0, v3
	v_mov_b32_e32 v40, 0
	v_mov_b32_e32 v4, 0
	s_and_saveexec_b64 s[4:5], s[2:3]
	s_cbranch_execz .LBB0_40
	v_ashrrev_i32_e32 v39, 31, v38
	v_lshlrev_b64 v[42:43], 9, v[38:39]
	v_lshl_add_u64 v[42:43], v[34:35], 0, v[42:43]
	global_load_dword v4, v[42:43], off nt
.LBB0_40:
	s_or_b64 exec, exec, s[4:5]
	s_and_saveexec_b64 s[4:5], s[2:3]
	s_cbranch_execz .LBB0_42
	v_or_b32_e32 v40, 2, v38
	v_ashrrev_i32_e32 v41, 31, v40
	v_lshlrev_b64 v[40:41], 9, v[40:41]
	v_lshl_add_u64 v[40:41], v[34:35], 0, v[40:41]
	global_load_dword v40, v[40:41], off nt
.LBB0_42:
	s_or_b64 exec, exec, s[4:5]
	v_mov_b32_e32 v39, 0
	v_mov_b32_e32 v41, 0
	s_and_saveexec_b64 s[4:5], s[2:3]
	s_cbranch_execz .LBB0_44
	v_or_b32_e32 v42, 4, v38
	v_ashrrev_i32_e32 v43, 31, v42
	v_lshlrev_b64 v[42:43], 9, v[42:43]
	v_lshl_add_u64 v[42:43], v[34:35], 0, v[42:43]
	global_load_dword v41, v[42:43], off nt
.LBB0_44:
	s_or_b64 exec, exec, s[4:5]
	s_and_saveexec_b64 s[4:5], s[2:3]
	s_cbranch_execz .LBB0_46
	v_or_b32_e32 v42, 6, v38
	v_ashrrev_i32_e32 v43, 31, v42
	v_lshlrev_b64 v[42:43], 9, v[42:43]
	v_lshl_add_u64 v[42:43], v[34:35], 0, v[42:43]
	global_load_dword v39, v[42:43], off nt
.LBB0_46:
	s_or_b64 exec, exec, s[4:5]
	v_mov_b32_e32 v42, 0
	v_mov_b32_e32 v43, 0
	s_and_saveexec_b64 s[4:5], s[2:3]
	s_cbranch_execz .LBB0_48
	v_or_b32_e32 v44, 8, v38
	v_ashrrev_i32_e32 v45, 31, v44
	v_lshlrev_b64 v[44:45], 9, v[44:45]
	v_lshl_add_u64 v[44:45], v[34:35], 0, v[44:45]
	global_load_dword v43, v[44:45], off nt
.LBB0_48:
	s_or_b64 exec, exec, s[4:5]
	s_and_saveexec_b64 s[4:5], s[2:3]
	s_cbranch_execz .LBB0_50
	v_or_b32_e32 v44, 10, v38
	v_ashrrev_i32_e32 v45, 31, v44
	v_lshlrev_b64 v[44:45], 9, v[44:45]
	v_lshl_add_u64 v[44:45], v[34:35], 0, v[44:45]
	global_load_dword v42, v[44:45], off nt
.LBB0_50:
	s_or_b64 exec, exec, s[4:5]
	v_mov_b32_e32 v44, 0
	v_mov_b32_e32 v45, 0
	s_and_saveexec_b64 s[4:5], s[2:3]
	s_cbranch_execz .LBB0_52
	v_or_b32_e32 v46, 12, v38
	v_ashrrev_i32_e32 v47, 31, v46
	v_lshlrev_b64 v[46:47], 9, v[46:47]
	v_lshl_add_u64 v[46:47], v[34:35], 0, v[46:47]
	global_load_dword v45, v[46:47], off nt
.LBB0_52:
	s_or_b64 exec, exec, s[4:5]
	s_and_saveexec_b64 s[4:5], s[2:3]
	s_cbranch_execz .LBB0_54
	v_or_b32_e32 v46, 14, v38
	v_ashrrev_i32_e32 v47, 31, v46
	v_lshlrev_b64 v[46:47], 9, v[46:47]
	v_lshl_add_u64 v[46:47], v[34:35], 0, v[46:47]
	global_load_dword v44, v[46:47], off nt
.LBB0_54:
	s_or_b64 exec, exec, s[4:5]
	v_mov_b32_e32 v46, 0
	v_mov_b32_e32 v47, 0
	s_and_saveexec_b64 s[4:5], s[2:3]
	s_cbranch_execz .LBB0_56
	v_or_b32_e32 v48, 16, v38
	v_ashrrev_i32_e32 v49, 31, v48
	v_lshlrev_b64 v[48:49], 9, v[48:49]
	v_lshl_add_u64 v[48:49], v[34:35], 0, v[48:49]
	global_load_dword v47, v[48:49], off nt
.LBB0_56:
	s_or_b64 exec, exec, s[4:5]
	s_and_saveexec_b64 s[4:5], s[2:3]
	s_cbranch_execz .LBB0_58
	v_or_b32_e32 v48, 18, v38
	v_ashrrev_i32_e32 v49, 31, v48
	v_lshlrev_b64 v[48:49], 9, v[48:49]
	v_lshl_add_u64 v[48:49], v[34:35], 0, v[48:49]
	global_load_dword v46, v[48:49], off nt
.LBB0_58:
	s_or_b64 exec, exec, s[4:5]
	v_mov_b32_e32 v48, 0
	v_mov_b32_e32 v49, 0
	s_and_saveexec_b64 s[4:5], s[2:3]
	s_cbranch_execz .LBB0_60
	v_or_b32_e32 v50, 20, v38
	v_ashrrev_i32_e32 v51, 31, v50
	v_lshlrev_b64 v[50:51], 9, v[50:51]
	v_lshl_add_u64 v[50:51], v[34:35], 0, v[50:51]
	global_load_dword v49, v[50:51], off nt
.LBB0_60:
	s_or_b64 exec, exec, s[4:5]
	s_and_saveexec_b64 s[4:5], s[2:3]
	s_cbranch_execz .LBB0_62
	v_or_b32_e32 v50, 22, v38
	v_ashrrev_i32_e32 v51, 31, v50
	v_lshlrev_b64 v[50:51], 9, v[50:51]
	v_lshl_add_u64 v[50:51], v[34:35], 0, v[50:51]
	global_load_dword v48, v[50:51], off nt
.LBB0_62:
	s_or_b64 exec, exec, s[4:5]
	v_mov_b32_e32 v50, 0
	v_mov_b32_e32 v51, 0
	s_and_saveexec_b64 s[4:5], s[2:3]
	s_cbranch_execz .LBB0_64
	v_or_b32_e32 v52, 24, v38
	v_ashrrev_i32_e32 v53, 31, v52
	v_lshlrev_b64 v[52:53], 9, v[52:53]
	v_lshl_add_u64 v[52:53], v[34:35], 0, v[52:53]
	global_load_dword v51, v[52:53], off nt
.LBB0_64:
	s_or_b64 exec, exec, s[4:5]
	s_and_saveexec_b64 s[4:5], s[2:3]
	s_cbranch_execz .LBB0_66
	v_or_b32_e32 v52, 26, v38
	v_ashrrev_i32_e32 v53, 31, v52
	v_lshlrev_b64 v[52:53], 9, v[52:53]
	v_lshl_add_u64 v[52:53], v[34:35], 0, v[52:53]
	global_load_dword v50, v[52:53], off nt
.LBB0_66:
	s_or_b64 exec, exec, s[4:5]
	v_mov_b32_e32 v52, 0
	v_mov_b32_e32 v53, 0
	s_and_saveexec_b64 s[4:5], s[2:3]
	s_cbranch_execz .LBB0_68
	v_or_b32_e32 v54, 28, v38
	v_ashrrev_i32_e32 v55, 31, v54
	v_lshlrev_b64 v[54:55], 9, v[54:55]
	v_lshl_add_u64 v[54:55], v[34:35], 0, v[54:55]
	global_load_dword v53, v[54:55], off nt
; #define LAS __attribute__((address_space(3)))
; template <bool F8 = false, class Map>
; __device__ __forceinline__ void transpose_item(const float* __restrict__ W, int Nsrc, int K, void* WTv, const float* kscale, float mul, LAS float* scr, int kb, int nb, int lane, const Map map) {
;     const int k0 = 64 * kb, j0 = 32 * nb, sc = map(j0 + (lane & 31)), kh = lane >> 5;
;     float v[32];
; #pragma unroll
;     for (int i = 0; i < 32; ++i) v[i] = sc >= 0 ? W[(size_t)(k0 + 2 * i + kh) * Nsrc + sc] : 0.f;
.LBB0_68:
	s_or_b64 exec, exec, s[4:5]
	s_and_saveexec_b64 s[4:5], s[2:3]
	s_cbranch_execz .LBB0_70
	v_or_b32_e32 v54, 30, v38
	v_ashrrev_i32_e32 v55, 31, v54
	v_lshlrev_b64 v[54:55], 9, v[54:55]
	v_lshl_add_u64 v[54:55], v[34:35], 0, v[54:55]
	global_load_dword v52, v[54:55], off nt
.LBB0_70:
	s_or_b64 exec, exec, s[4:5]
	v_mov_b32_e32 v54, 0
	v_mov_b32_e32 v55, 0
	s_and_saveexec_b64 s[4:5], s[2:3]
	s_cbranch_execz .LBB0_72
	v_or_b32_e32 v56, 32, v38
	v_ashrrev_i32_e32 v57, 31, v56
	v_lshlrev_b64 v[56:57], 9, v[56:57]
	v_lshl_add_u64 v[56:57], v[34:35], 0, v[56:57]
	global_load_dword v55, v[56:57], off nt
.LBB0_72:
	s_or_b64 exec, exec, s[4:5]
	s_and_saveexec_b64 s[4:5], s[2:3]
	s_cbranch_execz .LBB0_74
	v_or_b32_e32 v56, 34, v38
	v_ashrrev_i32_e32 v57, 31, v56
	v_lshlrev_b64 v[56:57], 9, v[56:57]
	v_lshl_add_u64 v[56:57], v[34:35], 0, v[56:57]
	global_load_dword v54, v[56:57], off nt
.LBB0_74:
	s_or_b64 exec, exec, s[4:5]
	v_mov_b32_e32 v56, 0
	v_mov_b32_e32 v57, 0
	s_and_saveexec_b64 s[4:5], s[2:3]
	s_cbranch_execz .LBB0_76
	v_or_b32_e32 v58, 36, v38
	v_ashrrev_i32_e32 v59, 31, v58
	v_lshlrev_b64 v[58:59], 9, v[58:59]
	v_lshl_add_u64 v[58:59], v[34:35], 0, v[58:59]
	global_load_dword v57, v[58:59], off nt
.LBB0_76:
	s_or_b64 exec, exec, s[4:5]
	s_and_saveexec_b64 s[4:5], s[2:3]
	s_cbranch_execz .LBB0_78
	v_or_b32_e32 v58, 38, v38
	v_ashrrev_i32_e32 v59, 31, v58
	v_lshlrev_b64 v[58:59], 9, v[58:59]
	v_lshl_add_u64 v[58:59], v[34:35], 0, v[58:59]
	global_load_dword v56, v[58:59], off nt
.LBB0_78:
	s_or_b64 exec, exec, s[4:5]
	v_mov_b32_e32 v58, 0
	v_mov_b32_e32 v59, 0
	s_and_saveexec_b64 s[4:5], s[2:3]
	s_cbranch_execz .LBB0_80
	v_or_b32_e32 v60, 40, v38
	v_ashrrev_i32_e32 v61, 31, v60
	v_lshlrev_b64 v[60:61], 9, v[60:61]
	v_lshl_add_u64 v[60:61], v[34:35], 0, v[60:61]
	global_load_dword v59, v[60:61], off nt
.LBB0_80:
	s_or_b64 exec, exec, s[4:5]
	s_and_saveexec_b64 s[4:5], s[2:3]
	s_cbranch_execz .LBB0_82
	v_or_b32_e32 v60, 42, v38
	v_ashrrev_i32_e32 v61, 31, v60
	v_lshlrev_b64 v[60:61], 9, v[60:61]
	v_lshl_add_u64 v[60:61], v[34:35], 0, v[60:61]
	global_load_dword v58, v[60:61], off nt
.LBB0_82:
	s_or_b64 exec, exec, s[4:5]
	v_mov_b32_e32 v60, 0
	v_mov_b32_e32 v61, 0
	s_and_saveexec_b64 s[4:5], s[2:3]
	s_cbranch_execz .LBB0_84
	v_or_b32_e32 v62, 44, v38
	v_ashrrev_i32_e32 v63, 31, v62
	v_lshlrev_b64 v[62:63], 9, v[62:63]
	v_lshl_add_u64 v[62:63], v[34:35], 0, v[62:63]
	global_load_dword v61, v[62:63], off nt
.LBB0_84:
	s_or_b64 exec, exec, s[4:5]
	s_and_saveexec_b64 s[4:5], s[2:3]
	s_cbranch_execz .LBB0_86
	v_or_b32_e32 v62, 46, v38
	v_ashrrev_i32_e32 v63, 31, v62
	v_lshlrev_b64 v[62:63], 9, v[62:63]
	v_lshl_add_u64 v[62:63], v[34:35], 0, v[62:63]
	global_load_dword v60, v[62:63], off nt
.LBB0_86:
	s_or_b64 exec, exec, s[4:5]
	v_mov_b32_e32 v62, 0
	v_mov_b32_e32 v63, 0
	s_and_saveexec_b64 s[4:5], s[2:3]
	s_cbranch_execz .LBB0_88
	v_or_b32_e32 v64, 48, v38
	v_ashrrev_i32_e32 v65, 31, v64
	v_lshlrev_b64 v[64:65], 9, v[64:65]
	v_lshl_add_u64 v[64:65], v[34:35], 0, v[64:65]
	global_load_dword v63, v[64:65], off nt
.LBB0_88:
	s_or_b64 exec, exec, s[4:5]
	s_and_saveexec_b64 s[4:5], s[2:3]
	s_cbranch_execz .LBB0_90
	v_or_b32_e32 v64, 50, v38
	v_ashrrev_i32_e32 v65, 31, v64
	v_lshlrev_b64 v[64:65], 9, v[64:65]
	v_lshl_add_u64 v[64:65], v[34:35], 0, v[64:65]
	global_load_dword v62, v[64:65], off nt
.LBB0_90:
	s_or_b64 exec, exec, s[4:5]
	v_mov_b32_e32 v64, 0
	v_mov_b32_e32 v65, 0
	s_and_saveexec_b64 s[4:5], s[2:3]
	s_cbranch_execz .LBB0_92
	v_or_b32_e32 v66, 52, v38
	v_ashrrev_i32_e32 v67, 31, v66
	v_lshlrev_b64 v[66:67], 9, v[66:67]
	v_lshl_add_u64 v[66:67], v[34:35], 0, v[66:67]
	global_load_dword v65, v[66:67], off nt
.LBB0_92:
	s_or_b64 exec, exec, s[4:5]
	s_and_saveexec_b64 s[4:5], s[2:3]
	s_cbranch_execz .LBB0_94
	v_or_b32_e32 v66, 54, v38
	v_ashrrev_i32_e32 v67, 31, v66
	v_lshlrev_b64 v[66:67], 9, v[66:67]
	v_lshl_add_u64 v[66:67], v[34:35], 0, v[66:67]
	global_load_dword v64, v[66:67], off nt
.LBB0_94:
	s_or_b64 exec, exec, s[4:5]
	v_mov_b32_e32 v66, 0
	v_mov_b32_e32 v67, 0
	s_and_saveexec_b64 s[4:5], s[2:3]
	s_cbranch_execz .LBB0_96
	v_or_b32_e32 v68, 56, v38
	v_ashrrev_i32_e32 v69, 31, v68
	v_lshlrev_b64 v[68:69], 9, v[68:69]
	v_lshl_add_u64 v[68:69], v[34:35], 0, v[68:69]
	global_load_dword v67, v[68:69], off nt
.LBB0_96:
	s_or_b64 exec, exec, s[4:5]
	s_and_saveexec_b64 s[4:5], s[2:3]
	s_cbranch_execz .LBB0_98
	v_or_b32_e32 v68, 58, v38
	v_ashrrev_i32_e32 v69, 31, v68
	v_lshlrev_b64 v[68:69], 9, v[68:69]
	v_lshl_add_u64 v[68:69], v[34:35], 0, v[68:69]
	global_load_dword v66, v[68:69], off nt
.LBB0_98:
	s_or_b64 exec, exec, s[4:5]
	v_mov_b32_e32 v68, 0
	v_mov_b32_e32 v69, 0
	s_and_saveexec_b64 s[4:5], s[2:3]
	s_cbranch_execz .LBB0_100
	v_or_b32_e32 v84, 60, v38
	v_ashrrev_i32_e32 v85, 31, v84
	v_lshlrev_b64 v[84:85], 9, v[84:85]
	v_lshl_add_u64 v[84:85], v[34:35], 0, v[84:85]
	global_load_dword v69, v[84:85], off nt
.LBB0_100:
	s_or_b64 exec, exec, s[4:5]
	s_and_saveexec_b64 s[4:5], s[2:3]
	s_cbranch_execz .LBB0_102
	v_or_b32_e32 v84, 62, v38
	v_ashrrev_i32_e32 v85, 31, v84
	v_lshlrev_b64 v[84:85], 9, v[84:85]
	v_lshl_add_u64 v[84:85], v[34:35], 0, v[84:85]
	global_load_dword v68, v[84:85], off nt

; #define LAS __attribute__((address_space(3)))
; template <bool F8 = false, class Map>
; __device__ __forceinline__ void transpose_item(const float* __restrict__ W, int Nsrc, int K, void* WTv, const float* kscale, float mul, LAS float* scr, int kb, int nb, int lane, const Map map) {
;     const int k0 = 64 * kb, j0 = 32 * nb, sc = map(j0 + (lane & 31)), kh = lane >> 5;
;     float v[32];
; #pragma unroll
;     for (int i = 0; i < 32; ++i) v[i] = sc >= 0 ? W[(size_t)(k0 + 2 * i + kh) * Nsrc + sc] : 0.f;
; __device__ __forceinline__ void p0_prologue(Frame& F) {
;     ...
;             if (r < I_C2) { transpose_item(F.k2, 128, 256, (bf16_t*)(ws + WS_SMALL + 65536), nullptr, 1.f, scr, r / 8, r % 8, lane, MapPad{128}); continue; } r -= I_C2;
.LBB0_103:
	s_and_b64 vcc, exec, s[4:5]
	s_cbranch_vccz .LBB0_169
	s_and_b32 s0, s17, 0xfffc0
	s_add_i32 s0, s0, 0xfff4a800
	v_or_b32_e32 v4, s0, v3
	v_mov_b32_e32 v39, 0
	v_mov_b32_e32 v38, 0
	s_and_saveexec_b64 s[4:5], s[2:3]
	s_cbranch_execz .LBB0_106
	v_lshlrev_b64 v[40:41], 9, v[4:5]
	v_lshl_add_u64 v[40:41], v[36:37], 0, v[40:41]
	global_load_dword v38, v[40:41], off nt
.LBB0_106:
	s_or_b64 exec, exec, s[4:5]
	s_and_saveexec_b64 s[4:5], s[2:3]
	s_cbranch_execz .LBB0_108
	v_or_b32_e32 v40, 2, v4
	v_mov_b32_e32 v41, v5
	v_lshlrev_b64 v[40:41], 9, v[40:41]
	v_lshl_add_u64 v[40:41], v[36:37], 0, v[40:41]
	global_load_dword v39, v[40:41], off nt
.LBB0_108:
	s_or_b64 exec, exec, s[4:5]
	v_mov_b32_e32 v40, 0
	v_mov_b32_e32 v41, 0
	s_and_saveexec_b64 s[4:5], s[2:3]
	s_cbranch_execz .LBB0_110
	v_or_b32_e32 v42, 4, v4
	v_mov_b32_e32 v43, v5
	v_lshlrev_b64 v[42:43], 9, v[42:43]
	v_lshl_add_u64 v[42:43], v[36:37], 0, v[42:43]
	global_load_dword v41, v[42:43], off nt
.LBB0_110:
	s_or_b64 exec, exec, s[4:5]
	s_and_saveexec_b64 s[4:5], s[2:3]
	s_cbranch_execz .LBB0_112
	v_or_b32_e32 v42, 6, v4
	v_mov_b32_e32 v43, v5
	v_lshlrev_b64 v[42:43], 9, v[42:43]
	v_lshl_add_u64 v[42:43], v[36:37], 0, v[42:43]
	global_load_dword v40, v[42:43], off nt
.LBB0_112:
	s_or_b64 exec, exec, s[4:5]
	v_mov_b32_e32 v42, 0
	v_mov_b32_e32 v43, 0
	s_and_saveexec_b64 s[4:5], s[2:3]
	s_cbranch_execz .LBB0_114
	v_or_b32_e32 v44, 8, v4
	v_mov_b32_e32 v45, v5
	v_lshlrev_b64 v[44:45], 9, v[44:45]
	v_lshl_add_u64 v[44:45], v[36:37], 0, v[44:45]
	global_load_dword v43, v[44:45], off nt
.LBB0_114:
	s_or_b64 exec, exec, s[4:5]
	s_and_saveexec_b64 s[4:5], s[2:3]
	s_cbranch_execz .LBB0_116
	v_or_b32_e32 v44, 10, v4
	v_mov_b32_e32 v45, v5
	v_lshlrev_b64 v[44:45], 9, v[44:45]
	v_lshl_add_u64 v[44:45], v[36:37], 0, v[44:45]
	global_load_dword v42, v[44:45], off nt
.LBB0_116:
	s_or_b64 exec, exec, s[4:5]
	v_mov_b32_e32 v44, 0
	v_mov_b32_e32 v45, 0
	s_and_saveexec_b64 s[4:5], s[2:3]
	s_cbranch_execz .LBB0_118
	v_or_b32_e32 v46, 12, v4
	v_mov_b32_e32 v47, v5
	v_lshlrev_b64 v[46:47], 9, v[46:47]
	v_lshl_add_u64 v[46:47], v[36:37], 0, v[46:47]
	global_load_dword v45, v[46:47], off nt
.LBB0_118:
	s_or_b64 exec, exec, s[4:5]
	s_and_saveexec_b64 s[4:5], s[2:3]
	s_cbranch_execz .LBB0_120
	v_or_b32_e32 v46, 14, v4
	v_mov_b32_e32 v47, v5
	v_lshlrev_b64 v[46:47], 9, v[46:47]
	v_lshl_add_u64 v[46:47], v[36:37], 0, v[46:47]
	global_load_dword v44, v[46:47], off nt
.LBB0_120:
	s_or_b64 exec, exec, s[4:5]
	v_mov_b32_e32 v46, 0
	v_mov_b32_e32 v47, 0
	s_and_saveexec_b64 s[4:5], s[2:3]
	s_cbranch_execz .LBB0_122
	v_or_b32_e32 v48, 16, v4
	v_mov_b32_e32 v49, v5
	v_lshlrev_b64 v[48:49], 9, v[48:49]
	v_lshl_add_u64 v[48:49], v[36:37], 0, v[48:49]
	global_load_dword v47, v[48:49], off nt
.LBB0_122:
	s_or_b64 exec, exec, s[4:5]
	s_and_saveexec_b64 s[4:5], s[2:3]
	s_cbranch_execz .LBB0_124
	v_or_b32_e32 v48, 18, v4
	v_mov_b32_e32 v49, v5
	v_lshlrev_b64 v[48:49], 9, v[48:49]
	v_lshl_add_u64 v[48:49], v[36:37], 0, v[48:49]
	global_load_dword v46, v[48:49], off nt
.LBB0_124:
	s_or_b64 exec, exec, s[4:5]
	v_mov_b32_e32 v48, 0
	v_mov_b32_e32 v49, 0
	s_and_saveexec_b64 s[4:5], s[2:3]
	s_cbranch_execz .LBB0_126
	v_or_b32_e32 v50, 20, v4
	v_mov_b32_e32 v51, v5
	v_lshlrev_b64 v[50:51], 9, v[50:51]
	v_lshl_add_u64 v[50:51], v[36:37], 0, v[50:51]
	global_load_dword v49, v[50:51], off nt
.LBB0_126:
	s_or_b64 exec, exec, s[4:5]
	s_and_saveexec_b64 s[4:5], s[2:3]
	s_cbranch_execz .LBB0_128
	v_or_b32_e32 v50, 22, v4
	v_mov_b32_e32 v51, v5
	v_lshlrev_b64 v[50:51], 9, v[50:51]
	v_lshl_add_u64 v[50:51], v[36:37], 0, v[50:51]
	global_load_dword v48, v[50:51], off nt
.LBB0_128:
	s_or_b64 exec, exec, s[4:5]
	v_mov_b32_e32 v50, 0
	v_mov_b32_e32 v51, 0
	s_and_saveexec_b64 s[4:5], s[2:3]
	s_cbranch_execz .LBB0_130
	v_or_b32_e32 v52, 24, v4
	v_mov_b32_e32 v53, v5
	v_lshlrev_b64 v[52:53], 9, v[52:53]
	v_lshl_add_u64 v[52:53], v[36:37], 0, v[52:53]
	global_load_dword v51, v[52:53], off nt
.LBB0_130:
	s_or_b64 exec, exec, s[4:5]
	s_and_saveexec_b64 s[4:5], s[2:3]
	s_cbranch_execz .LBB0_132
	v_or_b32_e32 v52, 26, v4
	v_mov_b32_e32 v53, v5
	v_lshlrev_b64 v[52:53], 9, v[52:53]
	v_lshl_add_u64 v[52:53], v[36:37], 0, v[52:53]
	global_load_dword v50, v[52:53], off nt
.LBB0_132:
	s_or_b64 exec, exec, s[4:5]
	v_mov_b32_e32 v52, 0
	v_mov_b32_e32 v53, 0
	s_and_saveexec_b64 s[4:5], s[2:3]
	s_cbranch_execz .LBB0_134
	v_or_b32_e32 v54, 28, v4
	v_mov_b32_e32 v55, v5
	v_lshlrev_b64 v[54:55], 9, v[54:55]
	v_lshl_add_u64 v[54:55], v[36:37], 0, v[54:55]
	global_load_dword v53, v[54:55], off nt
.LBB0_134:
	s_or_b64 exec, exec, s[4:5]
	s_and_saveexec_b64 s[4:5], s[2:3]
	s_cbranch_execz .LBB0_136
	v_or_b32_e32 v54, 30, v4
	v_mov_b32_e32 v55, v5
	v_lshlrev_b64 v[54:55], 9, v[54:55]
	v_lshl_add_u64 v[54:55], v[36:37], 0, v[54:55]
	global_load_dword v52, v[54:55], off nt
; #define LAS __attribute__((address_space(3)))
; template <bool F8 = false, class Map>
; __device__ __forceinline__ void transpose_item(const float* __restrict__ W, int Nsrc, int K, void* WTv, const float* kscale, float mul, LAS float* scr, int kb, int nb, int lane, const Map map) {
;     const int k0 = 64 * kb, j0 = 32 * nb, sc = map(j0 + (lane & 31)), kh = lane >> 5;
;     float v[32];
; #pragma unroll
;     for (int i = 0; i < 32; ++i) v[i] = sc >= 0 ? W[(size_t)(k0 + 2 * i + kh) * Nsrc + sc] : 0.f;
.LBB0_136:
	s_or_b64 exec, exec, s[4:5]
	v_mov_b32_e32 v54, 0
	v_mov_b32_e32 v55, 0
	s_and_saveexec_b64 s[4:5], s[2:3]
	s_cbranch_execz .LBB0_138
	v_or_b32_e32 v56, 32, v4
	v_mov_b32_e32 v57, v5
	v_lshlrev_b64 v[56:57], 9, v[56:57]
	v_lshl_add_u64 v[56:57], v[36:37], 0, v[56:57]
	global_load_dword v55, v[56:57], off nt
.LBB0_138:
	s_or_b64 exec, exec, s[4:5]
	s_and_saveexec_b64 s[4:5], s[2:3]
	s_cbranch_execz .LBB0_140
	v_or_b32_e32 v56, 34, v4
	v_mov_b32_e32 v57, v5
	v_lshlrev_b64 v[56:57], 9, v[56:57]
	v_lshl_add_u64 v[56:57], v[36:37], 0, v[56:57]
	global_load_dword v54, v[56:57], off nt
.LBB0_140:
	s_or_b64 exec, exec, s[4:5]
	v_mov_b32_e32 v56, 0
	v_mov_b32_e32 v57, 0
	s_and_saveexec_b64 s[4:5], s[2:3]
	s_cbranch_execz .LBB0_142
	v_or_b32_e32 v58, 36, v4
	v_mov_b32_e32 v59, v5
	v_lshlrev_b64 v[58:59], 9, v[58:59]
	v_lshl_add_u64 v[58:59], v[36:37], 0, v[58:59]
	global_load_dword v57, v[58:59], off nt
.LBB0_142:
	s_or_b64 exec, exec, s[4:5]
	s_and_saveexec_b64 s[4:5], s[2:3]
	s_cbranch_execz .LBB0_144
	v_or_b32_e32 v58, 38, v4
	v_mov_b32_e32 v59, v5
	v_lshlrev_b64 v[58:59], 9, v[58:59]
	v_lshl_add_u64 v[58:59], v[36:37], 0, v[58:59]
	global_load_dword v56, v[58:59], off nt
.LBB0_144:
	s_or_b64 exec, exec, s[4:5]
	v_mov_b32_e32 v58, 0
	v_mov_b32_e32 v59, 0
	s_and_saveexec_b64 s[4:5], s[2:3]
	s_cbranch_execz .LBB0_146
	v_or_b32_e32 v60, 40, v4
	v_mov_b32_e32 v61, v5
	v_lshlrev_b64 v[60:61], 9, v[60:61]
	v_lshl_add_u64 v[60:61], v[36:37], 0, v[60:61]
	global_load_dword v59, v[60:61], off nt
.LBB0_146:
	s_or_b64 exec, exec, s[4:5]
	s_and_saveexec_b64 s[4:5], s[2:3]
	s_cbranch_execz .LBB0_148
	v_or_b32_e32 v60, 42, v4
	v_mov_b32_e32 v61, v5
	v_lshlrev_b64 v[60:61], 9, v[60:61]
	v_lshl_add_u64 v[60:61], v[36:37], 0, v[60:61]
	global_load_dword v58, v[60:61], off nt
.LBB0_148:
	s_or_b64 exec, exec, s[4:5]
	v_mov_b32_e32 v60, 0
	v_mov_b32_e32 v61, 0
	s_and_saveexec_b64 s[4:5], s[2:3]
	s_cbranch_execz .LBB0_150
	v_or_b32_e32 v62, 44, v4
	v_mov_b32_e32 v63, v5
	v_lshlrev_b64 v[62:63], 9, v[62:63]
	v_lshl_add_u64 v[62:63], v[36:37], 0, v[62:63]
	global_load_dword v61, v[62:63], off nt
.LBB0_150:
	s_or_b64 exec, exec, s[4:5]
	s_and_saveexec_b64 s[4:5], s[2:3]
	s_cbranch_execz .LBB0_152
	v_or_b32_e32 v62, 46, v4
	v_mov_b32_e32 v63, v5
	v_lshlrev_b64 v[62:63], 9, v[62:63]
	v_lshl_add_u64 v[62:63], v[36:37], 0, v[62:63]
	global_load_dword v60, v[62:63], off nt
.LBB0_152:
	s_or_b64 exec, exec, s[4:5]
	v_mov_b32_e32 v62, 0
	v_mov_b32_e32 v63, 0
	s_and_saveexec_b64 s[4:5], s[2:3]
	s_cbranch_execz .LBB0_154
	v_or_b32_e32 v64, 48, v4
	v_mov_b32_e32 v65, v5
	v_lshlrev_b64 v[64:65], 9, v[64:65]
	v_lshl_add_u64 v[64:65], v[36:37], 0, v[64:65]
	global_load_dword v63, v[64:65], off nt
.LBB0_154:
	s_or_b64 exec, exec, s[4:5]
	s_and_saveexec_b64 s[4:5], s[2:3]
	s_cbranch_execz .LBB0_156
	v_or_b32_e32 v64, 50, v4
	v_mov_b32_e32 v65, v5
	v_lshlrev_b64 v[64:65], 9, v[64:65]
	v_lshl_add_u64 v[64:65], v[36:37], 0, v[64:65]
	global_load_dword v62, v[64:65], off nt
.LBB0_156:
	s_or_b64 exec, exec, s[4:5]
	v_mov_b32_e32 v64, 0
	v_mov_b32_e32 v65, 0
	s_and_saveexec_b64 s[4:5], s[2:3]
	s_cbranch_execz .LBB0_158
	v_or_b32_e32 v66, 52, v4
	v_mov_b32_e32 v67, v5
	v_lshlrev_b64 v[66:67], 9, v[66:67]
	v_lshl_add_u64 v[66:67], v[36:37], 0, v[66:67]
	global_load_dword v65, v[66:67], off nt
.LBB0_158:
	s_or_b64 exec, exec, s[4:5]
	s_and_saveexec_b64 s[4:5], s[2:3]
	s_cbranch_execz .LBB0_160
	v_or_b32_e32 v66, 54, v4
	v_mov_b32_e32 v67, v5
	v_lshlrev_b64 v[66:67], 9, v[66:67]
	v_lshl_add_u64 v[66:67], v[36:37], 0, v[66:67]
	global_load_dword v64, v[66:67], off nt
.LBB0_160:
	s_or_b64 exec, exec, s[4:5]
	v_mov_b32_e32 v66, 0
	v_mov_b32_e32 v67, 0
	s_and_saveexec_b64 s[4:5], s[2:3]
	s_cbranch_execz .LBB0_162
	v_or_b32_e32 v68, 56, v4
	v_mov_b32_e32 v69, v5
	v_lshlrev_b64 v[68:69], 9, v[68:69]
	v_lshl_add_u64 v[68:69], v[36:37], 0, v[68:69]
	global_load_dword v67, v[68:69], off nt
.LBB0_162:
	s_or_b64 exec, exec, s[4:5]
	s_and_saveexec_b64 s[4:5], s[2:3]
	s_cbranch_execz .LBB0_164
	v_or_b32_e32 v68, 58, v4
	v_mov_b32_e32 v69, v5
	v_lshlrev_b64 v[68:69], 9, v[68:69]
	v_lshl_add_u64 v[68:69], v[36:37], 0, v[68:69]
	global_load_dword v66, v[68:69], off nt
.LBB0_164:
	s_or_b64 exec, exec, s[4:5]
	v_mov_b32_e32 v68, 0
	v_mov_b32_e32 v69, 0
	s_and_saveexec_b64 s[4:5], s[2:3]
	s_cbranch_execz .LBB0_166
	v_or_b32_e32 v84, 60, v4
	v_mov_b32_e32 v85, v5
	v_lshlrev_b64 v[84:85], 9, v[84:85]
	v_lshl_add_u64 v[84:85], v[36:37], 0, v[84:85]
	global_load_dword v69, v[84:85], off nt
.LBB0_166:
	s_or_b64 exec, exec, s[4:5]
	s_and_saveexec_b64 s[4:5], s[2:3]
	s_cbranch_execz .LBB0_168
	v_or_b32_e32 v4, 62, v4
	v_lshlrev_b64 v[84:85], 9, v[4:5]
	v_lshl_add_u64 v[84:85], v[36:37], 0, v[84:85]
	global_load_dword v68, v[84:85], off nt

; #define LAS __attribute__((address_space(3)))
; template <bool F8 = false, class Map>
; __device__ __forceinline__ void transpose_item(const float* __restrict__ W, int Nsrc, int K, void* WTv, const float* kscale, float mul, LAS float* scr, int kb, int nb, int lane, const Map map) {
;     const int k0 = 64 * kb, j0 = 32 * nb, sc = map(j0 + (lane & 31)), kh = lane >> 5;
;     float v[32];
; #pragma unroll
;     for (int i = 0; i < 32; ++i) v[i] = sc >= 0 ? W[(size_t)(k0 + 2 * i + kh) * Nsrc + sc] : 0.f;
;     if (kscale) {
; #pragma unroll
;         for (int i = 0; i < 32; ++i) v[i] *= kscale[k0 + 2 * i + kh];
;     }
; #pragma unroll
;     for (int i = 0; i < 32; ++i) scr[(2 * i + kh) * 33 + (lane & 31)] = v[i];
; __device__ __forceinline__ void p0_prologue(Frame& F) {
;     ...
;             if (r < I_C1) { transpose_item(F.v1, 256, 4096, (bf16_t*)(ws + WS_V1T), nullptr, 1.f, scr, r / 8, r % 8, lane, MapId{}); continue; } r -= I_C1;
.LBB0_170:
	s_andn2_b64 vcc, exec, s[4:5]
	s_cbranch_vccnz .LBB0_172
	s_and_b32 s0, s17, 0xfffc0
	s_and_b32 s4, s15, 0xe0
	s_add_i32 s0, s0, 0xfff4b800
	v_or_b32_e32 v4, s4, v1
	v_or_b32_e32 v38, s0, v3
	v_lshlrev_b32_e32 v4, 2, v4
	v_lshl_add_u64 v[40:41], s[80:81], 0, v[4:5]
	v_or_b32_e32 v4, 2, v38
	v_lshlrev_b64 v[44:45], 10, v[4:5]
	v_or_b32_e32 v4, 4, v38
	v_lshlrev_b64 v[46:47], 10, v[4:5]
	v_or_b32_e32 v4, 6, v38
	v_lshlrev_b64 v[48:49], 10, v[4:5]
	v_or_b32_e32 v4, 8, v38
	v_lshlrev_b64 v[50:51], 10, v[4:5]
	v_or_b32_e32 v4, 10, v38
	v_mov_b32_e32 v39, v5
	v_lshlrev_b64 v[52:53], 10, v[4:5]
	v_or_b32_e32 v4, 12, v38
	v_lshlrev_b64 v[42:43], 10, v[38:39]
	v_lshlrev_b64 v[54:55], 10, v[4:5]
	v_or_b32_e32 v4, 14, v38
	v_lshl_add_u64 v[42:43], v[40:41], 0, v[42:43]
	v_lshlrev_b64 v[56:57], 10, v[4:5]
	v_or_b32_e32 v4, 16, v38
	v_lshl_add_u64 v[44:45], v[40:41], 0, v[44:45]
	v_lshl_add_u64 v[46:47], v[40:41], 0, v[46:47]
	v_lshl_add_u64 v[48:49], v[40:41], 0, v[48:49]
	v_lshl_add_u64 v[50:51], v[40:41], 0, v[50:51]
	v_lshl_add_u64 v[52:53], v[40:41], 0, v[52:53]
	v_lshl_add_u64 v[54:55], v[40:41], 0, v[54:55]
	v_lshl_add_u64 v[56:57], v[40:41], 0, v[56:57]
	global_load_dword v58, v[42:43], off nt
	global_load_dword v59, v[44:45], off nt
	global_load_dword v60, v[46:47], off nt
	global_load_dword v61, v[48:49], off nt
	global_load_dword v62, v[50:51], off nt
	global_load_dword v63, v[52:53], off nt
	global_load_dword v64, v[54:55], off nt
	global_load_dword v65, v[56:57], off nt
	v_lshlrev_b64 v[42:43], 10, v[4:5]
	v_or_b32_e32 v4, 18, v38
	v_lshlrev_b64 v[44:45], 10, v[4:5]
	v_or_b32_e32 v4, 20, v38
	v_lshlrev_b64 v[46:47], 10, v[4:5]
	v_or_b32_e32 v4, 22, v38
	v_lshlrev_b64 v[48:49], 10, v[4:5]
	v_or_b32_e32 v4, 24, v38
	v_lshlrev_b64 v[50:51], 10, v[4:5]
	v_or_b32_e32 v4, 26, v38
	v_lshlrev_b64 v[52:53], 10, v[4:5]
	v_or_b32_e32 v4, 28, v38
	v_lshlrev_b64 v[54:55], 10, v[4:5]
	v_or_b32_e32 v4, 30, v38
	v_lshl_add_u64 v[42:43], v[40:41], 0, v[42:43]
	v_lshlrev_b64 v[56:57], 10, v[4:5]
	v_or_b32_e32 v4, 32, v38
	v_lshl_add_u64 v[44:45], v[40:41], 0, v[44:45]
	v_lshl_add_u64 v[46:47], v[40:41], 0, v[46:47]
	v_lshl_add_u64 v[48:49], v[40:41], 0, v[48:49]
	v_lshl_add_u64 v[50:51], v[40:41], 0, v[50:51]
	v_lshl_add_u64 v[52:53], v[40:41], 0, v[52:53]
	v_lshl_add_u64 v[54:55], v[40:41], 0, v[54:55]
	v_lshl_add_u64 v[56:57], v[40:41], 0, v[56:57]
	global_load_dword v66, v[42:43], off nt
	global_load_dword v67, v[44:45], off nt
	global_load_dword v68, v[46:47], off nt
	global_load_dword v69, v[48:49], off nt
	global_load_dword v83, v[50:51], off nt
	global_load_dword v84, v[52:53], off nt
	global_load_dword v85, v[54:55], off nt
	global_load_dword v86, v[56:57], off nt
	v_lshlrev_b64 v[42:43], 10, v[4:5]
	v_or_b32_e32 v4, 34, v38
	v_lshlrev_b64 v[44:45], 10, v[4:5]
	v_or_b32_e32 v4, 36, v38
	v_lshlrev_b64 v[46:47], 10, v[4:5]
	v_or_b32_e32 v4, 38, v38
	v_lshlrev_b64 v[48:49], 10, v[4:5]
	v_or_b32_e32 v4, 40, v38
	v_lshlrev_b64 v[50:51], 10, v[4:5]
	v_or_b32_e32 v4, 42, v38
	v_lshlrev_b64 v[52:53], 10, v[4:5]
	v_or_b32_e32 v4, 44, v38
	v_lshlrev_b64 v[54:55], 10, v[4:5]
	v_or_b32_e32 v4, 46, v38
	v_lshlrev_b64 v[56:57], 10, v[4:5]
	v_lshl_add_u64 v[42:43], v[40:41], 0, v[42:43]
	v_lshl_add_u64 v[56:57], v[40:41], 0, v[56:57]
	v_or_b32_e32 v4, 48, v38
	v_lshl_add_u64 v[44:45], v[40:41], 0, v[44:45]
	v_lshl_add_u64 v[46:47], v[40:41], 0, v[46:47]
	v_lshl_add_u64 v[48:49], v[40:41], 0, v[48:49]
	v_lshl_add_u64 v[50:51], v[40:41], 0, v[50:51]
	v_lshl_add_u64 v[52:53], v[40:41], 0, v[52:53]
	v_lshl_add_u64 v[54:55], v[40:41], 0, v[54:55]
	global_load_dword v87, v[42:43], off nt
	global_load_dword v88, v[44:45], off nt
	global_load_dword v89, v[46:47], off nt
	global_load_dword v90, v[48:49], off nt
	global_load_dword v91, v[50:51], off nt
	global_load_dword v92, v[52:53], off nt
	global_load_dword v93, v[54:55], off nt
	s_nop 0
	global_load_dword v56, v[56:57], off nt
	v_lshlrev_b64 v[42:43], 10, v[4:5]
	v_or_b32_e32 v4, 50, v38
	v_lshlrev_b64 v[44:45], 10, v[4:5]
	v_or_b32_e32 v4, 52, v38
	v_lshlrev_b64 v[46:47], 10, v[4:5]
	v_or_b32_e32 v4, 54, v38
	v_lshlrev_b64 v[48:49], 10, v[4:5]
	v_or_b32_e32 v4, 56, v38
	v_lshlrev_b64 v[50:51], 10, v[4:5]
	v_or_b32_e32 v4, 58, v38
	v_lshlrev_b64 v[52:53], 10, v[4:5]
	v_or_b32_e32 v4, 60, v38
	v_lshlrev_b64 v[54:55], 10, v[4:5]
	v_or_b32_e32 v4, 62, v38
	v_lshlrev_b64 v[38:39], 10, v[4:5]
	v_lshl_add_u64 v[42:43], v[40:41], 0, v[42:43]
	v_lshl_add_u64 v[44:45], v[40:41], 0, v[44:45]
	v_lshl_add_u64 v[38:39], v[40:41], 0, v[38:39]
	v_lshl_add_u64 v[46:47], v[40:41], 0, v[46:47]
	v_lshl_add_u64 v[48:49], v[40:41], 0, v[48:49]
	v_lshl_add_u64 v[50:51], v[40:41], 0, v[50:51]
	v_lshl_add_u64 v[52:53], v[40:41], 0, v[52:53]
	v_lshl_add_u64 v[54:55], v[40:41], 0, v[54:55]
	global_load_dword v4, v[42:43], off nt
	global_load_dword v40, v[44:45], off nt
	global_load_dword v41, v[46:47], off nt
	s_nop 0
	global_load_dword v42, v[48:49], off nt
	global_load_dword v43, v[50:51], off nt
	global_load_dword v44, v[52:53], off nt
	global_load_dword v45, v[54:55], off nt
	s_nop 0
	global_load_dword v38, v[38:39], off nt
	v_add_u32_e32 v39, 0x400, v70
	s_waitcnt vmcnt(30)
; #define LAS __attribute__((address_space(3)))
; __device__ __forceinline__ unsigned cvtpk(float lo, float hi) { f32x2 v = {lo, hi}; bf16x2_t b = __builtin_convertvector(v, bf16x2_t); return __builtin_bit_cast(unsigned, b); }
; template <bool F8 = false, class Map>
; __device__ __forceinline__ void transpose_item(const float* __restrict__ W, int Nsrc, int K, void* WTv, const float* kscale, float mul, LAS float* scr, int kb, int nb, int lane, const Map map) {
;     ...
;     for (int i = 0; i < 32; ++i) scr[(2 * i + kh) * 33 + (lane & 31)] = v[i];
;     asm volatile("s_waitcnt lgkmcnt(0)" ::: "memory");
;     ...
;     } else {
;         bf16_t* WT = (bf16_t*)WTv; const int c = lane & 7;
; #pragma unroll
;         for (int jj = 0; jj < 4; ++jj) { const int n = (lane >> 3) + 8 * jj; const LAS float* s = scr + (8 * c) * 33 + n;
;             u32x4 o; o.x = cvtpk(s[0 * 33], s[1 * 33]); o.y = cvtpk(s[2 * 33], s[3 * 33]); o.z = cvtpk(s[4 * 33], s[5 * 33]); o.w = cvtpk(s[6 * 33], s[7 * 33]);
;             *(u32x4*)(WT + (size_t)(j0 + n) * K + k0 + 8 * c) = o; }
;     }
;     asm volatile("s_waitcnt lgkmcnt(0)" ::: "memory");
	ds_write2_b32 v70, v58, v59 offset1:66
	s_waitcnt vmcnt(28)
	ds_write2_b32 v70, v60, v61 offset0:132 offset1:198
	s_waitcnt vmcnt(26)
	ds_write2_b32 v39, v62, v63 offset0:8 offset1:74
	s_waitcnt vmcnt(24)
	ds_write2_b32 v39, v64, v65 offset0:140 offset1:206
	v_add_u32_e32 v39, 0x800, v70
	s_waitcnt vmcnt(22)
	ds_write2_b32 v39, v66, v67 offset0:16 offset1:82
	s_waitcnt vmcnt(20)
	ds_write2_b32 v39, v68, v69 offset0:148 offset1:214
	v_add_u32_e32 v39, 0xc00, v70
	s_waitcnt vmcnt(18)
	ds_write2_b32 v39, v83, v84 offset0:24 offset1:90
	s_waitcnt vmcnt(16)
	ds_write2_b32 v39, v85, v86 offset0:156 offset1:222
	v_add_u32_e32 v39, 0x1000, v70
	s_waitcnt vmcnt(14)
	ds_write2_b32 v39, v87, v88 offset0:32 offset1:98
	s_waitcnt vmcnt(12)
	ds_write2_b32 v39, v89, v90 offset0:164 offset1:230
	v_add_u32_e32 v39, 0x1400, v70
	s_waitcnt vmcnt(10)
	ds_write2_b32 v39, v91, v92 offset0:40 offset1:106
	s_waitcnt vmcnt(8)
	ds_write2_b32 v39, v93, v56 offset0:172 offset1:238
	v_add_u32_e32 v39, 0x1800, v70
	s_waitcnt vmcnt(6)
	ds_write2_b32 v39, v4, v40 offset0:48 offset1:114
	s_waitcnt vmcnt(4)
	ds_write2_b32 v39, v41, v42 offset0:180 offset1:246
	v_add_u32_e32 v4, 0x1c00, v70
	s_waitcnt vmcnt(2)
	ds_write2_b32 v4, v43, v44 offset0:56 offset1:122
	s_waitcnt vmcnt(0)
	ds_write2_b32 v4, v45, v38 offset0:188 offset1:254
	s_waitcnt lgkmcnt(0)
	ds_read2_b32 v[42:43], v72 offset0:33 offset1:41
	ds_read2_b32 v[44:45], v72 offset1:8
	ds_read2_b32 v[46:47], v72 offset0:66 offset1:74
	ds_read2_b32 v[48:49], v72 offset0:99 offset1:107
	ds_read2_b32 v[50:51], v72 offset0:132 offset1:140
	ds_read2_b32 v[52:53], v72 offset0:165 offset1:173
	ds_read2_b32 v[54:55], v72 offset0:198 offset1:206
	ds_read2_b32 v[56:57], v72 offset0:231 offset1:239
	v_or_b32_e32 v4, s4, v71
	v_lshl_add_u64 v[58:59], s[0:1], 1, v[10:11]
	v_lshlrev_b32_e32 v4, 13, v4
	s_waitcnt lgkmcnt(6)
	v_cvt_pk_bf16_f32 v38, v44, v42
	s_waitcnt lgkmcnt(4)
	v_cvt_pk_bf16_f32 v39, v46, v48
	s_waitcnt lgkmcnt(2)
	v_cvt_pk_bf16_f32 v40, v50, v52
	s_waitcnt lgkmcnt(0)
	v_cvt_pk_bf16_f32 v41, v54, v56
	v_lshl_add_u64 v[60:61], v[58:59], 0, v[4:5]
	global_store_dwordx4 v[60:61], v[38:41], off
	v_or_b32_e32 v4, s4, v73
	v_lshlrev_b32_e32 v4, 13, v4
	v_cvt_pk_bf16_f32 v38, v45, v43
	v_cvt_pk_bf16_f32 v39, v47, v49
	v_cvt_pk_bf16_f32 v40, v51, v53
	v_cvt_pk_bf16_f32 v41, v55, v57
	ds_read2_b32 v[44:45], v72 offset0:49 offset1:57
	ds_read2_b32 v[46:47], v72 offset0:16 offset1:24
	ds_read2_b32 v[48:49], v72 offset0:82 offset1:90
	ds_read2_b32 v[50:51], v72 offset0:115 offset1:123
	ds_read2_b32 v[52:53], v72 offset0:148 offset1:156
	ds_read2_b32 v[54:55], v72 offset0:181 offset1:189
	ds_read2_b32 v[56:57], v72 offset0:214 offset1:222
	ds_read2_b32 v[60:61], v72 offset0:247 offset1:255
	v_lshl_add_u64 v[42:43], v[58:59], 0, v[4:5]
	v_or_b32_e32 v4, s4, v74
	v_lshlrev_b32_e32 v4, 13, v4
	global_store_dwordx4 v[42:43], v[38:41], off
	v_lshl_add_u64 v[42:43], v[58:59], 0, v[4:5]
	v_or_b32_e32 v4, s4, v75
	s_waitcnt lgkmcnt(6)
	v_cvt_pk_bf16_f32 v38, v46, v44
	s_waitcnt lgkmcnt(4)
	v_cvt_pk_bf16_f32 v39, v48, v50
	s_waitcnt lgkmcnt(2)
	v_cvt_pk_bf16_f32 v40, v52, v54
	s_waitcnt lgkmcnt(0)
	v_cvt_pk_bf16_f32 v41, v56, v60
	v_lshlrev_b32_e32 v4, 13, v4
	global_store_dwordx4 v[42:43], v[38:41], off
	v_lshl_add_u64 v[42:43], v[58:59], 0, v[4:5]
	s_nop 0
	v_cvt_pk_bf16_f32 v38, v47, v45
	v_cvt_pk_bf16_f32 v39, v49, v51
	v_cvt_pk_bf16_f32 v40, v53, v55
	v_cvt_pk_bf16_f32 v41, v57, v61
	global_store_dwordx4 v[42:43], v[38:41], off
	s_waitcnt lgkmcnt(0)

; #define LAS __attribute__((address_space(3)))
; template <bool F8 = false, class Map>
; __device__ __forceinline__ void transpose_item(const float* __restrict__ W, int Nsrc, int K, void* WTv, const float* kscale, float mul, LAS float* scr, int kb, int nb, int lane, const Map map) {
;     const int k0 = 64 * kb, j0 = 32 * nb, sc = map(j0 + (lane & 31)), kh = lane >> 5;
;     float v[32];
; #pragma unroll
;     for (int i = 0; i < 32; ++i) v[i] = sc >= 0 ? W[(size_t)(k0 + 2 * i + kh) * Nsrc + sc] : 0.f;
;     if (kscale) {
; #pragma unroll
;         for (int i = 0; i < 32; ++i) v[i] *= kscale[k0 + 2 * i + kh];
;     }
; #pragma unroll
;     for (int i = 0; i < 32; ++i) scr[(2 * i + kh) * 33 + (lane & 31)] = v[i];
; __device__ __forceinline__ void p0_prologue(Frame& F) {
;     ...
;             if (r < I_C1) { transpose_item(F.k1, 256, 4096, (bf16_t*)(ws + WS_K1T), nullptr, 1.f, scr, r / 8, r % 8, lane, MapId{}); continue; } r -= I_C1;
.LBB0_173:
	s_andn2_b64 vcc, exec, s[4:5]
	s_cbranch_vccnz .LBB0_175
	s_and_b32 s0, s17, 0xfffc0
	s_and_b32 s4, s15, 0xe0
	s_add_i32 s0, s0, 0xfff4c800
	v_or_b32_e32 v4, s4, v1
	v_or_b32_e32 v38, s0, v3
	v_lshlrev_b32_e32 v4, 2, v4
	v_lshl_add_u64 v[40:41], s[76:77], 0, v[4:5]
	v_or_b32_e32 v4, 2, v38
	v_lshlrev_b64 v[44:45], 10, v[4:5]
	v_or_b32_e32 v4, 4, v38
	v_lshlrev_b64 v[46:47], 10, v[4:5]
	v_or_b32_e32 v4, 6, v38
	v_lshlrev_b64 v[48:49], 10, v[4:5]
	v_or_b32_e32 v4, 8, v38
	v_lshlrev_b64 v[50:51], 10, v[4:5]
	v_or_b32_e32 v4, 10, v38
	v_mov_b32_e32 v39, v5
	v_lshlrev_b64 v[52:53], 10, v[4:5]
	v_or_b32_e32 v4, 12, v38
	v_lshlrev_b64 v[42:43], 10, v[38:39]
	v_lshlrev_b64 v[54:55], 10, v[4:5]
	v_or_b32_e32 v4, 14, v38
	v_lshl_add_u64 v[42:43], v[40:41], 0, v[42:43]
	v_lshlrev_b64 v[56:57], 10, v[4:5]
	v_or_b32_e32 v4, 16, v38
	v_lshl_add_u64 v[44:45], v[40:41], 0, v[44:45]
	v_lshl_add_u64 v[46:47], v[40:41], 0, v[46:47]
	v_lshl_add_u64 v[48:49], v[40:41], 0, v[48:49]
	v_lshl_add_u64 v[50:51], v[40:41], 0, v[50:51]
	v_lshl_add_u64 v[52:53], v[40:41], 0, v[52:53]
	v_lshl_add_u64 v[54:55], v[40:41], 0, v[54:55]
	v_lshl_add_u64 v[56:57], v[40:41], 0, v[56:57]
	global_load_dword v58, v[42:43], off nt
	global_load_dword v59, v[44:45], off nt
	global_load_dword v60, v[46:47], off nt
	global_load_dword v61, v[48:49], off nt
	global_load_dword v62, v[50:51], off nt
	global_load_dword v63, v[52:53], off nt
	global_load_dword v64, v[54:55], off nt
	global_load_dword v65, v[56:57], off nt
	v_lshlrev_b64 v[42:43], 10, v[4:5]
	v_or_b32_e32 v4, 18, v38
	v_lshlrev_b64 v[44:45], 10, v[4:5]
	v_or_b32_e32 v4, 20, v38
	v_lshlrev_b64 v[46:47], 10, v[4:5]
	v_or_b32_e32 v4, 22, v38
	v_lshlrev_b64 v[48:49], 10, v[4:5]
	v_or_b32_e32 v4, 24, v38
	v_lshlrev_b64 v[50:51], 10, v[4:5]
	v_or_b32_e32 v4, 26, v38
	v_lshlrev_b64 v[52:53], 10, v[4:5]
	v_or_b32_e32 v4, 28, v38
	v_lshlrev_b64 v[54:55], 10, v[4:5]
	v_or_b32_e32 v4, 30, v38
	v_lshl_add_u64 v[42:43], v[40:41], 0, v[42:43]
	v_lshlrev_b64 v[56:57], 10, v[4:5]
	v_or_b32_e32 v4, 32, v38
	v_lshl_add_u64 v[44:45], v[40:41], 0, v[44:45]
	v_lshl_add_u64 v[46:47], v[40:41], 0, v[46:47]
	v_lshl_add_u64 v[48:49], v[40:41], 0, v[48:49]
	v_lshl_add_u64 v[50:51], v[40:41], 0, v[50:51]
	v_lshl_add_u64 v[52:53], v[40:41], 0, v[52:53]
	v_lshl_add_u64 v[54:55], v[40:41], 0, v[54:55]
	v_lshl_add_u64 v[56:57], v[40:41], 0, v[56:57]
	global_load_dword v66, v[42:43], off nt
	global_load_dword v67, v[44:45], off nt
	global_load_dword v68, v[46:47], off nt
	global_load_dword v69, v[48:49], off nt
	global_load_dword v83, v[50:51], off nt
	global_load_dword v84, v[52:53], off nt
	global_load_dword v85, v[54:55], off nt
	global_load_dword v86, v[56:57], off nt
	v_lshlrev_b64 v[42:43], 10, v[4:5]
	v_or_b32_e32 v4, 34, v38
	v_lshlrev_b64 v[44:45], 10, v[4:5]
	v_or_b32_e32 v4, 36, v38
	v_lshlrev_b64 v[46:47], 10, v[4:5]
	v_or_b32_e32 v4, 38, v38
	v_lshlrev_b64 v[48:49], 10, v[4:5]
	v_or_b32_e32 v4, 40, v38
	v_lshlrev_b64 v[50:51], 10, v[4:5]
	v_or_b32_e32 v4, 42, v38
	v_lshlrev_b64 v[52:53], 10, v[4:5]
	v_or_b32_e32 v4, 44, v38
	v_lshlrev_b64 v[54:55], 10, v[4:5]
	v_or_b32_e32 v4, 46, v38
	v_lshlrev_b64 v[56:57], 10, v[4:5]
	v_lshl_add_u64 v[42:43], v[40:41], 0, v[42:43]
	v_lshl_add_u64 v[56:57], v[40:41], 0, v[56:57]
	v_or_b32_e32 v4, 48, v38
	v_lshl_add_u64 v[44:45], v[40:41], 0, v[44:45]
	v_lshl_add_u64 v[46:47], v[40:41], 0, v[46:47]
	v_lshl_add_u64 v[48:49], v[40:41], 0, v[48:49]
	v_lshl_add_u64 v[50:51], v[40:41], 0, v[50:51]
	v_lshl_add_u64 v[52:53], v[40:41], 0, v[52:53]
	v_lshl_add_u64 v[54:55], v[40:41], 0, v[54:55]
	global_load_dword v87, v[42:43], off nt
	global_load_dword v88, v[44:45], off nt
	global_load_dword v89, v[46:47], off nt
	global_load_dword v90, v[48:49], off nt
	global_load_dword v91, v[50:51], off nt
	global_load_dword v92, v[52:53], off nt
	global_load_dword v93, v[54:55], off nt
	s_nop 0
	global_load_dword v56, v[56:57], off nt
	v_lshlrev_b64 v[42:43], 10, v[4:5]
	v_or_b32_e32 v4, 50, v38
	v_lshlrev_b64 v[44:45], 10, v[4:5]
	v_or_b32_e32 v4, 52, v38
	v_lshlrev_b64 v[46:47], 10, v[4:5]
	v_or_b32_e32 v4, 54, v38
	v_lshlrev_b64 v[48:49], 10, v[4:5]
	v_or_b32_e32 v4, 56, v38
	v_lshlrev_b64 v[50:51], 10, v[4:5]
	v_or_b32_e32 v4, 58, v38
	v_lshlrev_b64 v[52:53], 10, v[4:5]
	v_or_b32_e32 v4, 60, v38
	v_lshlrev_b64 v[54:55], 10, v[4:5]
	v_or_b32_e32 v4, 62, v38
	v_lshlrev_b64 v[38:39], 10, v[4:5]
	v_lshl_add_u64 v[42:43], v[40:41], 0, v[42:43]
	v_lshl_add_u64 v[44:45], v[40:41], 0, v[44:45]
	v_lshl_add_u64 v[38:39], v[40:41], 0, v[38:39]
	v_lshl_add_u64 v[46:47], v[40:41], 0, v[46:47]
	v_lshl_add_u64 v[48:49], v[40:41], 0, v[48:49]
	v_lshl_add_u64 v[50:51], v[40:41], 0, v[50:51]
	v_lshl_add_u64 v[52:53], v[40:41], 0, v[52:53]
	v_lshl_add_u64 v[54:55], v[40:41], 0, v[54:55]
	global_load_dword v4, v[42:43], off nt
	global_load_dword v40, v[44:45], off nt
	global_load_dword v41, v[46:47], off nt
	s_nop 0
	global_load_dword v42, v[48:49], off nt
	global_load_dword v43, v[50:51], off nt
	global_load_dword v44, v[52:53], off nt
	global_load_dword v45, v[54:55], off nt
	s_nop 0
	global_load_dword v38, v[38:39], off nt
	v_add_u32_e32 v39, 0x400, v70
	s_waitcnt vmcnt(30)
; #define LAS __attribute__((address_space(3)))
; __device__ __forceinline__ unsigned cvtpk(float lo, float hi) { f32x2 v = {lo, hi}; bf16x2_t b = __builtin_convertvector(v, bf16x2_t); return __builtin_bit_cast(unsigned, b); }
; __device__ __forceinline__ unsigned pack4_fp8(float a, float b, float c, float d) { unsigned w = 0u; w = (unsigned)__builtin_amdgcn_cvt_pk_fp8_f32(a, b, (int)w, false); w = (unsigned)__builtin_amdgcn_cvt_pk_fp8_f32(c, d, (int)w, true); return w; }
; template <bool F8 = false, class Map>
; __device__ __forceinline__ void transpose_item(const float* __restrict__ W, int Nsrc, int K, void* WTv, const float* kscale, float mul, LAS float* scr, int kb, int nb, int lane, const Map map) {
;     ...
;     for (int i = 0; i < 32; ++i) scr[(2 * i + kh) * 33 + (lane & 31)] = v[i];
;     asm volatile("s_waitcnt lgkmcnt(0)" ::: "memory");
;     if constexpr (F8) {
;         unsigned char* WT = (unsigned char*)WTv; const int c = lane & 3;
; #pragma unroll
;         for (int jj = 0; jj < 2; ++jj) { const int n = (lane >> 2) + 16 * jj; const LAS float* s = scr + (16 * c) * 33 + n;
;             u32x4 o; o.x = pack4_fp8(s[0 * 33] * mul, s[1 * 33] * mul, s[2 * 33] * mul, s[3 * 33] * mul); o.y = pack4_fp8(s[4 * 33] * mul, s[5 * 33] * mul, s[6 * 33] * mul, s[7 * 33] * mul);
;             o.z = pack4_fp8(s[8 * 33] * mul, s[9 * 33] * mul, s[10 * 33] * mul, s[11 * 33] * mul); o.w = pack4_fp8(s[12 * 33] * mul, s[13 * 33] * mul, s[14 * 33] * mul, s[15 * 33] * mul);
;             *(u32x4*)(WT + (size_t)(j0 + n) * K + k0 + 16 * c) = o; }
;     } else {
;         bf16_t* WT = (bf16_t*)WTv; const int c = lane & 7;
; #pragma unroll
;         for (int jj = 0; jj < 4; ++jj) { const int n = (lane >> 3) + 8 * jj; const LAS float* s = scr + (8 * c) * 33 + n;
;             u32x4 o; o.x = cvtpk(s[0 * 33], s[1 * 33]); o.y = cvtpk(s[2 * 33], s[3 * 33]); o.z = cvtpk(s[4 * 33], s[5 * 33]); o.w = cvtpk(s[6 * 33], s[7 * 33]);
;             *(u32x4*)(WT + (size_t)(j0 + n) * K + k0 + 8 * c) = o; }
;     }
;     asm volatile("s_waitcnt lgkmcnt(0)" ::: "memory");
	ds_write2_b32 v70, v58, v59 offset1:66
	s_waitcnt vmcnt(28)
	ds_write2_b32 v70, v60, v61 offset0:132 offset1:198
	s_waitcnt vmcnt(26)
	ds_write2_b32 v39, v62, v63 offset0:8 offset1:74
	s_waitcnt vmcnt(24)
	ds_write2_b32 v39, v64, v65 offset0:140 offset1:206
	v_add_u32_e32 v39, 0x800, v70
	s_waitcnt vmcnt(22)
	ds_write2_b32 v39, v66, v67 offset0:16 offset1:82
	s_waitcnt vmcnt(20)
	ds_write2_b32 v39, v68, v69 offset0:148 offset1:214
	v_add_u32_e32 v39, 0xc00, v70
	s_waitcnt vmcnt(18)
	ds_write2_b32 v39, v83, v84 offset0:24 offset1:90
	s_waitcnt vmcnt(16)
	ds_write2_b32 v39, v85, v86 offset0:156 offset1:222
	v_add_u32_e32 v39, 0x1000, v70
	s_waitcnt vmcnt(14)
	ds_write2_b32 v39, v87, v88 offset0:32 offset1:98
	s_waitcnt vmcnt(12)
	ds_write2_b32 v39, v89, v90 offset0:164 offset1:230
	v_add_u32_e32 v39, 0x1400, v70
	s_waitcnt vmcnt(10)
	ds_write2_b32 v39, v91, v92 offset0:40 offset1:106
	s_waitcnt vmcnt(8)
	ds_write2_b32 v39, v93, v56 offset0:172 offset1:238
	v_add_u32_e32 v39, 0x1800, v70
	s_waitcnt vmcnt(6)
	ds_write2_b32 v39, v4, v40 offset0:48 offset1:114
	s_waitcnt vmcnt(4)
	ds_write2_b32 v39, v41, v42 offset0:180 offset1:246
	v_add_u32_e32 v4, 0x1c00, v70
	s_waitcnt vmcnt(2)
	ds_write2_b32 v4, v43, v44 offset0:56 offset1:122
	s_waitcnt vmcnt(0)
	ds_write2_b32 v4, v45, v38 offset0:188 offset1:254
	s_waitcnt lgkmcnt(0)
	ds_read2_b32 v[42:43], v72 offset0:33 offset1:41
	ds_read2_b32 v[44:45], v72 offset1:8
	ds_read2_b32 v[46:47], v72 offset0:66 offset1:74
	ds_read2_b32 v[48:49], v72 offset0:99 offset1:107
	ds_read2_b32 v[50:51], v72 offset0:132 offset1:140
	ds_read2_b32 v[52:53], v72 offset0:165 offset1:173
	ds_read2_b32 v[54:55], v72 offset0:198 offset1:206
	ds_read2_b32 v[56:57], v72 offset0:231 offset1:239
	v_or_b32_e32 v4, s4, v71
	v_lshl_add_u64 v[58:59], s[0:1], 1, v[12:13]
	v_lshlrev_b32_e32 v4, 13, v4
	s_waitcnt lgkmcnt(6)
	v_cvt_pk_bf16_f32 v38, v44, v42
	s_waitcnt lgkmcnt(4)
	v_cvt_pk_bf16_f32 v39, v46, v48
	s_waitcnt lgkmcnt(2)
	v_cvt_pk_bf16_f32 v40, v50, v52
	s_waitcnt lgkmcnt(0)
	v_cvt_pk_bf16_f32 v41, v54, v56
	v_lshl_add_u64 v[60:61], v[58:59], 0, v[4:5]
	global_store_dwordx4 v[60:61], v[38:41], off
	v_or_b32_e32 v4, s4, v73
	v_lshlrev_b32_e32 v4, 13, v4
	v_cvt_pk_bf16_f32 v38, v45, v43
	v_cvt_pk_bf16_f32 v39, v47, v49
	v_cvt_pk_bf16_f32 v40, v51, v53
	v_cvt_pk_bf16_f32 v41, v55, v57
	ds_read2_b32 v[44:45], v72 offset0:49 offset1:57
	ds_read2_b32 v[46:47], v72 offset0:16 offset1:24
	ds_read2_b32 v[48:49], v72 offset0:82 offset1:90
	ds_read2_b32 v[50:51], v72 offset0:115 offset1:123
	ds_read2_b32 v[52:53], v72 offset0:148 offset1:156
	ds_read2_b32 v[54:55], v72 offset0:181 offset1:189
	ds_read2_b32 v[56:57], v72 offset0:214 offset1:222
	ds_read2_b32 v[60:61], v72 offset0:247 offset1:255
	v_lshl_add_u64 v[42:43], v[58:59], 0, v[4:5]
	v_or_b32_e32 v4, s4, v74
	v_lshlrev_b32_e32 v4, 13, v4
	global_store_dwordx4 v[42:43], v[38:41], off
	v_lshl_add_u64 v[42:43], v[58:59], 0, v[4:5]
	v_or_b32_e32 v4, s4, v75
	s_waitcnt lgkmcnt(6)
	v_cvt_pk_bf16_f32 v38, v46, v44
	s_waitcnt lgkmcnt(4)
	v_cvt_pk_bf16_f32 v39, v48, v50
	s_waitcnt lgkmcnt(2)
	v_cvt_pk_bf16_f32 v40, v52, v54
	s_waitcnt lgkmcnt(0)
	v_cvt_pk_bf16_f32 v41, v56, v60
	v_lshlrev_b32_e32 v4, 13, v4
	global_store_dwordx4 v[42:43], v[38:41], off
	v_lshl_add_u64 v[42:43], v[58:59], 0, v[4:5]
	s_nop 0
	v_cvt_pk_bf16_f32 v38, v47, v45
	v_cvt_pk_bf16_f32 v39, v49, v51
	v_cvt_pk_bf16_f32 v40, v53, v55
	v_cvt_pk_bf16_f32 v41, v57, v61
	global_store_dwordx4 v[42:43], v[38:41], off
	s_waitcnt lgkmcnt(0)

; #define LAS __attribute__((address_space(3)))
; template <bool F8 = false, class Map>
; __device__ __forceinline__ void transpose_item(const float* __restrict__ W, int Nsrc, int K, void* WTv, const float* kscale, float mul, LAS float* scr, int kb, int nb, int lane, const Map map) {
;     const int k0 = 64 * kb, j0 = 32 * nb, sc = map(j0 + (lane & 31)), kh = lane >> 5;
;     float v[32];
; #pragma unroll
;     for (int i = 0; i < 32; ++i) v[i] = sc >= 0 ? W[(size_t)(k0 + 2 * i + kh) * Nsrc + sc] : 0.f;
; __device__ __forceinline__ void p0_prologue(Frame& F) {
;     ...
;             if (r < I_UKV) { transpose_item<FP8_UP>(F.w_ukv, 4096, KVR, (void*)(ws + WS_WUKVT), F.kvn, FP8_UP ? 16.f : 1.f, scr, r / 128, r % 128, lane, MapUkv{}); continue; } r -= I_UKV;
.LBB0_181:
	s_add_i32 s0, s58, 0xfffe9d00
	s_lshr_b32 s0, s0, 1
	s_and_b32 s0, s0, 0x7fffffc0
	v_or_b32_e32 v83, s0, v3
	v_lshl_add_u64 v[62:63], v[4:5], 2, s[90:91]
	v_mov_b32_e32 v4, v83
	v_or_b32_e32 v40, 2, v83
	v_mov_b32_e32 v41, v5
	v_or_b32_e32 v42, 4, v83
	v_mov_b32_e32 v43, v5
	v_or_b32_e32 v44, 6, v83
	v_mov_b32_e32 v45, v5
	v_or_b32_e32 v46, 8, v83
	v_mov_b32_e32 v47, v5
	v_or_b32_e32 v48, 10, v83
	v_mov_b32_e32 v49, v5
	v_or_b32_e32 v50, 12, v83
	v_mov_b32_e32 v51, v5
	v_or_b32_e32 v52, 14, v83
	v_mov_b32_e32 v53, v5
	v_lshlrev_b64 v[38:39], 14, v[4:5]
	v_lshlrev_b64 v[40:41], 14, v[40:41]
	v_lshlrev_b64 v[42:43], 14, v[42:43]
	v_lshlrev_b64 v[44:45], 14, v[44:45]
	v_lshlrev_b64 v[46:47], 14, v[46:47]
	v_lshlrev_b64 v[48:49], 14, v[48:49]
	v_lshlrev_b64 v[50:51], 14, v[50:51]
	v_lshlrev_b64 v[52:53], 14, v[52:53]
	v_lshl_add_u64 v[38:39], v[62:63], 0, v[38:39]
	v_lshl_add_u64 v[40:41], v[62:63], 0, v[40:41]
	v_lshl_add_u64 v[42:43], v[62:63], 0, v[42:43]
	v_lshl_add_u64 v[44:45], v[62:63], 0, v[44:45]
	v_lshl_add_u64 v[46:47], v[62:63], 0, v[46:47]
	v_lshl_add_u64 v[48:49], v[62:63], 0, v[48:49]
	v_lshl_add_u64 v[50:51], v[62:63], 0, v[50:51]
	v_lshl_add_u64 v[52:53], v[62:63], 0, v[52:53]
	global_load_dword v38, v[38:39], off nt
	s_nop 0
	global_load_dword v39, v[40:41], off nt
	s_nop 0
	global_load_dword v42, v[42:43], off nt
	s_nop 0
	global_load_dword v43, v[44:45], off nt
	global_load_dword v40, v[46:47], off nt
	global_load_dword v41, v[48:49], off nt
	s_nop 0
	global_load_dword v44, v[50:51], off nt
	global_load_dword v45, v[52:53], off nt
	v_or_b32_e32 v46, 16, v83
	v_mov_b32_e32 v47, v5
	v_or_b32_e32 v48, 18, v83
	v_mov_b32_e32 v49, v5
	v_or_b32_e32 v50, 20, v83
	v_mov_b32_e32 v51, v5
	v_or_b32_e32 v52, 22, v83
	v_mov_b32_e32 v53, v5
	v_or_b32_e32 v54, 24, v83
	v_mov_b32_e32 v55, v5
	v_or_b32_e32 v56, 26, v83
	v_mov_b32_e32 v57, v5
	v_or_b32_e32 v58, 28, v83
	v_mov_b32_e32 v59, v5
	v_or_b32_e32 v60, 30, v83
	v_mov_b32_e32 v61, v5
	v_lshlrev_b64 v[46:47], 14, v[46:47]
	v_lshlrev_b64 v[48:49], 14, v[48:49]
	v_lshlrev_b64 v[50:51], 14, v[50:51]
	v_lshlrev_b64 v[52:53], 14, v[52:53]
	v_lshlrev_b64 v[54:55], 14, v[54:55]
	v_lshlrev_b64 v[56:57], 14, v[56:57]
	v_lshlrev_b64 v[58:59], 14, v[58:59]
	v_lshlrev_b64 v[60:61], 14, v[60:61]
	v_lshl_add_u64 v[46:47], v[62:63], 0, v[46:47]
	v_lshl_add_u64 v[48:49], v[62:63], 0, v[48:49]
	v_lshl_add_u64 v[50:51], v[62:63], 0, v[50:51]
	v_lshl_add_u64 v[52:53], v[62:63], 0, v[52:53]
	v_lshl_add_u64 v[54:55], v[62:63], 0, v[54:55]
	v_lshl_add_u64 v[56:57], v[62:63], 0, v[56:57]
	v_lshl_add_u64 v[58:59], v[62:63], 0, v[58:59]
	v_lshl_add_u64 v[60:61], v[62:63], 0, v[60:61]
	global_load_dword v46, v[46:47], off nt
	s_nop 0
	global_load_dword v47, v[48:49], off nt
	s_nop 0
	global_load_dword v50, v[50:51], off nt
	s_nop 0
	global_load_dword v51, v[52:53], off nt
	global_load_dword v48, v[54:55], off nt
	global_load_dword v49, v[56:57], off nt
	s_nop 0
	global_load_dword v52, v[58:59], off nt
	global_load_dword v53, v[60:61], off nt
	v_or_b32_e32 v54, 32, v83
	v_mov_b32_e32 v55, v5
	v_or_b32_e32 v56, 34, v83
	v_mov_b32_e32 v57, v5
	v_or_b32_e32 v58, 36, v83
	v_mov_b32_e32 v59, v5
	v_or_b32_e32 v60, 38, v83
	v_mov_b32_e32 v61, v5
	v_or_b32_e32 v64, 40, v83
	v_mov_b32_e32 v65, v5
	v_or_b32_e32 v66, 42, v83
	v_mov_b32_e32 v67, v5
	v_or_b32_e32 v68, 44, v83
	v_mov_b32_e32 v69, v5
	v_lshlrev_b64 v[54:55], 14, v[54:55]
	v_lshlrev_b64 v[56:57], 14, v[56:57]
	v_lshlrev_b64 v[58:59], 14, v[58:59]
	v_lshlrev_b64 v[60:61], 14, v[60:61]
	v_lshlrev_b64 v[64:65], 14, v[64:65]
	v_lshlrev_b64 v[66:67], 14, v[66:67]
	v_lshlrev_b64 v[68:69], 14, v[68:69]
	v_or_b32_e32 v84, 46, v83
	v_mov_b32_e32 v85, v5
	v_lshl_add_u64 v[54:55], v[62:63], 0, v[54:55]
	v_lshl_add_u64 v[56:57], v[62:63], 0, v[56:57]
	v_lshl_add_u64 v[58:59], v[62:63], 0, v[58:59]
	v_lshl_add_u64 v[60:61], v[62:63], 0, v[60:61]
	v_lshl_add_u64 v[64:65], v[62:63], 0, v[64:65]
	v_lshl_add_u64 v[66:67], v[62:63], 0, v[66:67]
	v_lshl_add_u64 v[68:69], v[62:63], 0, v[68:69]
	v_lshlrev_b64 v[84:85], 14, v[84:85]
	v_lshl_add_u64 v[84:85], v[62:63], 0, v[84:85]
	global_load_dword v54, v[54:55], off nt
	s_nop 0
	global_load_dword v55, v[56:57], off nt
	s_nop 0
	global_load_dword v58, v[58:59], off nt
	s_nop 0
	global_load_dword v59, v[60:61], off nt
	global_load_dword v56, v[64:65], off nt
	global_load_dword v57, v[66:67], off nt
	s_nop 0
	global_load_dword v60, v[68:69], off nt
	global_load_dword v61, v[84:85], off nt
	v_or_b32_e32 v64, 48, v83
	v_mov_b32_e32 v65, v5
	v_or_b32_e32 v66, 50, v83
	v_mov_b32_e32 v67, v5
	v_or_b32_e32 v68, 52, v83
	v_mov_b32_e32 v69, v5
	v_lshlrev_b64 v[64:65], 14, v[64:65]
	v_lshlrev_b64 v[66:67], 14, v[66:67]
	v_lshlrev_b64 v[68:69], 14, v[68:69]
	v_or_b32_e32 v84, 54, v83
	v_mov_b32_e32 v85, v5
	v_or_b32_e32 v86, 56, v83
	v_mov_b32_e32 v87, v5
	v_or_b32_e32 v88, 58, v83
	v_mov_b32_e32 v89, v5
	v_or_b32_e32 v90, 60, v83
	v_mov_b32_e32 v91, v5
	v_or_b32_e32 v92, 62, v83
	v_mov_b32_e32 v93, v5
	v_lshl_add_u64 v[64:65], v[62:63], 0, v[64:65]
	v_lshl_add_u64 v[66:67], v[62:63], 0, v[66:67]
	v_lshl_add_u64 v[68:69], v[62:63], 0, v[68:69]
	v_lshlrev_b64 v[84:85], 14, v[84:85]
	v_lshlrev_b64 v[86:87], 14, v[86:87]
	v_lshlrev_b64 v[88:89], 14, v[88:89]
	v_lshlrev_b64 v[90:91], 14, v[90:91]
	v_lshlrev_b64 v[92:93], 14, v[92:93]
	v_lshl_add_u64 v[84:85], v[62:63], 0, v[84:85]
	v_lshl_add_u64 v[86:87], v[62:63], 0, v[86:87]
	v_lshl_add_u64 v[88:89], v[62:63], 0, v[88:89]
	v_lshl_add_u64 v[90:91], v[62:63], 0, v[90:91]
	v_lshl_add_u64 v[92:93], v[62:63], 0, v[92:93]
	global_load_dword v62, v[64:65], off nt
	global_load_dword v63, v[66:67], off nt
	s_nop 0
	global_load_dword v68, v[68:69], off nt
	s_nop 0
	global_load_dword v69, v[84:85], off nt
	global_load_dword v66, v[86:87], off nt
	global_load_dword v67, v[88:89], off nt
	global_load_dword v64, v[90:91], off nt
	global_load_dword v65, v[92:93], off nt
	s_andn2_b64 vcc, exec, s[6:7]
	s_cbranch_vccnz .LBB0_183
; template <bool F8 = false, class Map>
; __device__ __forceinline__ void transpose_item(const float* __restrict__ W, int Nsrc, int K, void* WTv, const float* kscale, float mul, LAS float* scr, int kb, int nb, int lane, const Map map) {
;     ...
;     if (kscale) {
; #pragma unroll
;         for (int i = 0; i < 32; ++i) v[i] *= kscale[k0 + 2 * i + kh];
;     }
	v_lshl_add_u64 v[84:85], v[4:5], 2, s[86:87]
	global_load_dword v86, v[84:85], off nt
	global_load_dword v87, v[84:85], off offset:8 nt
	global_load_dword v88, v[84:85], off offset:16 nt
	global_load_dword v89, v[84:85], off offset:24 nt
	global_load_dword v90, v[84:85], off offset:32 nt
	global_load_dword v91, v[84:85], off offset:40 nt
	global_load_dword v92, v[84:85], off offset:48 nt
	global_load_dword v93, v[84:85], off offset:56 nt
	global_load_dword v94, v[84:85], off offset:64 nt
	global_load_dword v95, v[84:85], off offset:72 nt
	global_load_dword v96, v[84:85], off offset:80 nt
	global_load_dword v97, v[84:85], off offset:88 nt
	global_load_dword v98, v[84:85], off offset:96 nt
	global_load_dword v99, v[84:85], off offset:104 nt
	global_load_dword v100, v[84:85], off offset:112 nt
	global_load_dword v101, v[84:85], off offset:120 nt
	global_load_dword v102, v[84:85], off offset:128 nt
	global_load_dword v103, v[84:85], off offset:136 nt
	global_load_dword v104, v[84:85], off offset:144 nt
	global_load_dword v105, v[84:85], off offset:152 nt
	global_load_dword v106, v[84:85], off offset:160 nt
	global_load_dword v107, v[84:85], off offset:168 nt
	global_load_dword v108, v[84:85], off offset:176 nt
	global_load_dword v109, v[84:85], off offset:184 nt
	global_load_dword v110, v[84:85], off offset:192 nt
	global_load_dword v111, v[84:85], off offset:200 nt
	global_load_dword v112, v[84:85], off offset:208 nt
	global_load_dword v113, v[84:85], off offset:216 nt
	global_load_dword v114, v[84:85], off offset:224 nt
	global_load_dword v115, v[84:85], off offset:232 nt
	global_load_dword v116, v[84:85], off offset:240 nt
	global_load_dword v117, v[84:85], off offset:248 nt
	s_waitcnt vmcnt(30)
	v_pk_mul_f32 v[38:39], v[38:39], v[86:87]
	s_waitcnt vmcnt(28)
	v_pk_mul_f32 v[42:43], v[42:43], v[88:89]
	s_waitcnt vmcnt(26)
	v_pk_mul_f32 v[40:41], v[40:41], v[90:91]
	s_waitcnt vmcnt(24)
	v_pk_mul_f32 v[44:45], v[44:45], v[92:93]
	s_waitcnt vmcnt(22)
	v_pk_mul_f32 v[46:47], v[46:47], v[94:95]
	s_waitcnt vmcnt(20)
	v_pk_mul_f32 v[50:51], v[50:51], v[96:97]
	s_waitcnt vmcnt(18)
	v_pk_mul_f32 v[48:49], v[48:49], v[98:99]
	s_waitcnt vmcnt(16)
	v_pk_mul_f32 v[52:53], v[52:53], v[100:101]
	s_waitcnt vmcnt(14)
	v_pk_mul_f32 v[54:55], v[54:55], v[102:103]
	s_waitcnt vmcnt(12)
	v_pk_mul_f32 v[58:59], v[58:59], v[104:105]
	s_waitcnt vmcnt(10)
	v_pk_mul_f32 v[56:57], v[56:57], v[106:107]
	s_waitcnt vmcnt(8)
	v_pk_mul_f32 v[60:61], v[60:61], v[108:109]
	s_waitcnt vmcnt(6)
	v_pk_mul_f32 v[62:63], v[62:63], v[110:111]
	s_waitcnt vmcnt(4)
	v_pk_mul_f32 v[68:69], v[68:69], v[112:113]
	s_waitcnt vmcnt(2)
	v_pk_mul_f32 v[66:67], v[66:67], v[114:115]
	s_waitcnt vmcnt(0)
	v_pk_mul_f32 v[64:65], v[64:65], v[116:117]

; #define LAS __attribute__((address_space(3)))
; template <bool F8 = false, class Map>
; __device__ __forceinline__ void transpose_item(const float* __restrict__ W, int Nsrc, int K, void* WTv, const float* kscale, float mul, LAS float* scr, int kb, int nb, int lane, const Map map) {
;     const int k0 = 64 * kb, j0 = 32 * nb, sc = map(j0 + (lane & 31)), kh = lane >> 5;
;     float v[32];
; #pragma unroll
;     for (int i = 0; i < 32; ++i) v[i] = sc >= 0 ? W[(size_t)(k0 + 2 * i + kh) * Nsrc + sc] : 0.f;
;     if (kscale) {
; #pragma unroll
;         for (int i = 0; i < 32; ++i) v[i] *= kscale[k0 + 2 * i + kh];
;     }
; __device__ __forceinline__ void p0_prologue(Frame& F) {
;     ...
;             if (r < I_UQ) { transpose_item<FP8_UP>(F.w_uq, 3072, QR, (void*)(ws + WS_WUQT), F.qn, FP8_UP ? 32.f : 1.f, scr, r / 96, r % 96, lane, MapUq{}); continue; } r -= I_UQ;
.LBB0_192:
	s_lshl_b32 s0, s0, 6
	s_and_b32 s0, s0, 0xffc0
	v_or_b32_e32 v83, s0, v3
	v_lshl_add_u64 v[62:63], v[4:5], 2, s[88:89]
	v_or_b32_e32 v4, 2, v83
	v_mad_u64_u32 v[40:41], s[4:5], v4, s21, v[62:63]
	v_or_b32_e32 v4, 4, v83
	v_mad_u64_u32 v[42:43], s[4:5], v4, s21, v[62:63]
	v_or_b32_e32 v4, 6, v83
	v_mad_u64_u32 v[44:45], s[4:5], v4, s21, v[62:63]
	v_or_b32_e32 v4, 8, v83
	v_mad_u64_u32 v[46:47], s[4:5], v4, s21, v[62:63]
	v_or_b32_e32 v4, 10, v83
	v_mad_u64_u32 v[48:49], s[4:5], v4, s21, v[62:63]
	v_or_b32_e32 v4, 12, v83
	v_mad_u64_u32 v[50:51], s[4:5], v4, s21, v[62:63]
	v_or_b32_e32 v4, 14, v83
	v_mad_u64_u32 v[38:39], s[4:5], v83, s21, v[62:63]
	v_mad_u64_u32 v[52:53], s[4:5], v4, s21, v[62:63]
	v_or_b32_e32 v4, 16, v83
	global_load_dword v38, v[38:39], off nt
	s_nop 0
	global_load_dword v39, v[40:41], off nt
	s_nop 0
	global_load_dword v42, v[42:43], off nt
	s_nop 0
	global_load_dword v43, v[44:45], off nt
	global_load_dword v40, v[46:47], off nt
	global_load_dword v41, v[48:49], off nt
	s_nop 0
	global_load_dword v44, v[50:51], off nt
	global_load_dword v45, v[52:53], off nt
	v_mad_u64_u32 v[46:47], s[4:5], v4, s21, v[62:63]
	v_or_b32_e32 v4, 18, v83
	v_mad_u64_u32 v[48:49], s[4:5], v4, s21, v[62:63]
	v_or_b32_e32 v4, 20, v83
	v_mad_u64_u32 v[50:51], s[4:5], v4, s21, v[62:63]
	v_or_b32_e32 v4, 22, v83
	v_mad_u64_u32 v[52:53], s[4:5], v4, s21, v[62:63]
	v_or_b32_e32 v4, 24, v83
	v_mad_u64_u32 v[54:55], s[4:5], v4, s21, v[62:63]
	v_or_b32_e32 v4, 26, v83
	v_mad_u64_u32 v[56:57], s[4:5], v4, s21, v[62:63]
	v_or_b32_e32 v4, 28, v83
	v_mad_u64_u32 v[58:59], s[4:5], v4, s21, v[62:63]
	v_or_b32_e32 v4, 30, v83
	v_mad_u64_u32 v[60:61], s[4:5], v4, s21, v[62:63]
	v_or_b32_e32 v4, 32, v83
	global_load_dword v46, v[46:47], off nt
	s_nop 0
	global_load_dword v47, v[48:49], off nt
	s_nop 0
	global_load_dword v50, v[50:51], off nt
	s_nop 0
	global_load_dword v51, v[52:53], off nt
	global_load_dword v48, v[54:55], off nt
	global_load_dword v49, v[56:57], off nt
	s_nop 0
	global_load_dword v52, v[58:59], off nt
	global_load_dword v53, v[60:61], off nt
	v_mad_u64_u32 v[54:55], s[4:5], v4, s21, v[62:63]
	v_or_b32_e32 v4, 34, v83
	v_mad_u64_u32 v[56:57], s[4:5], v4, s21, v[62:63]
	v_or_b32_e32 v4, 36, v83
	v_mad_u64_u32 v[58:59], s[4:5], v4, s21, v[62:63]
	v_or_b32_e32 v4, 38, v83
	v_mad_u64_u32 v[60:61], s[4:5], v4, s21, v[62:63]
	v_or_b32_e32 v4, 40, v83
	v_mad_u64_u32 v[64:65], s[4:5], v4, s21, v[62:63]
	v_or_b32_e32 v4, 42, v83
	v_mad_u64_u32 v[66:67], s[4:5], v4, s21, v[62:63]
	v_or_b32_e32 v4, 44, v83
	v_mad_u64_u32 v[68:69], s[4:5], v4, s21, v[62:63]
	v_or_b32_e32 v4, 46, v83
	v_mad_u64_u32 v[84:85], s[4:5], v4, s21, v[62:63]
	v_or_b32_e32 v4, 48, v83
	global_load_dword v54, v[54:55], off nt
	s_nop 0
	global_load_dword v55, v[56:57], off nt
	s_nop 0
	global_load_dword v58, v[58:59], off nt
	s_nop 0
	global_load_dword v59, v[60:61], off nt
	global_load_dword v56, v[64:65], off nt
	global_load_dword v57, v[66:67], off nt
	s_nop 0
	global_load_dword v60, v[68:69], off nt
	global_load_dword v61, v[84:85], off nt
	v_mad_u64_u32 v[64:65], s[4:5], v4, s21, v[62:63]
	v_or_b32_e32 v4, 50, v83
	v_mad_u64_u32 v[66:67], s[4:5], v4, s21, v[62:63]
	v_or_b32_e32 v4, 52, v83
	v_mad_u64_u32 v[68:69], s[4:5], v4, s21, v[62:63]
	v_or_b32_e32 v4, 54, v83
	v_mad_u64_u32 v[84:85], s[4:5], v4, s21, v[62:63]
	v_or_b32_e32 v4, 56, v83
	v_mad_u64_u32 v[86:87], s[4:5], v4, s21, v[62:63]
	v_or_b32_e32 v4, 58, v83
	v_mad_u64_u32 v[88:89], s[4:5], v4, s21, v[62:63]
	v_or_b32_e32 v4, 60, v83
	v_mad_u64_u32 v[90:91], s[4:5], v4, s21, v[62:63]
	v_or_b32_e32 v4, 62, v83
	v_mad_u64_u32 v[92:93], s[4:5], v4, s21, v[62:63]
	global_load_dword v62, v[64:65], off nt
	global_load_dword v63, v[66:67], off nt
	s_nop 0
	global_load_dword v68, v[68:69], off nt
	s_nop 0
	global_load_dword v69, v[84:85], off nt
	global_load_dword v66, v[86:87], off nt
	global_load_dword v67, v[88:89], off nt
	global_load_dword v64, v[90:91], off nt
	global_load_dword v65, v[92:93], off nt
	s_andn2_b64 vcc, exec, s[8:9]
	s_cbranch_vccnz .LBB0_194
	v_lshlrev_b32_e32 v4, 2, v83
	global_load_dword v84, v4, s[84:85] nt
	global_load_dword v85, v4, s[84:85] offset:8 nt
	global_load_dword v86, v4, s[84:85] offset:16 nt
	global_load_dword v87, v4, s[84:85] offset:24 nt
	global_load_dword v88, v4, s[84:85] offset:32 nt
	global_load_dword v89, v4, s[84:85] offset:40 nt
	global_load_dword v90, v4, s[84:85] offset:48 nt
	global_load_dword v91, v4, s[84:85] offset:56 nt
	global_load_dword v92, v4, s[84:85] offset:64 nt
	global_load_dword v93, v4, s[84:85] offset:72 nt
	global_load_dword v94, v4, s[84:85] offset:80 nt
	global_load_dword v95, v4, s[84:85] offset:88 nt
	global_load_dword v96, v4, s[84:85] offset:96 nt
	global_load_dword v97, v4, s[84:85] offset:104 nt
	global_load_dword v98, v4, s[84:85] offset:112 nt
	global_load_dword v99, v4, s[84:85] offset:120 nt
	global_load_dword v100, v4, s[84:85] offset:128 nt
	global_load_dword v101, v4, s[84:85] offset:136 nt
	global_load_dword v102, v4, s[84:85] offset:144 nt
	global_load_dword v103, v4, s[84:85] offset:152 nt
	global_load_dword v104, v4, s[84:85] offset:160 nt
	global_load_dword v105, v4, s[84:85] offset:168 nt
	global_load_dword v106, v4, s[84:85] offset:176 nt
	global_load_dword v107, v4, s[84:85] offset:184 nt
	global_load_dword v108, v4, s[84:85] offset:192 nt
	global_load_dword v109, v4, s[84:85] offset:200 nt
	global_load_dword v110, v4, s[84:85] offset:208 nt
	global_load_dword v111, v4, s[84:85] offset:216 nt
	global_load_dword v112, v4, s[84:85] offset:224 nt
	global_load_dword v113, v4, s[84:85] offset:232 nt
	global_load_dword v114, v4, s[84:85] offset:240 nt
	global_load_dword v115, v4, s[84:85] offset:248 nt
	s_waitcnt vmcnt(30)
	v_pk_mul_f32 v[38:39], v[38:39], v[84:85]
	s_waitcnt vmcnt(28)
	v_pk_mul_f32 v[42:43], v[42:43], v[86:87]
	s_waitcnt vmcnt(26)
	v_pk_mul_f32 v[40:41], v[40:41], v[88:89]
	s_waitcnt vmcnt(24)
	v_pk_mul_f32 v[44:45], v[44:45], v[90:91]
	s_waitcnt vmcnt(22)
	v_pk_mul_f32 v[46:47], v[46:47], v[92:93]
	s_waitcnt vmcnt(20)
	v_pk_mul_f32 v[50:51], v[50:51], v[94:95]
	s_waitcnt vmcnt(18)
	v_pk_mul_f32 v[48:49], v[48:49], v[96:97]
	s_waitcnt vmcnt(16)
	v_pk_mul_f32 v[52:53], v[52:53], v[98:99]
	s_waitcnt vmcnt(14)
	v_pk_mul_f32 v[54:55], v[54:55], v[100:101]
	s_waitcnt vmcnt(12)
	v_pk_mul_f32 v[58:59], v[58:59], v[102:103]
	s_waitcnt vmcnt(10)
	v_pk_mul_f32 v[56:57], v[56:57], v[104:105]
	s_waitcnt vmcnt(8)
	v_pk_mul_f32 v[60:61], v[60:61], v[106:107]
	s_waitcnt vmcnt(6)
	v_pk_mul_f32 v[62:63], v[62:63], v[108:109]
	s_waitcnt vmcnt(4)
	v_pk_mul_f32 v[68:69], v[68:69], v[110:111]
	s_waitcnt vmcnt(2)
	v_pk_mul_f32 v[66:67], v[66:67], v[112:113]
	s_waitcnt vmcnt(0)
	v_pk_mul_f32 v[64:65], v[64:65], v[114:115]

; #define LAS __attribute__((address_space(3)))
; template <bool F8 = false, class Map>
; __device__ __forceinline__ void transpose_item(const float* __restrict__ W, int Nsrc, int K, void* WTv, const float* kscale, float mul, LAS float* scr, int kb, int nb, int lane, const Map map) {
;     const int k0 = 64 * kb, j0 = 32 * nb, sc = map(j0 + (lane & 31)), kh = lane >> 5;
;     float v[32];
; #pragma unroll
;     for (int i = 0; i < 32; ++i) v[i] = sc >= 0 ? W[(size_t)(k0 + 2 * i + kh) * Nsrc + sc] : 0.f;
; __device__ __forceinline__ void p0_prologue(Frame& F) {
;     ...
;             if (r < I_OUT) { int kb, nb; blk16(r, 64, kb, nb); transpose_item<FP8_OUT>(F.w_out, D, D, (void*)(ws + WS_WOUTT), nullptr, FP8_OUT ? 64.f : 1.f, scr, kb, nb, lane, MapId{}); continue; } r -= I_OUT;
.LBB0_196:
	s_andn2_b64 vcc, exec, s[4:5]
	s_cbranch_vccnz .LBB0_198
	s_add_i32 s0, s58, 0xfffec600
	s_lshr_b32 s4, s0, 4
	s_and_b32 s4, s4, 48
	s_bfe_u32 s5, s58, 0x40004
	s_lshr_b32 s0, s0, 6
	s_or_b32 s4, s4, s5
	s_and_b32 s0, s0, 0x3f0
	s_and_b32 s5, s58, 15
	s_or_b32 s5, s0, s5
	s_lshl_b32 s0, s4, 6
	s_lshl_b32 s4, s5, 5
	v_or_b32_e32 v4, s4, v1
	v_readlane_b32 s60, v245, 10
	v_or_b32_e32 v40, s0, v3
	v_lshlrev_b32_e32 v4, 2, v4
	v_readlane_b32 s61, v245, 11
	v_readlane_b32 s62, v245, 12
	v_readlane_b32 s63, v245, 13
	v_lshl_add_u64 v[38:39], s[60:61], 0, v[4:5]
	v_lshlrev_b32_e32 v4, 14, v40
	v_lshl_add_u64 v[38:39], v[38:39], 0, v[4:5]
	v_add_co_u32_e32 v40, vcc, s22, v38
	v_readlane_b32 s64, v245, 14
	s_nop 0
	v_addc_co_u32_e32 v41, vcc, 0, v39, vcc
	v_add_co_u32_e32 v42, vcc, s23, v38
	v_readlane_b32 s65, v245, 15
	s_nop 0
	v_addc_co_u32_e32 v43, vcc, 0, v39, vcc
	v_add_co_u32_e32 v44, vcc, s24, v38
	v_readlane_b32 s66, v245, 16
	s_nop 0
	v_addc_co_u32_e32 v45, vcc, 0, v39, vcc
	v_add_co_u32_e32 v46, vcc, s25, v38
	v_readlane_b32 s67, v245, 17
	s_nop 0
	v_addc_co_u32_e32 v47, vcc, 0, v39, vcc
	v_add_co_u32_e32 v48, vcc, s26, v38
	v_readlane_b32 s68, v245, 18
	s_nop 0
	v_addc_co_u32_e32 v49, vcc, 0, v39, vcc
	v_add_co_u32_e32 v50, vcc, s27, v38
	v_readlane_b32 s69, v245, 19
	s_nop 0
	v_addc_co_u32_e32 v51, vcc, 0, v39, vcc
	v_add_co_u32_e32 v52, vcc, s28, v38
	v_readlane_b32 s70, v245, 20
	s_nop 0
	v_addc_co_u32_e32 v53, vcc, 0, v39, vcc
	global_load_dword v4, v[38:39], off nt
	global_load_dword v56, v[40:41], off nt
	global_load_dword v57, v[42:43], off nt
	global_load_dword v58, v[44:45], off nt
	global_load_dword v59, v[46:47], off nt
	global_load_dword v60, v[48:49], off nt
	global_load_dword v61, v[50:51], off nt
	global_load_dword v62, v[52:53], off nt
	v_add_co_u32_e32 v40, vcc, s29, v38
	v_readlane_b32 s71, v245, 21
	s_nop 0
	v_addc_co_u32_e32 v41, vcc, 0, v39, vcc
	v_add_co_u32_e32 v42, vcc, s33, v38
	v_readlane_b32 s72, v245, 22
	s_nop 0
	v_addc_co_u32_e32 v43, vcc, 0, v39, vcc
	v_add_co_u32_e32 v44, vcc, s34, v38
	v_readlane_b32 s73, v245, 23
	s_nop 0
	v_addc_co_u32_e32 v45, vcc, 0, v39, vcc
	v_add_co_u32_e32 v46, vcc, s36, v38
	v_readlane_b32 s74, v245, 24
	s_nop 0
	v_addc_co_u32_e32 v47, vcc, 0, v39, vcc
	v_add_co_u32_e32 v48, vcc, s38, v38
	v_readlane_b32 s75, v245, 25
	s_nop 0
	v_addc_co_u32_e32 v49, vcc, 0, v39, vcc
	v_add_co_u32_e32 v50, vcc, s39, v38
	s_nop 1
	v_addc_co_u32_e32 v51, vcc, 0, v39, vcc
	v_add_co_u32_e32 v52, vcc, s40, v38
	s_nop 1
	v_addc_co_u32_e32 v53, vcc, 0, v39, vcc
	v_add_co_u32_e32 v54, vcc, s41, v38
	s_nop 1
	v_addc_co_u32_e32 v55, vcc, 0, v39, vcc
	global_load_dword v63, v[40:41], off nt
	global_load_dword v64, v[42:43], off nt
	global_load_dword v65, v[44:45], off nt
	global_load_dword v66, v[46:47], off nt
	global_load_dword v67, v[48:49], off nt
	global_load_dword v68, v[50:51], off nt
	global_load_dword v69, v[52:53], off nt
	global_load_dword v83, v[54:55], off nt
	v_add_co_u32_e32 v40, vcc, s42, v38
	s_nop 1
	v_addc_co_u32_e32 v41, vcc, 0, v39, vcc
	v_add_co_u32_e32 v42, vcc, s43, v38
	s_nop 1
	v_addc_co_u32_e32 v43, vcc, 0, v39, vcc
	v_add_co_u32_e32 v44, vcc, s44, v38
	s_nop 1
	v_addc_co_u32_e32 v45, vcc, 0, v39, vcc
	v_add_co_u32_e32 v46, vcc, s45, v38
	s_nop 1
	v_addc_co_u32_e32 v47, vcc, 0, v39, vcc
	v_add_co_u32_e32 v48, vcc, s46, v38
	s_nop 1
	v_addc_co_u32_e32 v49, vcc, 0, v39, vcc
	v_add_co_u32_e32 v50, vcc, s47, v38
	s_nop 1
	v_addc_co_u32_e32 v51, vcc, 0, v39, vcc
	v_add_co_u32_e32 v52, vcc, s48, v38
	s_nop 1
	v_addc_co_u32_e32 v53, vcc, 0, v39, vcc
	v_add_co_u32_e32 v54, vcc, s49, v38
	s_nop 1
	v_addc_co_u32_e32 v55, vcc, 0, v39, vcc
	global_load_dword v84, v[40:41], off nt
	global_load_dword v85, v[42:43], off nt
	global_load_dword v86, v[44:45], off nt
	global_load_dword v87, v[46:47], off nt
	global_load_dword v88, v[48:49], off nt
	global_load_dword v89, v[50:51], off nt
	global_load_dword v90, v[52:53], off nt
	s_nop 0
	global_load_dword v54, v[54:55], off nt
	v_add_co_u32_e32 v40, vcc, s50, v38
	s_nop 1
	v_addc_co_u32_e32 v41, vcc, 0, v39, vcc
	v_add_co_u32_e32 v42, vcc, s51, v38
	s_nop 1
	v_addc_co_u32_e32 v43, vcc, 0, v39, vcc
	v_add_co_u32_e32 v44, vcc, s52, v38
	s_nop 1
	v_addc_co_u32_e32 v45, vcc, 0, v39, vcc
	v_add_co_u32_e32 v46, vcc, s53, v38
	s_nop 1
	v_addc_co_u32_e32 v47, vcc, 0, v39, vcc
	v_add_co_u32_e32 v48, vcc, s54, v38
	s_nop 1
	v_addc_co_u32_e32 v49, vcc, 0, v39, vcc
	v_add_co_u32_e32 v50, vcc, s55, v38
	s_nop 1
	v_addc_co_u32_e32 v51, vcc, 0, v39, vcc
	v_add_co_u32_e32 v52, vcc, s56, v38
	s_nop 1
	v_addc_co_u32_e32 v53, vcc, 0, v39, vcc
	v_add_co_u32_e32 v38, vcc, s57, v38
	s_nop 1
	v_addc_co_u32_e32 v39, vcc, 0, v39, vcc
	global_load_dword v40, v[40:41], off nt
	s_nop 0
	global_load_dword v41, v[42:43], off nt
	s_nop 0
	global_load_dword v42, v[44:45], off nt
	global_load_dword v43, v[46:47], off nt
	s_nop 0
	global_load_dword v44, v[48:49], off nt
	global_load_dword v45, v[50:51], off nt
	global_load_dword v46, v[52:53], off nt
	s_nop 0
	global_load_dword v38, v[38:39], off nt
	s_waitcnt vmcnt(30)
; #define LAS __attribute__((address_space(3)))
; __device__ __forceinline__ unsigned pack4_fp8(float a, float b, float c, float d) { unsigned w = 0u; w = (unsigned)__builtin_amdgcn_cvt_pk_fp8_f32(a, b, (int)w, false); w = (unsigned)__builtin_amdgcn_cvt_pk_fp8_f32(c, d, (int)w, true); return w; }
; template <bool F8 = false, class Map>
; __device__ __forceinline__ void transpose_item(const float* __restrict__ W, int Nsrc, int K, void* WTv, const float* kscale, float mul, LAS float* scr, int kb, int nb, int lane, const Map map) {
;     ...
;     for (int i = 0; i < 32; ++i) scr[(2 * i + kh) * 33 + (lane & 31)] = v[i];
;     asm volatile("s_waitcnt lgkmcnt(0)" ::: "memory");
;     if constexpr (F8) {
;         unsigned char* WT = (unsigned char*)WTv; const int c = lane & 3;
; #pragma unroll
;         for (int jj = 0; jj < 2; ++jj) { const int n = (lane >> 2) + 16 * jj; const LAS float* s = scr + (16 * c) * 33 + n;
;             u32x4 o; o.x = pack4_fp8(s[0 * 33] * mul, s[1 * 33] * mul, s[2 * 33] * mul, s[3 * 33] * mul); o.y = pack4_fp8(s[4 * 33] * mul, s[5 * 33] * mul, s[6 * 33] * mul, s[7 * 33] * mul);
;             o.z = pack4_fp8(s[8 * 33] * mul, s[9 * 33] * mul, s[10 * 33] * mul, s[11 * 33] * mul); o.w = pack4_fp8(s[12 * 33] * mul, s[13 * 33] * mul, s[14 * 33] * mul, s[15 * 33] * mul);
;             *(u32x4*)(WT + (size_t)(j0 + n) * K + k0 + 16 * c) = o; }
	ds_write2_b32 v70, v4, v56 offset1:66
	s_waitcnt vmcnt(28)
	ds_write2_b32 v70, v57, v58 offset0:132 offset1:198
	v_add_u32_e32 v4, 0x400, v70
	s_waitcnt vmcnt(26)
	ds_write2_b32 v4, v59, v60 offset0:8 offset1:74
	s_waitcnt vmcnt(24)
	ds_write2_b32 v4, v61, v62 offset0:140 offset1:206
	v_add_u32_e32 v4, 0x800, v70
	s_waitcnt vmcnt(22)
	ds_write2_b32 v4, v63, v64 offset0:16 offset1:82
	s_waitcnt vmcnt(20)
	ds_write2_b32 v4, v65, v66 offset0:148 offset1:214
	v_add_u32_e32 v4, 0xc00, v70
	s_waitcnt vmcnt(18)
	ds_write2_b32 v4, v67, v68 offset0:24 offset1:90
	s_waitcnt vmcnt(16)
	ds_write2_b32 v4, v69, v83 offset0:156 offset1:222
	v_add_u32_e32 v4, 0x1000, v70
	s_waitcnt vmcnt(14)
	ds_write2_b32 v4, v84, v85 offset0:32 offset1:98
	s_waitcnt vmcnt(12)
	ds_write2_b32 v4, v86, v87 offset0:164 offset1:230
	v_add_u32_e32 v4, 0x1400, v70
	s_waitcnt vmcnt(10)
	ds_write2_b32 v4, v88, v89 offset0:40 offset1:106
	s_waitcnt vmcnt(8)
	ds_write2_b32 v4, v90, v54 offset0:172 offset1:238
	v_add_u32_e32 v4, 0x1800, v70
	s_waitcnt vmcnt(6)
	ds_write2_b32 v4, v40, v41 offset0:48 offset1:114
	s_waitcnt vmcnt(4)
	ds_write2_b32 v4, v42, v43 offset0:180 offset1:246
	v_add_u32_e32 v4, 0x1c00, v70
	s_waitcnt vmcnt(2)
	ds_write2_b32 v4, v44, v45 offset0:56 offset1:122
	s_waitcnt vmcnt(0)
	ds_write2_b32 v4, v46, v38 offset0:188 offset1:254
	s_waitcnt lgkmcnt(0)
	ds_read2_b32 v[42:43], v77 offset1:16
	ds_read2_b32 v[44:45], v77 offset0:33 offset1:49
	ds_read2_b32 v[46:47], v77 offset0:66 offset1:82
	ds_read2_b32 v[50:51], v77 offset0:99 offset1:115
	v_mov_b32_e32 v38, v5
	s_waitcnt lgkmcnt(3)
	v_mul_f32_e32 v4, 0x42800000, v42
	s_waitcnt lgkmcnt(2)
	v_mul_f32_e32 v39, 0x42800000, v44
	v_cvt_pk_fp8_f32 v38, v4, v39
	ds_read2_b32 v[52:53], v77 offset0:132 offset1:148
	ds_read2_b32 v[54:55], v77 offset0:165 offset1:181
	ds_read2_b32 v[56:57], v77 offset0:198 offset1:214
	s_waitcnt lgkmcnt(4)
	v_mul_f32_e32 v40, 0x42800000, v46
	s_waitcnt lgkmcnt(3)
	v_mul_f32_e32 v4, 0x42800000, v50
	v_cvt_pk_fp8_f32 v38, v40, v4 op_sel:[0,0,1]
	s_waitcnt lgkmcnt(2)
	v_mul_f32_e32 v4, 0x42800000, v52
	s_waitcnt lgkmcnt(1)
	v_mul_f32_e32 v40, 0x42800000, v54
	v_mov_b32_e32 v39, v5
	ds_read2_b32 v[58:59], v77 offset0:231 offset1:247
	v_cvt_pk_fp8_f32 v39, v4, v40
	v_add_u32_e32 v4, 0x400, v77
	ds_read2_b32 v[60:61], v4 offset0:8 offset1:24
	ds_read2_b32 v[62:63], v4 offset0:41 offset1:57
	ds_read2_b32 v[64:65], v4 offset0:74 offset1:90
	ds_read2_b32 v[66:67], v4 offset0:107 offset1:123
	ds_read2_b32 v[68:69], v4 offset0:140 offset1:156
	ds_read2_b32 v[84:85], v4 offset0:173 offset1:189
	s_waitcnt lgkmcnt(7)
	v_mul_f32_e32 v41, 0x42800000, v56
	s_waitcnt lgkmcnt(6)
	v_mul_f32_e32 v40, 0x42800000, v58
	v_cvt_pk_fp8_f32 v39, v41, v40 op_sel:[0,0,1]
	s_waitcnt lgkmcnt(5)
	v_mul_f32_e32 v41, 0x42800000, v60
	s_waitcnt lgkmcnt(4)
	v_mul_f32_e32 v42, 0x42800000, v62
	v_mov_b32_e32 v40, v5
	ds_read2_b32 v[86:87], v4 offset0:206 offset1:222
	ds_read2_b32 v[88:89], v4 offset0:239 offset1:255
	v_cvt_pk_fp8_f32 v40, v41, v42
	s_waitcnt lgkmcnt(3)
	v_mul_f32_e32 v42, 0x42800000, v68
	s_waitcnt lgkmcnt(2)
	v_mul_f32_e32 v50, 0x42800000, v84
	v_mov_b32_e32 v41, v5
	v_cvt_pk_fp8_f32 v41, v42, v50
	v_mul_f32_e32 v44, 0x42800000, v64
	v_mul_f32_e32 v46, 0x42800000, v66
	s_waitcnt lgkmcnt(1)
	v_mul_f32_e32 v4, 0x42800000, v86
	s_waitcnt lgkmcnt(0)
	v_mul_f32_e32 v42, 0x42800000, v88
	v_cvt_pk_fp8_f32 v40, v44, v46 op_sel:[0,0,1]
	v_cvt_pk_fp8_f32 v41, v4, v42 op_sel:[0,0,1]
	v_or_b32_e32 v4, s4, v76
	v_lshl_add_u64 v[48:49], v[18:19], 0, s[0:1]
	v_lshlrev_b32_e32 v4, 12, v4
	v_lshl_add_u64 v[90:91], v[48:49], 0, v[4:5]
	global_store_dwordx4 v[90:91], v[38:41], off
	v_mul_f32_e32 v4, 0x42800000, v43
	v_mul_f32_e32 v42, 0x42800000, v55
	v_mul_f32_e32 v39, 0x42800000, v45
	v_mov_b32_e32 v38, v5
	v_cvt_pk_fp8_f32 v38, v4, v39
	v_mul_f32_e32 v4, 0x42800000, v53
	v_mov_b32_e32 v39, v5
	v_cvt_pk_fp8_f32 v39, v4, v42
	v_mul_f32_e32 v40, 0x42800000, v47
	v_mul_f32_e32 v41, 0x42800000, v51
	v_cvt_pk_fp8_f32 v38, v40, v41 op_sel:[0,0,1]
	v_mul_f32_e32 v4, 0x42800000, v57
	v_mul_f32_e32 v40, 0x42800000, v59
	v_cvt_pk_fp8_f32 v39, v4, v40 op_sel:[0,0,1]
	v_mul_f32_e32 v4, 0x42800000, v61
	v_mul_f32_e32 v41, 0x42800000, v63
	v_mov_b32_e32 v40, v5
	v_cvt_pk_fp8_f32 v40, v4, v41
	v_mul_f32_e32 v4, 0x42800000, v69
	v_mul_f32_e32 v44, 0x42800000, v85
	v_mov_b32_e32 v41, v5
	v_cvt_pk_fp8_f32 v41, v4, v44
	v_mul_f32_e32 v42, 0x42800000, v65
	v_mul_f32_e32 v43, 0x42800000, v67
	v_cvt_pk_fp8_f32 v40, v42, v43 op_sel:[0,0,1]
	v_mul_f32_e32 v4, 0x42800000, v87
	v_mul_f32_e32 v42, 0x42800000, v89
	v_cvt_pk_fp8_f32 v41, v4, v42 op_sel:[0,0,1]
	v_or_b32_e32 v4, s4, v78
	v_lshlrev_b32_e32 v4, 12, v4
	v_lshl_add_u64 v[42:43], v[48:49], 0, v[4:5]
	global_store_dwordx4 v[42:43], v[38:41], off
	s_waitcnt lgkmcnt(0)

; #define LAS __attribute__((address_space(3)))
; template <bool F8 = false, class Map>
; __device__ __forceinline__ void transpose_item(const float* __restrict__ W, int Nsrc, int K, void* WTv, const float* kscale, float mul, LAS float* scr, int kb, int nb, int lane, const Map map) {
;     const int k0 = 64 * kb, j0 = 32 * nb, sc = map(j0 + (lane & 31)), kh = lane >> 5;
;     float v[32];
; #pragma unroll
;     for (int i = 0; i < 32; ++i) v[i] = sc >= 0 ? W[(size_t)(k0 + 2 * i + kh) * Nsrc + sc] : 0.f;
; __device__ __forceinline__ void p0_prologue(Frame& F) {
;     ...
;             if (r < I_IN) { int kb, nb; blk8(r, 64, kb, nb); transpose_item<FP8_IN>(F.w_in, 7280, D, (void*)(ws + WS_WINT), nullptr, FP8_IN ? 64.f : 1.f, scr, kb, nb, lane, MapWin{}); continue; } r -= I_IN;
.LBB0_216:
	s_and_b32 s0, s17, 0xfc0
	v_readlane_b32 s60, v245, 29
	v_or_b32_e32 v40, s0, v3
	v_readlane_b32 s70, v245, 39
	v_readlane_b32 s71, v245, 40
	v_cmp_lt_i32_e64 s[4:5], -1, v4
	v_mov_b32_e32 v41, 0
	v_lshl_add_u64 v[38:39], v[4:5], 2, s[70:71]
	v_mul_u32_u24_e32 v4, 0x71c0, v40
	v_mov_b32_e32 v40, 0
	v_readlane_b32 s61, v245, 30
	v_readlane_b32 s62, v245, 31
	v_readlane_b32 s63, v245, 32
	v_readlane_b32 s64, v245, 33
	v_readlane_b32 s65, v245, 34
	v_readlane_b32 s66, v245, 35
	v_readlane_b32 s67, v245, 36
	v_readlane_b32 s68, v245, 37
	v_readlane_b32 s69, v245, 38
	v_readlane_b32 s72, v245, 41
	v_readlane_b32 s73, v245, 42
	v_readlane_b32 s74, v245, 43
	v_readlane_b32 s75, v245, 44
	s_and_saveexec_b64 s[10:11], s[4:5]
	s_cbranch_execz .LBB0_218
	v_lshl_add_u64 v[42:43], v[38:39], 0, v[4:5]
	global_load_dword v40, v[42:43], off nt
.LBB0_218:
	s_or_b64 exec, exec, s[10:11]
	s_and_saveexec_b64 s[10:11], s[4:5]
	s_cbranch_execz .LBB0_220
	v_lshl_add_u64 v[42:43], v[38:39], 0, v[4:5]
	v_add_co_u32_e32 v42, vcc, 0xe000, v42
	s_nop 1
	v_addc_co_u32_e32 v43, vcc, 0, v43, vcc
	global_load_dword v41, v[42:43], off offset:896 nt
.LBB0_220:
	s_or_b64 exec, exec, s[10:11]
	v_mov_b32_e32 v42, 0
	v_mov_b32_e32 v43, 0
	s_and_saveexec_b64 s[10:11], s[4:5]
	s_cbranch_execz .LBB0_222
	v_lshl_add_u64 v[44:45], v[38:39], 0, v[4:5]
	v_add_co_u32_e32 v44, vcc, 0x1c000, v44
	s_nop 1
	v_addc_co_u32_e32 v45, vcc, 0, v45, vcc
	global_load_dword v43, v[44:45], off offset:1792 nt
.LBB0_222:
	s_or_b64 exec, exec, s[10:11]
	s_and_saveexec_b64 s[10:11], s[4:5]
	s_cbranch_execz .LBB0_224
	v_lshl_add_u64 v[44:45], v[38:39], 0, v[4:5]
	v_add_co_u32_e32 v44, vcc, 0x2a000, v44
	s_nop 1
	v_addc_co_u32_e32 v45, vcc, 0, v45, vcc
	global_load_dword v42, v[44:45], off offset:2688 nt
.LBB0_224:
	s_or_b64 exec, exec, s[10:11]
	v_mov_b32_e32 v44, 0
	v_mov_b32_e32 v45, 0
	s_and_saveexec_b64 s[10:11], s[4:5]
	s_cbranch_execz .LBB0_226
	v_lshl_add_u64 v[46:47], v[38:39], 0, v[4:5]
	v_add_co_u32_e32 v46, vcc, 0x38000, v46
	s_nop 1
	v_addc_co_u32_e32 v47, vcc, 0, v47, vcc
	global_load_dword v45, v[46:47], off offset:3584 nt
.LBB0_226:
	s_or_b64 exec, exec, s[10:11]
	s_and_saveexec_b64 s[10:11], s[4:5]
	s_cbranch_execz .LBB0_228
	v_lshl_add_u64 v[46:47], v[38:39], 0, v[4:5]
	v_add_co_u32_e32 v46, vcc, 0x47000, v46
	s_nop 1
	v_addc_co_u32_e32 v47, vcc, 0, v47, vcc
	global_load_dword v44, v[46:47], off offset:384 nt
.LBB0_228:
	s_or_b64 exec, exec, s[10:11]
	v_mov_b32_e32 v46, 0
	v_mov_b32_e32 v47, 0
	s_and_saveexec_b64 s[10:11], s[4:5]
	s_cbranch_execz .LBB0_230
	v_lshl_add_u64 v[48:49], v[38:39], 0, v[4:5]
	v_add_co_u32_e32 v48, vcc, 0x55000, v48
	s_nop 1
	v_addc_co_u32_e32 v49, vcc, 0, v49, vcc
	global_load_dword v47, v[48:49], off offset:1280 nt
.LBB0_230:
	s_or_b64 exec, exec, s[10:11]
	s_and_saveexec_b64 s[10:11], s[4:5]
	s_cbranch_execz .LBB0_232
	v_lshl_add_u64 v[48:49], v[38:39], 0, v[4:5]
	v_add_co_u32_e32 v48, vcc, 0x63000, v48
	s_nop 1
	v_addc_co_u32_e32 v49, vcc, 0, v49, vcc
	global_load_dword v46, v[48:49], off offset:2176 nt
.LBB0_232:
	s_or_b64 exec, exec, s[10:11]
	v_mov_b32_e32 v48, 0
	v_mov_b32_e32 v49, 0
	s_and_saveexec_b64 s[10:11], s[4:5]
	s_cbranch_execz .LBB0_234
	v_lshl_add_u64 v[50:51], v[38:39], 0, v[4:5]
	v_add_co_u32_e32 v50, vcc, 0x71000, v50
	s_nop 1
	v_addc_co_u32_e32 v51, vcc, 0, v51, vcc
	global_load_dword v49, v[50:51], off offset:3072 nt
.LBB0_234:
	s_or_b64 exec, exec, s[10:11]
	s_and_saveexec_b64 s[10:11], s[4:5]
	s_cbranch_execz .LBB0_236
	v_lshl_add_u64 v[50:51], v[38:39], 0, v[4:5]
	v_add_co_u32_e32 v50, vcc, 0x7f000, v50
	s_nop 1
	v_addc_co_u32_e32 v51, vcc, 0, v51, vcc
	global_load_dword v48, v[50:51], off offset:3968 nt
.LBB0_236:
	s_or_b64 exec, exec, s[10:11]
	v_mov_b32_e32 v50, 0
	v_mov_b32_e32 v51, 0
	s_and_saveexec_b64 s[10:11], s[4:5]
	s_cbranch_execz .LBB0_238
	v_lshl_add_u64 v[52:53], v[38:39], 0, v[4:5]
	v_add_co_u32_e32 v52, vcc, 0x8e000, v52
	s_nop 1
	v_addc_co_u32_e32 v53, vcc, 0, v53, vcc
	global_load_dword v51, v[52:53], off offset:768 nt
.LBB0_238:
	s_or_b64 exec, exec, s[10:11]
	s_and_saveexec_b64 s[10:11], s[4:5]
	s_cbranch_execz .LBB0_240
	v_lshl_add_u64 v[52:53], v[38:39], 0, v[4:5]
	v_add_co_u32_e32 v52, vcc, 0x9c000, v52
	s_nop 1
	v_addc_co_u32_e32 v53, vcc, 0, v53, vcc
	global_load_dword v50, v[52:53], off offset:1664 nt
.LBB0_240:
	s_or_b64 exec, exec, s[10:11]
	v_mov_b32_e32 v52, 0
	v_mov_b32_e32 v53, 0
	s_and_saveexec_b64 s[10:11], s[4:5]
	s_cbranch_execz .LBB0_242
	v_lshl_add_u64 v[54:55], v[38:39], 0, v[4:5]
	v_add_co_u32_e32 v54, vcc, 0xaa000, v54
	s_nop 1
	v_addc_co_u32_e32 v55, vcc, 0, v55, vcc
	global_load_dword v53, v[54:55], off offset:2560 nt
.LBB0_242:
	s_or_b64 exec, exec, s[10:11]
	s_and_saveexec_b64 s[10:11], s[4:5]
	s_cbranch_execz .LBB0_244
	v_lshl_add_u64 v[54:55], v[38:39], 0, v[4:5]
	v_add_co_u32_e32 v54, vcc, 0xb8000, v54
	s_nop 1
	v_addc_co_u32_e32 v55, vcc, 0, v55, vcc
	global_load_dword v52, v[54:55], off offset:3456 nt
.LBB0_244:
	s_or_b64 exec, exec, s[10:11]
	v_mov_b32_e32 v54, 0
	v_mov_b32_e32 v55, 0
	s_and_saveexec_b64 s[10:11], s[4:5]
	s_cbranch_execz .LBB0_246
	v_lshl_add_u64 v[56:57], v[38:39], 0, v[4:5]
	v_add_co_u32_e32 v56, vcc, 0xc7000, v56
	s_nop 1
	v_addc_co_u32_e32 v57, vcc, 0, v57, vcc
	global_load_dword v55, v[56:57], off offset:256 nt
; #define LAS __attribute__((address_space(3)))
; template <bool F8 = false, class Map>
; __device__ __forceinline__ void transpose_item(const float* __restrict__ W, int Nsrc, int K, void* WTv, const float* kscale, float mul, LAS float* scr, int kb, int nb, int lane, const Map map) {
;     const int k0 = 64 * kb, j0 = 32 * nb, sc = map(j0 + (lane & 31)), kh = lane >> 5;
;     float v[32];
; #pragma unroll
;     for (int i = 0; i < 32; ++i) v[i] = sc >= 0 ? W[(size_t)(k0 + 2 * i + kh) * Nsrc + sc] : 0.f;
.LBB0_246:
	s_or_b64 exec, exec, s[10:11]
	s_and_saveexec_b64 s[10:11], s[4:5]
	s_cbranch_execz .LBB0_248
	v_lshl_add_u64 v[56:57], v[38:39], 0, v[4:5]
	v_add_co_u32_e32 v56, vcc, 0xd5000, v56
	s_nop 1
	v_addc_co_u32_e32 v57, vcc, 0, v57, vcc
	global_load_dword v54, v[56:57], off offset:1152 nt
.LBB0_248:
	s_or_b64 exec, exec, s[10:11]
	v_mov_b32_e32 v56, 0
	v_mov_b32_e32 v57, 0
	s_and_saveexec_b64 s[10:11], s[4:5]
	s_cbranch_execz .LBB0_250
	v_lshl_add_u64 v[58:59], v[38:39], 0, v[4:5]
	v_add_co_u32_e32 v58, vcc, 0xe3000, v58
	s_nop 1
	v_addc_co_u32_e32 v59, vcc, 0, v59, vcc
	global_load_dword v57, v[58:59], off offset:2048 nt
.LBB0_250:
	s_or_b64 exec, exec, s[10:11]
	s_and_saveexec_b64 s[10:11], s[4:5]
	s_cbranch_execz .LBB0_252
	v_lshl_add_u64 v[58:59], v[38:39], 0, v[4:5]
	v_add_co_u32_e32 v58, vcc, 0xf1000, v58
	s_nop 1
	v_addc_co_u32_e32 v59, vcc, 0, v59, vcc
	global_load_dword v56, v[58:59], off offset:2944 nt
.LBB0_252:
	s_or_b64 exec, exec, s[10:11]
	v_mov_b32_e32 v58, 0
	v_mov_b32_e32 v59, 0
	s_and_saveexec_b64 s[10:11], s[4:5]
	s_cbranch_execz .LBB0_254
	v_lshl_add_u64 v[60:61], v[38:39], 0, v[4:5]
	v_add_co_u32_e32 v60, vcc, 0xff000, v60
	s_nop 1
	v_addc_co_u32_e32 v61, vcc, 0, v61, vcc
	global_load_dword v59, v[60:61], off offset:3840 nt
.LBB0_254:
	s_or_b64 exec, exec, s[10:11]
	s_and_saveexec_b64 s[10:11], s[4:5]
	s_cbranch_execz .LBB0_256
	v_lshl_add_u64 v[60:61], v[38:39], 0, v[4:5]
	v_add_co_u32_e32 v60, vcc, 0x10e000, v60
	s_nop 1
	v_addc_co_u32_e32 v61, vcc, 0, v61, vcc
	global_load_dword v58, v[60:61], off offset:640 nt
.LBB0_256:
	s_or_b64 exec, exec, s[10:11]
	v_mov_b32_e32 v60, 0
	v_mov_b32_e32 v61, 0
	s_and_saveexec_b64 s[10:11], s[4:5]
	s_cbranch_execz .LBB0_258
	v_lshl_add_u64 v[62:63], v[38:39], 0, v[4:5]
	v_add_co_u32_e32 v62, vcc, 0x11c000, v62
	s_nop 1
	v_addc_co_u32_e32 v63, vcc, 0, v63, vcc
	global_load_dword v61, v[62:63], off offset:1536 nt
.LBB0_258:
	s_or_b64 exec, exec, s[10:11]
	s_and_saveexec_b64 s[10:11], s[4:5]
	s_cbranch_execz .LBB0_260
	v_lshl_add_u64 v[62:63], v[38:39], 0, v[4:5]
	v_add_co_u32_e32 v62, vcc, 0x12a000, v62
	s_nop 1
	v_addc_co_u32_e32 v63, vcc, 0, v63, vcc
	global_load_dword v60, v[62:63], off offset:2432 nt
.LBB0_260:
	s_or_b64 exec, exec, s[10:11]
	v_mov_b32_e32 v62, 0
	v_mov_b32_e32 v63, 0
	s_and_saveexec_b64 s[10:11], s[4:5]
	s_cbranch_execz .LBB0_262
	v_lshl_add_u64 v[64:65], v[38:39], 0, v[4:5]
	v_add_co_u32_e32 v64, vcc, 0x138000, v64
	s_nop 1
	v_addc_co_u32_e32 v65, vcc, 0, v65, vcc
	global_load_dword v63, v[64:65], off offset:3328 nt
.LBB0_262:
	s_or_b64 exec, exec, s[10:11]
	s_and_saveexec_b64 s[10:11], s[4:5]
	s_cbranch_execz .LBB0_264
	v_lshl_add_u64 v[64:65], v[38:39], 0, v[4:5]
	v_add_co_u32_e32 v64, vcc, 0x147000, v64
	s_nop 1
	v_addc_co_u32_e32 v65, vcc, 0, v65, vcc
	global_load_dword v62, v[64:65], off offset:128 nt
.LBB0_264:
	s_or_b64 exec, exec, s[10:11]
	v_mov_b32_e32 v64, 0
	v_mov_b32_e32 v65, 0
	s_and_saveexec_b64 s[10:11], s[4:5]
	s_cbranch_execz .LBB0_266
	v_lshl_add_u64 v[66:67], v[38:39], 0, v[4:5]
	v_add_co_u32_e32 v66, vcc, 0x155000, v66
	s_nop 1
	v_addc_co_u32_e32 v67, vcc, 0, v67, vcc
	global_load_dword v65, v[66:67], off offset:1024 nt
.LBB0_266:
	s_or_b64 exec, exec, s[10:11]
	s_and_saveexec_b64 s[10:11], s[4:5]
	s_cbranch_execz .LBB0_268
	v_lshl_add_u64 v[66:67], v[38:39], 0, v[4:5]
	v_add_co_u32_e32 v66, vcc, 0x163000, v66
	s_nop 1
	v_addc_co_u32_e32 v67, vcc, 0, v67, vcc
	global_load_dword v64, v[66:67], off offset:1920 nt
.LBB0_268:
	s_or_b64 exec, exec, s[10:11]
	v_mov_b32_e32 v66, 0
	v_mov_b32_e32 v67, 0
	s_and_saveexec_b64 s[10:11], s[4:5]
	s_cbranch_execz .LBB0_270
	v_lshl_add_u64 v[68:69], v[38:39], 0, v[4:5]
	v_add_co_u32_e32 v68, vcc, 0x171000, v68
	s_nop 1
	v_addc_co_u32_e32 v69, vcc, 0, v69, vcc
	global_load_dword v67, v[68:69], off offset:2816 nt
.LBB0_270:
	s_or_b64 exec, exec, s[10:11]
	s_and_saveexec_b64 s[10:11], s[4:5]
	s_cbranch_execz .LBB0_272
	v_lshl_add_u64 v[68:69], v[38:39], 0, v[4:5]
	v_add_co_u32_e32 v68, vcc, 0x17f000, v68
	s_nop 1
	v_addc_co_u32_e32 v69, vcc, 0, v69, vcc
	global_load_dword v66, v[68:69], off offset:3712 nt
.LBB0_272:
	s_or_b64 exec, exec, s[10:11]
	v_mov_b32_e32 v68, 0
	v_mov_b32_e32 v69, 0
	s_and_saveexec_b64 s[10:11], s[4:5]
	s_cbranch_execz .LBB0_274
	v_lshl_add_u64 v[84:85], v[38:39], 0, v[4:5]
	v_add_co_u32_e32 v84, vcc, 0x18e000, v84
	s_nop 1
	v_addc_co_u32_e32 v85, vcc, 0, v85, vcc
	global_load_dword v69, v[84:85], off offset:512 nt
.LBB0_274:
	s_or_b64 exec, exec, s[10:11]
	s_and_saveexec_b64 s[10:11], s[4:5]
	s_cbranch_execz .LBB0_276
	v_lshl_add_u64 v[84:85], v[38:39], 0, v[4:5]
	v_add_co_u32_e32 v84, vcc, 0x19c000, v84
	s_nop 1
	v_addc_co_u32_e32 v85, vcc, 0, v85, vcc
	global_load_dword v68, v[84:85], off offset:1408 nt
.LBB0_276:
	s_or_b64 exec, exec, s[10:11]
	v_mov_b32_e32 v83, 0
	v_mov_b32_e32 v84, 0
	s_and_saveexec_b64 s[10:11], s[4:5]
	s_cbranch_execz .LBB0_278
	v_lshl_add_u64 v[84:85], v[38:39], 0, v[4:5]
	v_add_co_u32_e32 v84, vcc, 0x1aa000, v84
	s_nop 1
	v_addc_co_u32_e32 v85, vcc, 0, v85, vcc
	global_load_dword v84, v[84:85], off offset:2304 nt
.LBB0_278:
	s_or_b64 exec, exec, s[10:11]
	s_and_saveexec_b64 s[10:11], s[4:5]
	s_cbranch_execz .LBB0_280
	v_lshl_add_u64 v[38:39], v[38:39], 0, v[4:5]
	v_add_co_u32_e32 v38, vcc, 0x1b8000, v38
	s_nop 1
	v_addc_co_u32_e32 v39, vcc, 0, v39, vcc
	global_load_dword v83, v[38:39], off offset:3200 nt

; #define LAS __attribute__((address_space(3)))
; template <bool F8 = false, class Map>
; __device__ __forceinline__ void transpose_item(const float* __restrict__ W, int Nsrc, int K, void* WTv, const float* kscale, float mul, LAS float* scr, int kb, int nb, int lane, const Map map) {
;     const int k0 = 64 * kb, j0 = 32 * nb, sc = map(j0 + (lane & 31)), kh = lane >> 5;
;     float v[32];
; #pragma unroll
;     for (int i = 0; i < 32; ++i) v[i] = sc >= 0 ? W[(size_t)(k0 + 2 * i + kh) * Nsrc + sc] : 0.f;
.LBB0_282:
	s_andn2_b64 vcc, exec, s[4:5]
	s_cbranch_vccnz .LBB0_284
	s_lshr_b32 s0, s58, 8
	s_and_b32 s0, s0, 0xf0
	s_and_b32 s4, s58, 15
	s_or_b32 s4, s0, s4
	s_lshl_b32 s4, s4, 5
	s_and_b32 s0, s19, 0x3fc0
	v_bitop3_b32 v4, s4, v1, v82 bitop3:0xde
	v_readlane_b32 s60, v245, 10
	v_or_b32_e32 v40, s0, v3
	v_lshlrev_b32_e32 v4, 2, v4
	v_readlane_b32 s68, v245, 18
	v_readlane_b32 s69, v245, 19
	s_lshl_b32 s0, s0, 1
	v_readlane_b32 s61, v245, 11
	v_lshl_add_u64 v[38:39], s[68:69], 0, v[4:5]
	v_lshlrev_b32_e32 v4, 14, v40
	v_lshl_add_u64 v[38:39], v[38:39], 0, v[4:5]
	v_add_co_u32_e32 v40, vcc, s22, v38
	v_readlane_b32 s62, v245, 12
	s_nop 0
	v_addc_co_u32_e32 v41, vcc, 0, v39, vcc
	v_add_co_u32_e32 v42, vcc, s23, v38
	v_readlane_b32 s63, v245, 13
	s_nop 0
	v_addc_co_u32_e32 v43, vcc, 0, v39, vcc
	v_add_co_u32_e32 v44, vcc, s24, v38
	v_readlane_b32 s64, v245, 14
	s_nop 0
	v_addc_co_u32_e32 v45, vcc, 0, v39, vcc
	v_add_co_u32_e32 v46, vcc, s25, v38
	v_readlane_b32 s65, v245, 15
	s_nop 0
	v_addc_co_u32_e32 v47, vcc, 0, v39, vcc
	v_add_co_u32_e32 v48, vcc, s26, v38
	v_readlane_b32 s66, v245, 16
	s_nop 0
	v_addc_co_u32_e32 v49, vcc, 0, v39, vcc
	v_add_co_u32_e32 v50, vcc, s27, v38
	v_readlane_b32 s67, v245, 17
	s_nop 0
	v_addc_co_u32_e32 v51, vcc, 0, v39, vcc
	v_add_co_u32_e32 v52, vcc, s28, v38
	v_readlane_b32 s70, v245, 20
	s_nop 0
	v_addc_co_u32_e32 v53, vcc, 0, v39, vcc
	global_load_dword v4, v[38:39], off nt
	global_load_dword v56, v[40:41], off nt
	global_load_dword v57, v[42:43], off nt
	global_load_dword v58, v[44:45], off nt
	global_load_dword v59, v[46:47], off nt
	global_load_dword v60, v[48:49], off nt
	global_load_dword v61, v[50:51], off nt
	global_load_dword v62, v[52:53], off nt
	v_add_co_u32_e32 v40, vcc, s29, v38
	v_readlane_b32 s71, v245, 21
	s_nop 0
	v_addc_co_u32_e32 v41, vcc, 0, v39, vcc
	v_add_co_u32_e32 v42, vcc, s33, v38
	v_readlane_b32 s72, v245, 22
	s_nop 0
	v_addc_co_u32_e32 v43, vcc, 0, v39, vcc
	v_add_co_u32_e32 v44, vcc, s34, v38
	v_readlane_b32 s73, v245, 23
	s_nop 0
	v_addc_co_u32_e32 v45, vcc, 0, v39, vcc
	v_add_co_u32_e32 v46, vcc, s36, v38
	v_readlane_b32 s74, v245, 24
	s_nop 0
	v_addc_co_u32_e32 v47, vcc, 0, v39, vcc
	v_add_co_u32_e32 v48, vcc, s38, v38
	v_readlane_b32 s75, v245, 25
	s_nop 0
	v_addc_co_u32_e32 v49, vcc, 0, v39, vcc
	v_add_co_u32_e32 v50, vcc, s39, v38
	s_nop 1
	v_addc_co_u32_e32 v51, vcc, 0, v39, vcc
	v_add_co_u32_e32 v52, vcc, s40, v38
	s_nop 1
	v_addc_co_u32_e32 v53, vcc, 0, v39, vcc
	v_add_co_u32_e32 v54, vcc, s41, v38
	s_nop 1
	v_addc_co_u32_e32 v55, vcc, 0, v39, vcc
	global_load_dword v63, v[40:41], off nt
	global_load_dword v64, v[42:43], off nt
	global_load_dword v65, v[44:45], off nt
	global_load_dword v66, v[46:47], off nt
	global_load_dword v67, v[48:49], off nt
	global_load_dword v68, v[50:51], off nt
	global_load_dword v69, v[52:53], off nt
	global_load_dword v83, v[54:55], off nt
	v_add_co_u32_e32 v40, vcc, s42, v38
	s_nop 1
	v_addc_co_u32_e32 v41, vcc, 0, v39, vcc
	v_add_co_u32_e32 v42, vcc, s43, v38
	s_nop 1
	v_addc_co_u32_e32 v43, vcc, 0, v39, vcc
	v_add_co_u32_e32 v44, vcc, s44, v38
	s_nop 1
	v_addc_co_u32_e32 v45, vcc, 0, v39, vcc
	v_add_co_u32_e32 v46, vcc, s45, v38
	s_nop 1
	v_addc_co_u32_e32 v47, vcc, 0, v39, vcc
	v_add_co_u32_e32 v48, vcc, s46, v38
	s_nop 1
	v_addc_co_u32_e32 v49, vcc, 0, v39, vcc
	v_add_co_u32_e32 v50, vcc, s47, v38
	s_nop 1
	v_addc_co_u32_e32 v51, vcc, 0, v39, vcc
	v_add_co_u32_e32 v52, vcc, s48, v38
	s_nop 1
	v_addc_co_u32_e32 v53, vcc, 0, v39, vcc
	v_add_co_u32_e32 v54, vcc, s49, v38
	s_nop 1
	v_addc_co_u32_e32 v55, vcc, 0, v39, vcc
	global_load_dword v84, v[40:41], off nt
	global_load_dword v85, v[42:43], off nt
	global_load_dword v86, v[44:45], off nt
	global_load_dword v87, v[46:47], off nt
	global_load_dword v88, v[48:49], off nt
	global_load_dword v89, v[50:51], off nt
	global_load_dword v90, v[52:53], off nt
	s_nop 0
	global_load_dword v54, v[54:55], off nt
	v_add_co_u32_e32 v40, vcc, s50, v38
	s_nop 1
	v_addc_co_u32_e32 v41, vcc, 0, v39, vcc
	v_add_co_u32_e32 v42, vcc, s51, v38
	s_nop 1
	v_addc_co_u32_e32 v43, vcc, 0, v39, vcc
	v_add_co_u32_e32 v44, vcc, s52, v38
	s_nop 1
	v_addc_co_u32_e32 v45, vcc, 0, v39, vcc
	v_add_co_u32_e32 v46, vcc, s53, v38
	s_nop 1
	v_addc_co_u32_e32 v47, vcc, 0, v39, vcc
	v_add_co_u32_e32 v48, vcc, s54, v38
	s_nop 1
	v_addc_co_u32_e32 v49, vcc, 0, v39, vcc
	v_add_co_u32_e32 v50, vcc, s55, v38
	s_nop 1
	v_addc_co_u32_e32 v51, vcc, 0, v39, vcc
	v_add_co_u32_e32 v52, vcc, s56, v38
	s_nop 1
	v_addc_co_u32_e32 v53, vcc, 0, v39, vcc
	v_add_co_u32_e32 v38, vcc, s57, v38
	s_nop 1
	v_addc_co_u32_e32 v39, vcc, 0, v39, vcc
	global_load_dword v40, v[40:41], off nt
	s_nop 0
	global_load_dword v41, v[42:43], off nt
	s_nop 0
	global_load_dword v42, v[44:45], off nt
	global_load_dword v43, v[46:47], off nt
	s_nop 0
	global_load_dword v44, v[48:49], off nt
	global_load_dword v45, v[50:51], off nt
	global_load_dword v46, v[52:53], off nt
	s_nop 0
	global_load_dword v38, v[38:39], off nt
	s_waitcnt vmcnt(30)
; #define LAS __attribute__((address_space(3)))
; __device__ __forceinline__ unsigned cvtpk(float lo, float hi) { f32x2 v = {lo, hi}; bf16x2_t b = __builtin_convertvector(v, bf16x2_t); return __builtin_bit_cast(unsigned, b); }
; __device__ __forceinline__ unsigned pack4_fp8(float a, float b, float c, float d) { unsigned w = 0u; w = (unsigned)__builtin_amdgcn_cvt_pk_fp8_f32(a, b, (int)w, false); w = (unsigned)__builtin_amdgcn_cvt_pk_fp8_f32(c, d, (int)w, true); return w; }
; template <bool F8 = false, class Map>
; __device__ __forceinline__ void transpose_item(const float* __restrict__ W, int Nsrc, int K, void* WTv, const float* kscale, float mul, LAS float* scr, int kb, int nb, int lane, const Map map) {
;     ...
; #pragma unroll
;         for (int i = 0; i < 32; ++i) v[i] *= kscale[k0 + 2 * i + kh];
;     }
; #pragma unroll
;     for (int i = 0; i < 32; ++i) scr[(2 * i + kh) * 33 + (lane & 31)] = v[i];
;     asm volatile("s_waitcnt lgkmcnt(0)" ::: "memory");
;     if constexpr (F8) {
;         unsigned char* WT = (unsigned char*)WTv; const int c = lane & 3;
; #pragma unroll
;         for (int jj = 0; jj < 2; ++jj) { const int n = (lane >> 2) + 16 * jj; const LAS float* s = scr + (16 * c) * 33 + n;
;             u32x4 o; o.x = pack4_fp8(s[0 * 33] * mul, s[1 * 33] * mul, s[2 * 33] * mul, s[3 * 33] * mul); o.y = pack4_fp8(s[4 * 33] * mul, s[5 * 33] * mul, s[6 * 33] * mul, s[7 * 33] * mul);
;             o.z = pack4_fp8(s[8 * 33] * mul, s[9 * 33] * mul, s[10 * 33] * mul, s[11 * 33] * mul); o.w = pack4_fp8(s[12 * 33] * mul, s[13 * 33] * mul, s[14 * 33] * mul, s[15 * 33] * mul);
;             *(u32x4*)(WT + (size_t)(j0 + n) * K + k0 + 16 * c) = o; }
;     } else {
;         bf16_t* WT = (bf16_t*)WTv; const int c = lane & 7;
; #pragma unroll
;         for (int jj = 0; jj < 4; ++jj) { const int n = (lane >> 3) + 8 * jj; const LAS float* s = scr + (8 * c) * 33 + n;
;             u32x4 o; o.x = cvtpk(s[0 * 33], s[1 * 33]); o.y = cvtpk(s[2 * 33], s[3 * 33]); o.z = cvtpk(s[4 * 33], s[5 * 33]); o.w = cvtpk(s[6 * 33], s[7 * 33]);
;             *(u32x4*)(WT + (size_t)(j0 + n) * K + k0 + 8 * c) = o; }
;     }
;     asm volatile("s_waitcnt lgkmcnt(0)" ::: "memory");
	ds_write2_b32 v70, v4, v56 offset1:66
	s_waitcnt vmcnt(28)
	ds_write2_b32 v70, v57, v58 offset0:132 offset1:198
	v_add_u32_e32 v4, 0x400, v70
	s_waitcnt vmcnt(26)
	ds_write2_b32 v4, v59, v60 offset0:8 offset1:74
	s_waitcnt vmcnt(24)
	ds_write2_b32 v4, v61, v62 offset0:140 offset1:206
	v_add_u32_e32 v4, 0x800, v70
	s_waitcnt vmcnt(22)
	ds_write2_b32 v4, v63, v64 offset0:16 offset1:82
	s_waitcnt vmcnt(20)
	ds_write2_b32 v4, v65, v66 offset0:148 offset1:214
	v_add_u32_e32 v4, 0xc00, v70
	s_waitcnt vmcnt(18)
	ds_write2_b32 v4, v67, v68 offset0:24 offset1:90
	s_waitcnt vmcnt(16)
	ds_write2_b32 v4, v69, v83 offset0:156 offset1:222
	v_add_u32_e32 v4, 0x1000, v70
	s_waitcnt vmcnt(14)
	ds_write2_b32 v4, v84, v85 offset0:32 offset1:98
	s_waitcnt vmcnt(12)
	ds_write2_b32 v4, v86, v87 offset0:164 offset1:230
	v_add_u32_e32 v4, 0x1400, v70
	s_waitcnt vmcnt(10)
	ds_write2_b32 v4, v88, v89 offset0:40 offset1:106
	s_waitcnt vmcnt(8)
	ds_write2_b32 v4, v90, v54 offset0:172 offset1:238
	v_add_u32_e32 v4, 0x1800, v70
	s_waitcnt vmcnt(6)
	ds_write2_b32 v4, v40, v41 offset0:48 offset1:114
	s_waitcnt vmcnt(4)
	ds_write2_b32 v4, v42, v43 offset0:180 offset1:246
	v_add_u32_e32 v4, 0x1c00, v70
	s_waitcnt vmcnt(2)
	ds_write2_b32 v4, v44, v45 offset0:56 offset1:122
	s_waitcnt vmcnt(0)
	ds_write2_b32 v4, v46, v38 offset0:188 offset1:254
	s_waitcnt lgkmcnt(0)
	ds_read2_b32 v[42:43], v72 offset0:33 offset1:41
	ds_read2_b32 v[44:45], v72 offset1:8
	ds_read2_b32 v[46:47], v72 offset0:66 offset1:74
	ds_read2_b32 v[48:49], v72 offset0:99 offset1:107
	ds_read2_b32 v[50:51], v72 offset0:132 offset1:140
	ds_read2_b32 v[52:53], v72 offset0:165 offset1:173
	ds_read2_b32 v[54:55], v72 offset0:198 offset1:206
	ds_read2_b32 v[56:57], v72 offset0:231 offset1:239
	v_bitop3_b32 v4, s4, v71, v82 bitop3:0xde
	v_lshl_add_u64 v[58:59], v[22:23], 0, s[0:1]
	v_lshlrev_b32_e32 v4, 15, v4
	s_waitcnt lgkmcnt(6)
	v_cvt_pk_bf16_f32 v38, v44, v42
	s_waitcnt lgkmcnt(4)
	v_cvt_pk_bf16_f32 v39, v46, v48
	s_waitcnt lgkmcnt(2)
	v_cvt_pk_bf16_f32 v40, v50, v52
	s_waitcnt lgkmcnt(0)
	v_cvt_pk_bf16_f32 v41, v54, v56
	v_lshl_add_u64 v[60:61], v[58:59], 0, v[4:5]
	global_store_dwordx4 v[60:61], v[38:41], off
	v_bitop3_b32 v4, s4, v73, v82 bitop3:0xde
	v_lshlrev_b32_e32 v4, 15, v4
	v_cvt_pk_bf16_f32 v38, v45, v43
	v_cvt_pk_bf16_f32 v39, v47, v49
	v_cvt_pk_bf16_f32 v40, v51, v53
	v_cvt_pk_bf16_f32 v41, v55, v57
	ds_read2_b32 v[44:45], v72 offset0:49 offset1:57
	ds_read2_b32 v[46:47], v72 offset0:16 offset1:24
	ds_read2_b32 v[48:49], v72 offset0:82 offset1:90
	ds_read2_b32 v[50:51], v72 offset0:115 offset1:123
	ds_read2_b32 v[52:53], v72 offset0:148 offset1:156
	ds_read2_b32 v[54:55], v72 offset0:181 offset1:189
	ds_read2_b32 v[56:57], v72 offset0:214 offset1:222
	ds_read2_b32 v[60:61], v72 offset0:247 offset1:255
	v_lshl_add_u64 v[42:43], v[58:59], 0, v[4:5]
	v_bitop3_b32 v4, s4, v74, v82 bitop3:0xde
	v_lshlrev_b32_e32 v4, 15, v4
	global_store_dwordx4 v[42:43], v[38:41], off
	v_lshl_add_u64 v[42:43], v[58:59], 0, v[4:5]
	v_bitop3_b32 v4, s4, v75, v82 bitop3:0xde
	s_waitcnt lgkmcnt(6)
	v_cvt_pk_bf16_f32 v38, v46, v44
	s_waitcnt lgkmcnt(4)
	v_cvt_pk_bf16_f32 v39, v48, v50
	s_waitcnt lgkmcnt(2)
	v_cvt_pk_bf16_f32 v40, v52, v54
	s_waitcnt lgkmcnt(0)
	v_cvt_pk_bf16_f32 v41, v56, v60
	v_lshlrev_b32_e32 v4, 15, v4
	global_store_dwordx4 v[42:43], v[38:41], off
	v_lshl_add_u64 v[42:43], v[58:59], 0, v[4:5]
	s_nop 0
	v_cvt_pk_bf16_f32 v38, v47, v45
	v_cvt_pk_bf16_f32 v39, v49, v51
	v_cvt_pk_bf16_f32 v40, v53, v55
	v_cvt_pk_bf16_f32 v41, v57, v61
	global_store_dwordx4 v[42:43], v[38:41], off
	s_waitcnt lgkmcnt(0)

; template <bool F8 = false, class Map>
; __device__ __forceinline__ void transpose_item(const float* __restrict__ W, int Nsrc, int K, void* WTv, const float* kscale, float mul, LAS float* scr, int kb, int nb, int lane, const Map map) {
;     const int k0 = 64 * kb, j0 = 32 * nb, sc = map(j0 + (lane & 31)), kh = lane >> 5;
;     float v[32];
; #pragma unroll
;     for (int i = 0; i < 32; ++i) v[i] = sc >= 0 ? W[(size_t)(k0 + 2 * i + kh) * Nsrc + sc] : 0.f;
.LBB0_318:
	v_ashrrev_i32_e32 v39, 31, v38
	v_lshlrev_b64 v[44:45], 16, v[38:39]
	v_lshl_add_u64 v[44:45], v[40:41], 0, v[44:45]
	global_load_dword v4, v[44:45], off nt
	v_cndmask_b32_e64 v39, 0, 1, s[12:13]
	v_cmp_ne_u32_e64 s[4:5], 1, v39
	s_andn2_b64 vcc, exec, s[12:13]
	s_cbranch_vccnz .LBB0_288
.LBB0_319:
	v_or_b32_e32 v42, 2, v38
	v_ashrrev_i32_e32 v43, 31, v42
	v_lshlrev_b64 v[42:43], 16, v[42:43]
	v_lshl_add_u64 v[42:43], v[40:41], 0, v[42:43]
	global_load_dword v42, v[42:43], off nt
	v_mov_b32_e32 v39, 0
	s_and_b64 vcc, exec, s[4:5]
	v_mov_b32_e32 v43, 0
	s_cbranch_vccnz .LBB0_289
.LBB0_320:
	v_or_b32_e32 v44, 4, v38
	v_ashrrev_i32_e32 v45, 31, v44
	v_lshlrev_b64 v[44:45], 16, v[44:45]
	v_lshl_add_u64 v[44:45], v[40:41], 0, v[44:45]
	global_load_dword v43, v[44:45], off nt
	s_and_b64 vcc, exec, s[4:5]
	s_cbranch_vccnz .LBB0_290
.LBB0_321:
	v_or_b32_e32 v44, 6, v38
	v_ashrrev_i32_e32 v45, 31, v44
	v_lshlrev_b64 v[44:45], 16, v[44:45]
	v_lshl_add_u64 v[44:45], v[40:41], 0, v[44:45]
	global_load_dword v39, v[44:45], off nt
	v_mov_b32_e32 v44, 0
	s_and_b64 vcc, exec, s[4:5]
	v_mov_b32_e32 v45, 0
	s_cbranch_vccnz .LBB0_291
.LBB0_322:
	v_or_b32_e32 v46, 8, v38
	v_ashrrev_i32_e32 v47, 31, v46
	v_lshlrev_b64 v[46:47], 16, v[46:47]
	v_lshl_add_u64 v[46:47], v[40:41], 0, v[46:47]
	global_load_dword v45, v[46:47], off nt
	s_and_b64 vcc, exec, s[4:5]
	s_cbranch_vccnz .LBB0_292
.LBB0_323:
	v_or_b32_e32 v46, 10, v38
	v_ashrrev_i32_e32 v47, 31, v46
	v_lshlrev_b64 v[46:47], 16, v[46:47]
	v_lshl_add_u64 v[46:47], v[40:41], 0, v[46:47]
	global_load_dword v44, v[46:47], off nt
	v_mov_b32_e32 v46, 0
	s_and_b64 vcc, exec, s[4:5]
	v_mov_b32_e32 v47, 0
	s_cbranch_vccnz .LBB0_293
.LBB0_324:
	v_or_b32_e32 v48, 12, v38
	v_ashrrev_i32_e32 v49, 31, v48
	v_lshlrev_b64 v[48:49], 16, v[48:49]
	v_lshl_add_u64 v[48:49], v[40:41], 0, v[48:49]
	global_load_dword v47, v[48:49], off nt
	s_and_b64 vcc, exec, s[4:5]
	s_cbranch_vccnz .LBB0_294
.LBB0_325:
	v_or_b32_e32 v48, 14, v38
	v_ashrrev_i32_e32 v49, 31, v48
	v_lshlrev_b64 v[48:49], 16, v[48:49]
	v_lshl_add_u64 v[48:49], v[40:41], 0, v[48:49]
	global_load_dword v46, v[48:49], off nt
	v_mov_b32_e32 v48, 0
	s_and_b64 vcc, exec, s[4:5]
	v_mov_b32_e32 v49, 0
	s_cbranch_vccnz .LBB0_295
.LBB0_326:
	v_or_b32_e32 v50, 16, v38
	v_ashrrev_i32_e32 v51, 31, v50
	v_lshlrev_b64 v[50:51], 16, v[50:51]
	v_lshl_add_u64 v[50:51], v[40:41], 0, v[50:51]
	global_load_dword v49, v[50:51], off nt
	s_and_b64 vcc, exec, s[4:5]
	s_cbranch_vccnz .LBB0_296
.LBB0_327:
	v_or_b32_e32 v50, 18, v38
	v_ashrrev_i32_e32 v51, 31, v50
	v_lshlrev_b64 v[50:51], 16, v[50:51]
	v_lshl_add_u64 v[50:51], v[40:41], 0, v[50:51]
	global_load_dword v48, v[50:51], off nt
	v_mov_b32_e32 v50, 0
	s_and_b64 vcc, exec, s[4:5]
	v_mov_b32_e32 v51, 0
	s_cbranch_vccnz .LBB0_297
.LBB0_328:
	v_or_b32_e32 v52, 20, v38
	v_ashrrev_i32_e32 v53, 31, v52
	v_lshlrev_b64 v[52:53], 16, v[52:53]
	v_lshl_add_u64 v[52:53], v[40:41], 0, v[52:53]
	global_load_dword v51, v[52:53], off nt
	s_and_b64 vcc, exec, s[4:5]
	s_cbranch_vccnz .LBB0_298
.LBB0_329:
	v_or_b32_e32 v52, 22, v38
	v_ashrrev_i32_e32 v53, 31, v52
	v_lshlrev_b64 v[52:53], 16, v[52:53]
	v_lshl_add_u64 v[52:53], v[40:41], 0, v[52:53]
	global_load_dword v50, v[52:53], off nt
	v_mov_b32_e32 v52, 0
	s_and_b64 vcc, exec, s[4:5]
	v_mov_b32_e32 v53, 0
	s_cbranch_vccnz .LBB0_299
.LBB0_330:
	v_or_b32_e32 v54, 24, v38
	v_ashrrev_i32_e32 v55, 31, v54
	v_lshlrev_b64 v[54:55], 16, v[54:55]
	v_lshl_add_u64 v[54:55], v[40:41], 0, v[54:55]
	global_load_dword v53, v[54:55], off nt
	s_and_b64 vcc, exec, s[4:5]
	s_cbranch_vccnz .LBB0_300
.LBB0_331:
	v_or_b32_e32 v54, 26, v38
	v_ashrrev_i32_e32 v55, 31, v54
	v_lshlrev_b64 v[54:55], 16, v[54:55]
	v_lshl_add_u64 v[54:55], v[40:41], 0, v[54:55]
	global_load_dword v52, v[54:55], off nt
	v_mov_b32_e32 v54, 0
	s_and_b64 vcc, exec, s[4:5]
	v_mov_b32_e32 v55, 0
	s_cbranch_vccnz .LBB0_301
.LBB0_332:
	v_or_b32_e32 v56, 28, v38
	v_ashrrev_i32_e32 v57, 31, v56
	v_lshlrev_b64 v[56:57], 16, v[56:57]
	v_lshl_add_u64 v[56:57], v[40:41], 0, v[56:57]
	global_load_dword v55, v[56:57], off nt
	s_and_b64 vcc, exec, s[4:5]
	s_cbranch_vccnz .LBB0_302
.LBB0_333:
	v_or_b32_e32 v56, 30, v38
	v_ashrrev_i32_e32 v57, 31, v56
	v_lshlrev_b64 v[56:57], 16, v[56:57]
	v_lshl_add_u64 v[56:57], v[40:41], 0, v[56:57]
	global_load_dword v54, v[56:57], off nt
	v_mov_b32_e32 v56, 0
	s_and_b64 vcc, exec, s[4:5]
	v_mov_b32_e32 v57, 0
	s_cbranch_vccnz .LBB0_303
; template <bool F8 = false, class Map>
; __device__ __forceinline__ void transpose_item(const float* __restrict__ W, int Nsrc, int K, void* WTv, const float* kscale, float mul, LAS float* scr, int kb, int nb, int lane, const Map map) {
;     const int k0 = 64 * kb, j0 = 32 * nb, sc = map(j0 + (lane & 31)), kh = lane >> 5;
;     float v[32];
; #pragma unroll
;     for (int i = 0; i < 32; ++i) v[i] = sc >= 0 ? W[(size_t)(k0 + 2 * i + kh) * Nsrc + sc] : 0.f;
.LBB0_334:
	v_or_b32_e32 v58, 32, v38
	v_ashrrev_i32_e32 v59, 31, v58
	v_lshlrev_b64 v[58:59], 16, v[58:59]
	v_lshl_add_u64 v[58:59], v[40:41], 0, v[58:59]
	global_load_dword v57, v[58:59], off nt
	s_and_b64 vcc, exec, s[4:5]
	s_cbranch_vccnz .LBB0_304
.LBB0_335:
	v_or_b32_e32 v58, 34, v38
	v_ashrrev_i32_e32 v59, 31, v58
	v_lshlrev_b64 v[58:59], 16, v[58:59]
	v_lshl_add_u64 v[58:59], v[40:41], 0, v[58:59]
	global_load_dword v56, v[58:59], off nt
	v_mov_b32_e32 v58, 0
	s_and_b64 vcc, exec, s[4:5]
	v_mov_b32_e32 v59, 0
	s_cbranch_vccnz .LBB0_305
.LBB0_336:
	v_or_b32_e32 v60, 36, v38
	v_ashrrev_i32_e32 v61, 31, v60
	v_lshlrev_b64 v[60:61], 16, v[60:61]
	v_lshl_add_u64 v[60:61], v[40:41], 0, v[60:61]
	global_load_dword v59, v[60:61], off nt
	s_and_b64 vcc, exec, s[4:5]
	s_cbranch_vccnz .LBB0_306
.LBB0_337:
	v_or_b32_e32 v60, 38, v38
	v_ashrrev_i32_e32 v61, 31, v60
	v_lshlrev_b64 v[60:61], 16, v[60:61]
	v_lshl_add_u64 v[60:61], v[40:41], 0, v[60:61]
	global_load_dword v58, v[60:61], off nt
	v_mov_b32_e32 v60, 0
	s_and_b64 vcc, exec, s[4:5]
	v_mov_b32_e32 v61, 0
	s_cbranch_vccnz .LBB0_307
.LBB0_338:
	v_or_b32_e32 v62, 40, v38
	v_ashrrev_i32_e32 v63, 31, v62
	v_lshlrev_b64 v[62:63], 16, v[62:63]
	v_lshl_add_u64 v[62:63], v[40:41], 0, v[62:63]
	global_load_dword v61, v[62:63], off nt
	s_and_b64 vcc, exec, s[4:5]
	s_cbranch_vccnz .LBB0_308
.LBB0_339:
	v_or_b32_e32 v62, 42, v38
	v_ashrrev_i32_e32 v63, 31, v62
	v_lshlrev_b64 v[62:63], 16, v[62:63]
	v_lshl_add_u64 v[62:63], v[40:41], 0, v[62:63]
	global_load_dword v60, v[62:63], off nt
	v_mov_b32_e32 v62, 0
	s_and_b64 vcc, exec, s[4:5]
	v_mov_b32_e32 v63, 0
	s_cbranch_vccnz .LBB0_309
.LBB0_340:
	v_or_b32_e32 v64, 44, v38
	v_ashrrev_i32_e32 v65, 31, v64
	v_lshlrev_b64 v[64:65], 16, v[64:65]
	v_lshl_add_u64 v[64:65], v[40:41], 0, v[64:65]
	global_load_dword v63, v[64:65], off nt
	s_and_b64 vcc, exec, s[4:5]
	s_cbranch_vccnz .LBB0_310
.LBB0_341:
	v_or_b32_e32 v64, 46, v38
	v_ashrrev_i32_e32 v65, 31, v64
	v_lshlrev_b64 v[64:65], 16, v[64:65]
	v_lshl_add_u64 v[64:65], v[40:41], 0, v[64:65]
	global_load_dword v62, v[64:65], off nt
	v_mov_b32_e32 v64, 0
	s_and_b64 vcc, exec, s[4:5]
	v_mov_b32_e32 v65, 0
	s_cbranch_vccnz .LBB0_311
.LBB0_342:
	v_or_b32_e32 v66, 48, v38
	v_ashrrev_i32_e32 v67, 31, v66
	v_lshlrev_b64 v[66:67], 16, v[66:67]
	v_lshl_add_u64 v[66:67], v[40:41], 0, v[66:67]
	global_load_dword v65, v[66:67], off nt
	s_and_b64 vcc, exec, s[4:5]
	s_cbranch_vccnz .LBB0_312
.LBB0_343:
	v_or_b32_e32 v66, 50, v38
	v_ashrrev_i32_e32 v67, 31, v66
	v_lshlrev_b64 v[66:67], 16, v[66:67]
	v_lshl_add_u64 v[66:67], v[40:41], 0, v[66:67]
	global_load_dword v64, v[66:67], off nt
	v_mov_b32_e32 v66, 0
	s_and_b64 vcc, exec, s[4:5]
	v_mov_b32_e32 v67, 0
	s_cbranch_vccnz .LBB0_313
.LBB0_344:
	v_or_b32_e32 v68, 52, v38
	v_ashrrev_i32_e32 v69, 31, v68
	v_lshlrev_b64 v[68:69], 16, v[68:69]
	v_lshl_add_u64 v[68:69], v[40:41], 0, v[68:69]
	global_load_dword v67, v[68:69], off nt
	s_and_b64 vcc, exec, s[4:5]
	s_cbranch_vccnz .LBB0_314
.LBB0_345:
	v_or_b32_e32 v68, 54, v38
	v_ashrrev_i32_e32 v69, 31, v68
	v_lshlrev_b64 v[68:69], 16, v[68:69]
	v_lshl_add_u64 v[68:69], v[40:41], 0, v[68:69]
	global_load_dword v66, v[68:69], off nt
	v_mov_b32_e32 v68, 0
	s_and_b64 vcc, exec, s[4:5]
	v_mov_b32_e32 v69, 0
	s_cbranch_vccnz .LBB0_315
.LBB0_346:
	v_or_b32_e32 v84, 56, v38
	v_ashrrev_i32_e32 v85, 31, v84
	v_lshlrev_b64 v[84:85], 16, v[84:85]
	v_lshl_add_u64 v[84:85], v[40:41], 0, v[84:85]
	global_load_dword v69, v[84:85], off nt
	s_and_b64 vcc, exec, s[4:5]
	s_cbranch_vccnz .LBB0_316
.LBB0_347:
	v_or_b32_e32 v84, 58, v38
	v_ashrrev_i32_e32 v85, 31, v84
	v_lshlrev_b64 v[84:85], 16, v[84:85]
	v_lshl_add_u64 v[84:85], v[40:41], 0, v[84:85]
	global_load_dword v68, v[84:85], off nt
	v_mov_b32_e32 v83, 0
	s_and_b64 vcc, exec, s[4:5]
	v_mov_b32_e32 v84, 0
	s_cbranch_vccnz .LBB0_317
.LBB0_348:
	v_or_b32_e32 v84, 60, v38
	v_ashrrev_i32_e32 v85, 31, v84
	v_lshlrev_b64 v[84:85], 16, v[84:85]
	v_lshl_add_u64 v[84:85], v[40:41], 0, v[84:85]
	global_load_dword v84, v[84:85], off nt
	s_and_b64 vcc, exec, s[4:5]
	s_cbranch_vccnz .LBB0_27
.LBB0_349:
	v_or_b32_e32 v86, 62, v38
	v_ashrrev_i32_e32 v87, 31, v86
	v_lshlrev_b64 v[86:87], 16, v[86:87]
	v_lshl_add_u64 v[40:41], v[40:41], 0, v[86:87]
	global_load_dword v83, v[40:41], off nt
	s_branch .LBB0_27

; __device__ __forceinline__ void sincos_d(double a, float& s, float& c) {
;     const double k = __builtin_rint(a * 0.63661977236758134308);
;     double r = __builtin_fma(-k, 1.57079632679489655800e+00, a); r = __builtin_fma(-k, 6.12323399573676603587e-17, r);
;     const double r2 = r * r;
;     double sp = -7.6471637318198164759e-13; sp = sp * r2 + 1.6059043836821614599e-10; sp = sp * r2 - 2.5052108385441718775e-08; sp = sp * r2 + 2.7557319223985890653e-06;
;     sp = sp * r2 - 1.9841269841269841270e-04; sp = sp * r2 + 8.3333333333333333333e-03; sp = sp * r2 - 1.6666666666666666667e-01; const double sr = r + r * r2 * sp;
;     double cp = 4.7794773323873852974e-14; cp = cp * r2 - 1.1470745597729724714e-11; cp = cp * r2 + 2.0876756987868098979e-09; cp = cp * r2 - 2.7557319223985890653e-07;
;     cp = cp * r2 + 2.4801587301587301587e-05; cp = cp * r2 - 1.3888888888888888889e-03; cp = cp * r2 + 4.1666666666666666667e-02; cp = cp * r2 - 0.5; const double cr = 1.0 + r2 * cp;
;     const int q = (int)k & 3;
;     const double ss = (q == 0) ? sr : (q == 1) ? cr : (q == 2) ? -sr : -cr;
;     const double cc = (q == 0) ? cr : (q == 1) ? -sr : (q == 2) ? -cr : sr;
;     s = (float)ss; c = (float)cc;
; }
; __device__ __forceinline__ void p0_prologue(Frame& F) {
;     ...
;         for (int e = gt; e < T * 32; e += NT) {
;             const int t = e >> 5, i = e & 31;
;             const double inv = INVM[i];
;             float s, c; sincos_d((double)F.positions[t] * inv, s, c);
;             rm[(size_t)t * 64 + i] = c; rm[(size_t)t * 64 + 32 + i] = s;
;             if ((i & 1) == 0) { rp[(size_t)t * 32 + (i >> 1)] = c; rp[(size_t)t * 32 + 16 + (i >> 1)] = s; }
;         }
.LBB0_353:
	v_ashrrev_i32_e32 v32, 5, v40
	v_ashrrev_i32_e32 v33, 31, v32
	v_lshl_add_u64 v[34:35], v[32:33], 2, s[56:57]
	global_load_dword v1, v[34:35], off nt
	s_waitcnt vmcnt(0)
	v_cvt_f64_i32_e32 v[34:35], v1
	v_mul_f64 v[34:35], v[4:5], v[34:35]
	v_mul_f64 v[36:37], v[34:35], s[10:11]
	v_rndne_f64_e32 v[36:37], v[36:37]
	v_fmac_f64_e32 v[34:35], s[12:13], v[36:37]
	v_fmac_f64_e32 v[34:35], s[14:15], v[36:37]
	v_cvt_i32_f64_e32 v1, v[36:37]
	v_mul_f64 v[36:37], v[34:35], v[34:35]
	v_fma_f64 v[38:39], s[16:17], v[36:37], v[8:9]
	v_fma_f64 v[44:45], s[18:19], v[36:37], v[20:21]
	v_fma_f64 v[38:39], v[36:37], v[38:39], v[10:11]
	v_fma_f64 v[44:45], v[36:37], v[44:45], v[22:23]
	v_fma_f64 v[38:39], v[36:37], v[38:39], v[12:13]
	v_fma_f64 v[44:45], v[36:37], v[44:45], v[24:25]
	v_fma_f64 v[38:39], v[36:37], v[38:39], v[14:15]
	v_fma_f64 v[44:45], v[36:37], v[44:45], v[26:27]
	v_fma_f64 v[38:39], v[36:37], v[38:39], v[16:17]
	v_fma_f64 v[44:45], v[36:37], v[44:45], v[28:29]
	v_mul_f64 v[42:43], v[34:35], v[36:37]
	v_fma_f64 v[38:39], v[36:37], v[38:39], v[18:19]
	v_fma_f64 v[44:45], v[36:37], v[44:45], v[30:31]
	v_and_b32_e32 v1, 3, v1
	v_fmac_f64_e32 v[34:35], v[42:43], v[38:39]
	v_fma_f64 v[38:39], v[36:37], v[44:45], -0.5
	v_fma_f64 v[36:37], v[36:37], v[38:39], 1.0
	v_cmp_lt_i32_e64 s[0:1], 0, v1
	s_and_saveexec_b64 s[20:21], s[0:1]
	s_cbranch_execz .LBB0_357
	v_cmp_eq_u32_e64 s[0:1], 1, v1
	v_cmp_eq_u32_e64 s[2:3], 2, v1
	v_cmp_ne_u32_e64 s[4:5], 1, v1
	v_xor_b32_e32 v39, 0x80000000, v35
	v_mov_b32_e32 v38, v34
	s_and_saveexec_b64 s[24:25], s[4:5]
	s_xor_b64 s[4:5], exec, s[24:25]
	v_xor_b32_e32 v1, 0x80000000, v37
	v_cndmask_b32_e64 v39, v35, v1, s[2:3]
	v_cndmask_b32_e64 v38, v34, v36, s[2:3]
	s_andn2_saveexec_b64 s[4:5], s[4:5]
	s_or_b64 exec, exec, s[4:5]
	v_cndmask_b32_e64 v1, v36, v34, s[2:3]
	v_cndmask_b32_e64 v34, -v37, -v35, s[2:3]
	v_cndmask_b32_e64 v35, v34, v37, s[0:1]
	v_cndmask_b32_e64 v34, v1, v36, s[0:1]
	v_mov_b64_e32 v[36:37], v[38:39]

; __device__ __forceinline__ void p0_prologue(Frame& F) {
;     ...
;         for (int it = gw; it < 128; it += NGW) {
;             const int which = it >> 6, cg = it & 63; const float* pos = which ? F.pos_v : F.pos_k; const float* w1 = which ? F.v1 : F.k1;
;             f32x4 a = {0.f, 0.f, 0.f, 0.f};
;             for (int k = lane; k < 4096; k += 64) a += *(const f32x4*)(w1 + (size_t)k * 256 + 4 * cg) * pos[k];
; #pragma unroll
;             for (int e = 0; e < 4; ++e) a[e] = wave_sum(a[e]);
;             if (lane == 0) *(f32x4*)(bias + which * 256 + 4 * cg) = a;
;         }
.LBB0_363:
	global_load_dwordx4 v[22:25], v[12:13], off nt
	global_load_dword v26, v[10:11], off nt
	v_add_u32_e32 v20, 64, v20
	v_cmp_lt_u32_e64 s[0:1], s14, v20
	v_lshl_add_u64 v[10:11], v[10:11], 0, s[4:5]
	v_lshl_add_u64 v[12:13], v[12:13], 0, s[6:7]
	s_or_b64 s[8:9], s[0:1], s[8:9]
	s_waitcnt vmcnt(0)
	v_pk_fma_f32 v[6:7], v[24:25], v[26:27], v[6:7] op_sel_hi:[1,0,1]
	v_pk_fma_f32 v[8:9], v[22:23], v[26:27], v[8:9] op_sel_hi:[1,0,1]
	s_andn2_b64 exec, exec, s[8:9]
	s_cbranch_execnz .LBB0_363
	s_or_b64 exec, exec, s[8:9]
	ds_bpermute_b32 v10, v1, v8
	ds_bpermute_b32 v11, v1, v9
	ds_bpermute_b32 v12, v1, v6
	ds_bpermute_b32 v13, v1, v7
	s_waitcnt lgkmcnt(2)
	v_pk_add_f32 v[8:9], v[8:9], v[10:11]
	ds_bpermute_b32 v10, v14, v8
	s_waitcnt lgkmcnt(1)
	v_pk_add_f32 v[6:7], v[6:7], v[12:13]
	ds_bpermute_b32 v11, v14, v9
	ds_bpermute_b32 v12, v14, v6
	ds_bpermute_b32 v13, v14, v7
	s_waitcnt lgkmcnt(2)
	v_pk_add_f32 v[8:9], v[8:9], v[10:11]
	ds_bpermute_b32 v10, v15, v8
	s_waitcnt lgkmcnt(1)
	v_pk_add_f32 v[6:7], v[6:7], v[12:13]
	ds_bpermute_b32 v11, v15, v9
	ds_bpermute_b32 v12, v15, v6
	ds_bpermute_b32 v13, v15, v7
	s_waitcnt lgkmcnt(2)
	v_pk_add_f32 v[8:9], v[8:9], v[10:11]
	ds_bpermute_b32 v10, v16, v8
	s_waitcnt lgkmcnt(1)
	v_pk_add_f32 v[6:7], v[6:7], v[12:13]
	ds_bpermute_b32 v11, v16, v9
	ds_bpermute_b32 v12, v16, v6
	ds_bpermute_b32 v13, v16, v7
	s_waitcnt lgkmcnt(2)
	v_pk_add_f32 v[8:9], v[8:9], v[10:11]
	ds_bpermute_b32 v10, v17, v8
	s_waitcnt lgkmcnt(1)
	v_pk_add_f32 v[12:13], v[6:7], v[12:13]
	ds_bpermute_b32 v11, v17, v9
	ds_bpermute_b32 v20, v17, v12
	ds_bpermute_b32 v21, v17, v13
	s_waitcnt lgkmcnt(2)
	v_pk_add_f32 v[6:7], v[8:9], v[10:11]
	ds_bpermute_b32 v8, v18, v6
	s_waitcnt lgkmcnt(1)
	v_pk_add_f32 v[10:11], v[12:13], v[20:21]
	ds_bpermute_b32 v9, v18, v7
	ds_bpermute_b32 v12, v18, v10
	ds_bpermute_b32 v13, v18, v11
	s_and_saveexec_b64 s[0:1], vcc
	s_cbranch_execz .LBB0_361
	s_lshl_b32 s2, s35, 2
	s_and_b32 s8, s2, 0xffffff00
	s_ashr_i32 s9, s8, 31
	s_lshl_b64 s[8:9], s[8:9], 2
	s_add_u32 s8, s10, s8
	s_addc_u32 s9, s11, s9
	s_lshl_b32 s2, s35, 4
	s_and_b32 s2, s2, 0x3f0
	s_waitcnt lgkmcnt(0)
	v_pk_add_f32 v[10:11], v[10:11], v[12:13]
	v_pk_add_f32 v[8:9], v[6:7], v[8:9]
	v_mov_b32_e32 v6, s2
	global_store_dwordx4 v6, v[8:11], s[8:9]
	s_branch .LBB0_361
